# t2 + mid-MFMA-block s_setprio 0/1 flip pairs deleted in all GEMM K-loops (block-level flips kept)
# baseline (speedup 1.0000x reference)
; #define PG8_STAGE(bufoff, gbase, voff) do { _Pragma("unroll") for (int _i = 0; _i < 2; ++_i) \
;         __builtin_amdgcn_global_load_lds((const unsigned*)((const char*)(gbase) + (voff)[_i]), (LAS unsigned*)(lds + (bufoff) + ldsw + _i * 8192), 16, 0, 0); } while (0)
; #define PG8_LDA(dst, b, h) do { _Pragma("unroll") for (int m = 0; m < 4; ++m) _Pragma("unroll") for (int k = 0; k < 2; ++k) dst[m][k] = *(const LAS bf16x8*)(lds + PG8_SA(b, h) + aoff + m * 2048 + k * 1024); } while (0)
; #define PG8_LDB(dst, b, h) do { _Pragma("unroll") for (int n = 0; n < 2; ++n) _Pragma("unroll") for (int k = 0; k < 2; ++k) dst[n][k] = *(const LAS bf16x8*)(lds + PG8_SB(b, h) + boff + n * 2048 + k * 1024); } while (0)
; #define PG8_MMA(ai, bj, At, Bt) do { __builtin_amdgcn_s_setprio(1); _Pragma("unroll") for (int m = 0; m < 4; ++m) _Pragma("unroll") for (int n = 0; n < 2; ++n) _Pragma("unroll") for (int k = 0; k < 2; ++k) \
;         acc[ai][bj][m][n] = __builtin_amdgcn_mfma_f32_16x16x32_bf16(Bt[n][k], At[m][k], acc[ai][bj][m][n], 0, 0, 0); __builtin_amdgcn_s_setprio(0); } while (0)
; #define PG8_WAIT_V(n) asm volatile("s_waitcnt vmcnt(" #n ")" ::: "memory")
; #define PG8_WAIT_L(n) asm volatile("s_waitcnt lgkmcnt(" #n ")" ::: "memory")
; #define PG8_BAR __builtin_amdgcn_s_barrier()
; #define PG8_SCHED __builtin_amdgcn_sched_barrier(0)
; template <class Epi, class Sched, bool ALIGN_EPI, class Hook = NoHook>
; __device__ __forceinline__ void gemm_phase(LAS unsigned char* lds, const Gemm g, const Sched& S, const Epi& E, const Hook& H = Hook()) {
;     ...
;             const char* a1 = cA + (size_t)(t + 1) * kstep;
;             const char* a2 = last ? nA : cA + (size_t)(t + 2) * kstep; const char* b2 = last ? nB : cB + (size_t)(t + 2) * kstep;
;             const char* a3 = a2 + kstep; const char* b3 = b2 + kstep;
;             if (last && has_next) S.a_ready(nxt);
;             PG8_LDB(B0, 0, 0); PG8_LDB(B1, 0, 1); PG8_SCHED; PG8_LDA(At, 0, 0); PG8_STAGE(PG8_SA(1, 1), a1 + hA, voffA);
;             PG8_WAIT_V(8); PG8_WAIT_L(0); PG8_BAR; PG8_MMA(0, 0, At, B0); PG8_MMA(0, 1, At, B1); PG8_BAR; PG8_SCHED;
;             PG8_LDA(At, 0, 1); PG8_STAGE(PG8_SB(0, 0), b2, voffB); PG8_STAGE(PG8_SB(0, 1), b2 + hB, voffB); PG8_STAGE(PG8_SA(0, 0), a2, voffA);
;             PG8_WAIT_V(8); PG8_WAIT_L(0); PG8_BAR; PG8_MMA(1, 0, At, B0); PG8_MMA(1, 1, At, B1); PG8_BAR; PG8_SCHED;
.LBB0_199:
	ds_read_b128 v[130:133], v217
	ds_read_b128 v[134:137], v217 offset:1024
	s_add_i32 m0, s40, 0xc000
	s_nop 0
	global_load_lds_dwordx4 v172, s[4:5]
	ds_read_b128 v[138:141], v217 offset:2048
	ds_read_b128 v[142:145], v217 offset:3072
	ds_read_b128 v[146:149], v218
	ds_read_b128 v[150:153], v218 offset:1024
	ds_read_b128 v[154:157], v218 offset:2048
	ds_read_b128 v[158:161], v218 offset:3072
	ds_read_b128 v[180:183], v219
	s_add_i32 m0, s40, 0xe000
	s_nop 0
	global_load_lds_dwordx4 v174, s[4:5]
	s_add_u32 s34, s4, 0x100
	s_addc_u32 s35, s5, 0
	s_cmp_eq_u32 s64, 60
	s_cselect_b32 s39, s7, s35
	s_cselect_b32 s38, s8, s34
	s_cselect_b32 s37, s23, s63
	s_cselect_b32 s36, s25, s31
	ds_read_b128 v[184:187], v219 offset:1024
	ds_read_b128 v[188:191], v219 offset:2048
	ds_read_b128 v[192:195], v219 offset:3072
	ds_read_b128 v[196:199], v219 offset:4096
	ds_read_b128 v[200:203], v219 offset:5120
	ds_read_b128 v[204:207], v219 offset:6144
	ds_read_b128 v[208:211], v219 offset:7168
	s_barrier
	s_setprio 1
	s_waitcnt lgkmcnt(0)
	v_mfma_f32_16x16x32_bf16 v[126:129], v[130:133], v[180:183], v[126:129]
	v_mfma_f32_16x16x32_bf16 v[94:97], v[138:141], v[180:183], v[94:97]
	v_mfma_f32_16x16x32_bf16 v[122:125], v[130:133], v[188:191], v[122:125]
	v_mfma_f32_16x16x32_bf16 v[90:93], v[138:141], v[188:191], v[90:93]
	v_mfma_f32_16x16x32_bf16 v[118:121], v[130:133], v[196:199], v[118:121]
	v_mfma_f32_16x16x32_bf16 v[86:89], v[138:141], v[196:199], v[86:89]
	v_mfma_f32_16x16x32_bf16 v[114:117], v[130:133], v[204:207], v[114:117]
	v_mfma_f32_16x16x32_bf16 v[82:85], v[138:141], v[204:207], v[82:85]
	v_mfma_f32_16x16x32_bf16 v[126:129], v[134:137], v[184:187], v[126:129]
	v_mfma_f32_16x16x32_bf16 v[94:97], v[142:145], v[184:187], v[94:97]
	v_mfma_f32_16x16x32_bf16 v[122:125], v[134:137], v[192:195], v[122:125]
	v_mfma_f32_16x16x32_bf16 v[90:93], v[142:145], v[192:195], v[90:93]
	v_mfma_f32_16x16x32_bf16 v[118:121], v[134:137], v[200:203], v[118:121]
	v_mfma_f32_16x16x32_bf16 v[86:89], v[142:145], v[200:203], v[86:89]
	v_mfma_f32_16x16x32_bf16 v[114:117], v[134:137], v[208:211], v[114:117]
	v_mfma_f32_16x16x32_bf16 v[82:85], v[142:145], v[208:211], v[82:85]
	v_mfma_f32_16x16x32_bf16 v[62:65], v[146:149], v[180:183], v[62:65]
	v_mfma_f32_16x16x32_bf16 v[30:33], v[154:157], v[180:183], v[30:33]
	v_mfma_f32_16x16x32_bf16 v[58:61], v[146:149], v[188:191], v[58:61]
	v_mfma_f32_16x16x32_bf16 v[26:29], v[154:157], v[188:191], v[26:29]
	v_mfma_f32_16x16x32_bf16 v[54:57], v[146:149], v[196:199], v[54:57]
	v_mfma_f32_16x16x32_bf16 v[22:25], v[154:157], v[196:199], v[22:25]
	v_mfma_f32_16x16x32_bf16 v[50:53], v[146:149], v[204:207], v[50:53]
	v_mfma_f32_16x16x32_bf16 v[18:21], v[154:157], v[204:207], v[18:21]
	v_mfma_f32_16x16x32_bf16 v[62:65], v[150:153], v[184:187], v[62:65]
	v_mfma_f32_16x16x32_bf16 v[30:33], v[158:161], v[184:187], v[30:33]
	v_mfma_f32_16x16x32_bf16 v[58:61], v[150:153], v[192:195], v[58:61]
	v_mfma_f32_16x16x32_bf16 v[26:29], v[158:161], v[192:195], v[26:29]
	v_mfma_f32_16x16x32_bf16 v[54:57], v[150:153], v[200:203], v[54:57]
	v_mfma_f32_16x16x32_bf16 v[22:25], v[158:161], v[200:203], v[22:25]
	v_mfma_f32_16x16x32_bf16 v[50:53], v[150:153], v[208:211], v[50:53]
	v_mfma_f32_16x16x32_bf16 v[18:21], v[158:161], v[208:211], v[18:21]
	s_waitcnt vmcnt(8)
	s_barrier
	s_setprio 0
	s_add_i32 s4, s59, s21
	s_mov_b32 m0, s4
	ds_read_b128 v[180:183], v219 offset:16384
	ds_read_b128 v[184:187], v219 offset:17408
	global_load_lds_dwordx4 v164, s[36:37]
	ds_read_b128 v[188:191], v219 offset:18432
	s_add_i32 m0, s4, 0x2000
	s_add_u32 s4, s36, 0x100000
	s_addc_u32 s5, s37, 0
	s_add_i32 s65, s60, s21
	global_load_lds_dwordx4 v168, s[36:37]
	ds_read_b128 v[192:195], v219 offset:19456
	s_mov_b32 m0, s65
	s_nop 0
	global_load_lds_dwordx4 v164, s[4:5]
	ds_read_b128 v[196:199], v219 offset:20480
	s_add_i32 m0, s65, 0x2000
	s_nop 0
	global_load_lds_dwordx4 v168, s[4:5]
	ds_read_b128 v[200:203], v219 offset:21504
	s_mov_b32 m0, s40
	s_nop 0
	global_load_lds_dwordx4 v162, s[38:39]
	ds_read_b128 v[204:207], v219 offset:22528
	s_mov_b32 m0, s41
	s_nop 0
	global_load_lds_dwordx4 v166, s[38:39]
	ds_read_b128 v[208:211], v219 offset:23552
	s_barrier
	s_setprio 1
	s_waitcnt lgkmcnt(0)
	v_mfma_f32_16x16x32_bf16 v[110:113], v[130:133], v[180:183], v[110:113]
	v_mfma_f32_16x16x32_bf16 v[78:81], v[138:141], v[180:183], v[78:81]
	v_mfma_f32_16x16x32_bf16 v[106:109], v[130:133], v[188:191], v[106:109]
	v_mfma_f32_16x16x32_bf16 v[74:77], v[138:141], v[188:191], v[74:77]
	v_mfma_f32_16x16x32_bf16 v[102:105], v[130:133], v[196:199], v[102:105]
	v_mfma_f32_16x16x32_bf16 v[70:73], v[138:141], v[196:199], v[70:73]
	v_mfma_f32_16x16x32_bf16 v[98:101], v[130:133], v[204:207], v[98:101]
	v_mfma_f32_16x16x32_bf16 v[66:69], v[138:141], v[204:207], v[66:69]
	v_mfma_f32_16x16x32_bf16 v[110:113], v[134:137], v[184:187], v[110:113]
	v_mfma_f32_16x16x32_bf16 v[78:81], v[142:145], v[184:187], v[78:81]
	v_mfma_f32_16x16x32_bf16 v[106:109], v[134:137], v[192:195], v[106:109]
	v_mfma_f32_16x16x32_bf16 v[74:77], v[142:145], v[192:195], v[74:77]
	v_mfma_f32_16x16x32_bf16 v[102:105], v[134:137], v[200:203], v[102:105]
	v_mfma_f32_16x16x32_bf16 v[70:73], v[142:145], v[200:203], v[70:73]
	v_mfma_f32_16x16x32_bf16 v[98:101], v[134:137], v[208:211], v[98:101]
	v_mfma_f32_16x16x32_bf16 v[66:69], v[142:145], v[208:211], v[66:69]
	v_mfma_f32_16x16x32_bf16 v[46:49], v[146:149], v[180:183], v[46:49]
	v_mfma_f32_16x16x32_bf16 v[14:17], v[154:157], v[180:183], v[14:17]
	v_mfma_f32_16x16x32_bf16 v[42:45], v[146:149], v[188:191], v[42:45]
	v_mfma_f32_16x16x32_bf16 v[10:13], v[154:157], v[188:191], v[10:13]
	v_mfma_f32_16x16x32_bf16 v[38:41], v[146:149], v[196:199], v[38:41]
	v_mfma_f32_16x16x32_bf16 v[6:9], v[154:157], v[196:199], v[6:9]
	v_mfma_f32_16x16x32_bf16 v[34:37], v[146:149], v[204:207], v[34:37]
	v_mfma_f32_16x16x32_bf16 v[2:5], v[154:157], v[204:207], v[2:5]
	v_mfma_f32_16x16x32_bf16 v[46:49], v[150:153], v[184:187], v[46:49]
	v_mfma_f32_16x16x32_bf16 v[14:17], v[158:161], v[184:187], v[14:17]
	v_mfma_f32_16x16x32_bf16 v[42:45], v[150:153], v[192:195], v[42:45]
	v_mfma_f32_16x16x32_bf16 v[10:13], v[158:161], v[192:195], v[10:13]
	v_mfma_f32_16x16x32_bf16 v[38:41], v[150:153], v[200:203], v[38:41]
	v_mfma_f32_16x16x32_bf16 v[6:9], v[158:161], v[200:203], v[6:9]
	v_mfma_f32_16x16x32_bf16 v[34:37], v[150:153], v[208:211], v[34:37]
	v_mfma_f32_16x16x32_bf16 v[2:5], v[158:161], v[208:211], v[2:5]
	s_waitcnt vmcnt(8)
	s_barrier
; #define PG8_STAGE(bufoff, gbase, voff) do { _Pragma("unroll") for (int _i = 0; _i < 2; ++_i) \
;         __builtin_amdgcn_global_load_lds((const unsigned*)((const char*)(gbase) + (voff)[_i]), (LAS unsigned*)(lds + (bufoff) + ldsw + _i * 8192), 16, 0, 0); } while (0)
; #define PG8_LDA(dst, b, h) do { _Pragma("unroll") for (int m = 0; m < 4; ++m) _Pragma("unroll") for (int k = 0; k < 2; ++k) dst[m][k] = *(const LAS bf16x8*)(lds + PG8_SA(b, h) + aoff + m * 2048 + k * 1024); } while (0)
; #define PG8_LDB(dst, b, h) do { _Pragma("unroll") for (int n = 0; n < 2; ++n) _Pragma("unroll") for (int k = 0; k < 2; ++k) dst[n][k] = *(const LAS bf16x8*)(lds + PG8_SB(b, h) + boff + n * 2048 + k * 1024); } while (0)
; #define PG8_BAR __builtin_amdgcn_s_barrier()
; template <class Epi, class Sched, bool ALIGN_EPI, class Hook = NoHook>
; __device__ __forceinline__ void gemm_phase(LAS unsigned char* lds, const Gemm g, const Sched& S, const Epi& E, const Hook& H = Hook()) {
;     ...
;         for (int t = tb; t < te; t += 2) {
;             const bool last = (t == nt - 2);
;             const char* a1 = cA + (size_t)(t + 1) * kstep;
;             const char* a2 = last ? nA : cA + (size_t)(t + 2) * kstep; const char* b2 = last ? nB : cB + (size_t)(t + 2) * kstep;
;             const char* a3 = a2 + kstep; const char* b3 = b2 + kstep;
;             if (last && has_next) S.a_ready(nxt);
;             PG8_LDB(B0, 0, 0); PG8_LDB(B1, 0, 1); PG8_SCHED; PG8_LDA(At, 0, 0); PG8_STAGE(PG8_SA(1, 1), a1 + hA, voffA);
;             PG8_WAIT_V(8); PG8_WAIT_L(0); PG8_BAR; PG8_MMA(0, 0, At, B0); PG8_MMA(0, 1, At, B1); PG8_BAR; PG8_SCHED;
;             PG8_LDA(At, 0, 1); PG8_STAGE(PG8_SB(0, 0), b2, voffB); PG8_STAGE(PG8_SB(0, 1), b2 + hB, voffB); PG8_STAGE(PG8_SA(0, 0), a2, voffA);
;             PG8_WAIT_V(8); PG8_WAIT_L(0); PG8_BAR; PG8_MMA(1, 0, At, B0); PG8_MMA(1, 1, At, B1); PG8_BAR; PG8_SCHED;
;             PG8_LDB(B0, 1, 0); PG8_LDB(B1, 1, 1); PG8_SCHED; PG8_LDA(At, 1, 0); PG8_STAGE(PG8_SA(0, 1), a2 + hA, voffA);
;             PG8_WAIT_V(8); PG8_WAIT_L(0); PG8_BAR; PG8_MMA(0, 0, At, B0); PG8_MMA(0, 1, At, B1); PG8_BAR; PG8_SCHED;
;             PG8_LDA(At, 1, 1); PG8_STAGE(PG8_SB(1, 0), b3, voffB); PG8_STAGE(PG8_SB(1, 1), b3 + hB, voffB); PG8_STAGE(PG8_SA(1, 0), a3, voffA);
;             PG8_WAIT_V(8); PG8_WAIT_L(0); PG8_BAR; PG8_MMA(1, 0, At, B0); PG8_MMA(1, 1, At, B1); PG8_BAR; PG8_SCHED;
	s_setprio 0
	s_add_i32 s65, 0, 0x18000
	s_add_i32 s66, 0, 0x1c000
	v_add_u32_e32 v142, s65, v213
	v_add_u32_e32 v158, s66, v213
	ds_read_b128 v[130:133], v142
	ds_read_b128 v[134:137], v142 offset:1024
	s_add_u32 s4, s38, 0x8000
	s_addc_u32 s5, s39, 0
	s_mov_b32 m0, s42
	s_nop 0
	global_load_lds_dwordx4 v162, s[4:5]
	ds_read_b128 v[138:141], v142 offset:2048
	ds_read_b128 v[142:145], v142 offset:3072
	ds_read_b128 v[146:149], v158
	ds_read_b128 v[150:153], v158 offset:1024
	ds_read_b128 v[154:157], v158 offset:2048
	ds_read_b128 v[158:161], v158 offset:3072
	ds_read_b128 v[180:183], v219 offset:32768
	s_mov_b32 m0, s43
	s_nop 0
	global_load_lds_dwordx4 v166, s[4:5]
	ds_read_b128 v[184:187], v219 offset:33792
	ds_read_b128 v[188:191], v219 offset:34816
	ds_read_b128 v[192:195], v219 offset:35840
	ds_read_b128 v[196:199], v219 offset:36864
	ds_read_b128 v[200:203], v219 offset:37888
	ds_read_b128 v[204:207], v219 offset:38912
	ds_read_b128 v[208:211], v219 offset:39936
	s_barrier
	s_setprio 1
	s_waitcnt lgkmcnt(0)
	v_mfma_f32_16x16x32_bf16 v[126:129], v[130:133], v[180:183], v[126:129]
	v_mfma_f32_16x16x32_bf16 v[94:97], v[138:141], v[180:183], v[94:97]
	v_mfma_f32_16x16x32_bf16 v[122:125], v[130:133], v[188:191], v[122:125]
	v_mfma_f32_16x16x32_bf16 v[90:93], v[138:141], v[188:191], v[90:93]
	v_mfma_f32_16x16x32_bf16 v[118:121], v[130:133], v[196:199], v[118:121]
	v_mfma_f32_16x16x32_bf16 v[86:89], v[138:141], v[196:199], v[86:89]
	v_mfma_f32_16x16x32_bf16 v[114:117], v[130:133], v[204:207], v[114:117]
	v_mfma_f32_16x16x32_bf16 v[82:85], v[138:141], v[204:207], v[82:85]
	v_mfma_f32_16x16x32_bf16 v[126:129], v[134:137], v[184:187], v[126:129]
	v_mfma_f32_16x16x32_bf16 v[94:97], v[142:145], v[184:187], v[94:97]
	v_mfma_f32_16x16x32_bf16 v[122:125], v[134:137], v[192:195], v[122:125]
	v_mfma_f32_16x16x32_bf16 v[90:93], v[142:145], v[192:195], v[90:93]
	v_mfma_f32_16x16x32_bf16 v[118:121], v[134:137], v[200:203], v[118:121]
	v_mfma_f32_16x16x32_bf16 v[86:89], v[142:145], v[200:203], v[86:89]
	v_mfma_f32_16x16x32_bf16 v[114:117], v[134:137], v[208:211], v[114:117]
	v_mfma_f32_16x16x32_bf16 v[82:85], v[142:145], v[208:211], v[82:85]
	v_mfma_f32_16x16x32_bf16 v[62:65], v[146:149], v[180:183], v[62:65]
	v_mfma_f32_16x16x32_bf16 v[30:33], v[154:157], v[180:183], v[30:33]
	v_mfma_f32_16x16x32_bf16 v[58:61], v[146:149], v[188:191], v[58:61]
	v_mfma_f32_16x16x32_bf16 v[26:29], v[154:157], v[188:191], v[26:29]
	v_mfma_f32_16x16x32_bf16 v[54:57], v[146:149], v[196:199], v[54:57]
	v_mfma_f32_16x16x32_bf16 v[22:25], v[154:157], v[196:199], v[22:25]
	v_mfma_f32_16x16x32_bf16 v[50:53], v[146:149], v[204:207], v[50:53]
	v_mfma_f32_16x16x32_bf16 v[18:21], v[154:157], v[204:207], v[18:21]
	v_mfma_f32_16x16x32_bf16 v[62:65], v[150:153], v[184:187], v[62:65]
	v_mfma_f32_16x16x32_bf16 v[30:33], v[158:161], v[184:187], v[30:33]
	v_mfma_f32_16x16x32_bf16 v[58:61], v[150:153], v[192:195], v[58:61]
	v_mfma_f32_16x16x32_bf16 v[26:29], v[158:161], v[192:195], v[26:29]
	v_mfma_f32_16x16x32_bf16 v[54:57], v[150:153], v[200:203], v[54:57]
	v_mfma_f32_16x16x32_bf16 v[22:25], v[158:161], v[200:203], v[22:25]
	v_mfma_f32_16x16x32_bf16 v[50:53], v[150:153], v[208:211], v[50:53]
	v_mfma_f32_16x16x32_bf16 v[18:21], v[158:161], v[208:211], v[18:21]
	s_waitcnt vmcnt(8)
	s_barrier
	s_setprio 0
	s_add_i32 s4, s65, s21
	s_add_u32 s68, s36, s14
	s_addc_u32 s69, s37, s15
	s_mov_b32 m0, s4
	ds_read_b128 v[180:183], v219 offset:49152
	ds_read_b128 v[184:187], v219 offset:50176
	global_load_lds_dwordx4 v164, s[68:69]
	ds_read_b128 v[188:191], v219 offset:51200
	s_add_i32 m0, s4, 0x2000
	s_add_u32 s4, s36, 0x100080
	s_addc_u32 s5, s37, 0
	s_add_i32 s36, s66, s21
	global_load_lds_dwordx4 v168, s[68:69]
	ds_read_b128 v[192:195], v219 offset:52224
	s_mov_b32 m0, s36
	s_nop 0
	global_load_lds_dwordx4 v164, s[4:5]
	ds_read_b128 v[196:199], v219 offset:53248
	s_add_i32 m0, s36, 0x2000
	s_nop 0
	global_load_lds_dwordx4 v168, s[4:5]
	ds_read_b128 v[200:203], v219 offset:54272
	s_add_u32 s70, s38, s14
	s_addc_u32 s71, s39, s15
	s_mov_b32 m0, s51
	s_nop 0
	global_load_lds_dwordx4 v162, s[70:71]
	ds_read_b128 v[204:207], v219 offset:55296
	s_mov_b32 m0, s52
	s_nop 0
	global_load_lds_dwordx4 v166, s[70:71]
	s_add_i32 s64, s64, 2
	s_add_u32 s31, s31, 0x100
	s_addc_u32 s63, s63, 0
	s_cmp_gt_u32 s64, 61
	s_mov_b64 s[4:5], s[34:35]
	ds_read_b128 v[208:211], v219 offset:56320
	s_barrier
	s_setprio 1
	s_waitcnt lgkmcnt(0)
	v_mfma_f32_16x16x32_bf16 v[110:113], v[130:133], v[180:183], v[110:113]
	v_mfma_f32_16x16x32_bf16 v[78:81], v[138:141], v[180:183], v[78:81]
	v_mfma_f32_16x16x32_bf16 v[106:109], v[130:133], v[188:191], v[106:109]
	v_mfma_f32_16x16x32_bf16 v[74:77], v[138:141], v[188:191], v[74:77]
	v_mfma_f32_16x16x32_bf16 v[102:105], v[130:133], v[196:199], v[102:105]
	v_mfma_f32_16x16x32_bf16 v[70:73], v[138:141], v[196:199], v[70:73]
	v_mfma_f32_16x16x32_bf16 v[98:101], v[130:133], v[204:207], v[98:101]
	v_mfma_f32_16x16x32_bf16 v[66:69], v[138:141], v[204:207], v[66:69]
	v_mfma_f32_16x16x32_bf16 v[110:113], v[134:137], v[184:187], v[110:113]
	v_mfma_f32_16x16x32_bf16 v[78:81], v[142:145], v[184:187], v[78:81]
	v_mfma_f32_16x16x32_bf16 v[106:109], v[134:137], v[192:195], v[106:109]
	v_mfma_f32_16x16x32_bf16 v[74:77], v[142:145], v[192:195], v[74:77]
	v_mfma_f32_16x16x32_bf16 v[102:105], v[134:137], v[200:203], v[102:105]
	v_mfma_f32_16x16x32_bf16 v[70:73], v[142:145], v[200:203], v[70:73]
	v_mfma_f32_16x16x32_bf16 v[98:101], v[134:137], v[208:211], v[98:101]
	v_mfma_f32_16x16x32_bf16 v[66:69], v[142:145], v[208:211], v[66:69]
	v_mfma_f32_16x16x32_bf16 v[46:49], v[146:149], v[180:183], v[46:49]
	v_mfma_f32_16x16x32_bf16 v[14:17], v[154:157], v[180:183], v[14:17]
	v_mfma_f32_16x16x32_bf16 v[42:45], v[146:149], v[188:191], v[42:45]
	v_mfma_f32_16x16x32_bf16 v[10:13], v[154:157], v[188:191], v[10:13]
	v_mfma_f32_16x16x32_bf16 v[38:41], v[146:149], v[196:199], v[38:41]
	v_mfma_f32_16x16x32_bf16 v[6:9], v[154:157], v[196:199], v[6:9]
	v_mfma_f32_16x16x32_bf16 v[34:37], v[146:149], v[204:207], v[34:37]
	v_mfma_f32_16x16x32_bf16 v[2:5], v[154:157], v[204:207], v[2:5]
	v_mfma_f32_16x16x32_bf16 v[46:49], v[150:153], v[184:187], v[46:49]
	v_mfma_f32_16x16x32_bf16 v[14:17], v[158:161], v[184:187], v[14:17]
	v_mfma_f32_16x16x32_bf16 v[42:45], v[150:153], v[192:195], v[42:45]
	v_mfma_f32_16x16x32_bf16 v[10:13], v[158:161], v[192:195], v[10:13]
	v_mfma_f32_16x16x32_bf16 v[38:41], v[150:153], v[200:203], v[38:41]
	v_mfma_f32_16x16x32_bf16 v[6:9], v[158:161], v[200:203], v[6:9]
	v_mfma_f32_16x16x32_bf16 v[34:37], v[150:153], v[208:211], v[34:37]
	v_mfma_f32_16x16x32_bf16 v[2:5], v[158:161], v[208:211], v[2:5]
	s_waitcnt vmcnt(8)
	s_barrier
	s_setprio 0
	s_cbranch_scc0 .LBB0_199
	s_branch .Lmy_d199X
; #define PG8_STAGE(bufoff, gbase, voff) do { _Pragma("unroll") for (int _i = 0; _i < 2; ++_i) \
;         __builtin_amdgcn_global_load_lds((const unsigned*)((const char*)(gbase) + (voff)[_i]), (LAS unsigned*)(lds + (bufoff) + ldsw + _i * 8192), 16, 0, 0); } while (0)
; #define PG8_LDA(dst, b, h) do { _Pragma("unroll") for (int m = 0; m < 4; ++m) _Pragma("unroll") for (int k = 0; k < 2; ++k) dst[m][k] = *(const LAS bf16x8*)(lds + PG8_SA(b, h) + aoff + m * 2048 + k * 1024); } while (0)
; #define PG8_LDB(dst, b, h) do { _Pragma("unroll") for (int n = 0; n < 2; ++n) _Pragma("unroll") for (int k = 0; k < 2; ++k) dst[n][k] = *(const LAS bf16x8*)(lds + PG8_SB(b, h) + boff + n * 2048 + k * 1024); } while (0)
; #define PG8_MMA(ai, bj, At, Bt) do { __builtin_amdgcn_s_setprio(1); _Pragma("unroll") for (int m = 0; m < 4; ++m) _Pragma("unroll") for (int n = 0; n < 2; ++n) _Pragma("unroll") for (int k = 0; k < 2; ++k) \
;         acc[ai][bj][m][n] = __builtin_amdgcn_mfma_f32_16x16x32_bf16(Bt[n][k], At[m][k], acc[ai][bj][m][n], 0, 0, 0); __builtin_amdgcn_s_setprio(0); } while (0)
; #define PG8_WAIT_V(n) asm volatile("s_waitcnt vmcnt(" #n ")" ::: "memory")
; #define PG8_WAIT_L(n) asm volatile("s_waitcnt lgkmcnt(" #n ")" ::: "memory")
; #define PG8_BAR __builtin_amdgcn_s_barrier()
; #define PG8_SCHED __builtin_amdgcn_sched_barrier(0)
; template <class Epi, class Sched, bool ALIGN_EPI, class Hook = NoHook>
; __device__ __forceinline__ void gemm_phase(LAS unsigned char* lds, const Gemm g, const Sched& S, const Epi& E, const Hook& H = Hook()) {
;     ...
;             PG8_LDB(B0, 0, 0); PG8_LDB(B1, 0, 1); PG8_SCHED; PG8_LDA(At, 0, 0); PG8_STAGE(PG8_SA(1, 1), a1 + hA, voffA);
;             PG8_WAIT_V(8); PG8_WAIT_L(0); PG8_BAR; PG8_MMA(0, 0, At, B0); PG8_MMA(0, 1, At, B1); PG8_BAR; PG8_SCHED;
;             PG8_LDA(At, 0, 1); PG8_STAGE(PG8_SB(0, 0), b2, voffB); PG8_STAGE(PG8_SB(0, 1), b2 + hB, voffB); PG8_STAGE(PG8_SA(0, 0), a2, voffA);
;             PG8_WAIT_V(8); PG8_WAIT_L(0); PG8_BAR; PG8_MMA(1, 0, At, B0); PG8_MMA(1, 1, At, B1); PG8_BAR; PG8_SCHED;
.Lmy_d199B:
	ds_read_b128 v[130:133], v217
	ds_read_b128 v[134:137], v217 offset:1024
	s_add_i32 m0, s40, 0xc000
	s_nop 0
	global_load_lds_dwordx4 v172, s[4:5]
	ds_read_b128 v[138:141], v217 offset:2048
	ds_read_b128 v[142:145], v217 offset:3072
	ds_read_b128 v[146:149], v218
	ds_read_b128 v[150:153], v218 offset:1024
	ds_read_b128 v[154:157], v218 offset:2048
	ds_read_b128 v[158:161], v218 offset:3072
	ds_read_b128 v[180:183], v219
	s_add_i32 m0, s40, 0xe000
	s_nop 0
	global_load_lds_dwordx4 v174, s[4:5]
	s_add_u32 s34, s4, 0x100
	s_addc_u32 s35, s5, 0
	s_cmp_eq_u32 s64, 60
	s_cselect_b32 s39, s7, s35
	s_cselect_b32 s38, s8, s34
	s_cselect_b32 s37, s23, s63
	s_cselect_b32 s36, s25, s31
	ds_read_b128 v[184:187], v219 offset:1024
	ds_read_b128 v[188:191], v219 offset:2048
	ds_read_b128 v[192:195], v219 offset:3072
	ds_read_b128 v[196:199], v219 offset:4096
	ds_read_b128 v[200:203], v219 offset:5120
	ds_read_b128 v[204:207], v219 offset:6144
	ds_read_b128 v[208:211], v219 offset:7168
	s_waitcnt vmcnt(8) lgkmcnt(0)
	s_barrier
	s_setprio 1
	v_mfma_f32_16x16x32_bf16 v[126:129], v[130:133], v[180:183], v[126:129]
	v_mfma_f32_16x16x32_bf16 v[94:97], v[138:141], v[180:183], v[94:97]
	v_mfma_f32_16x16x32_bf16 v[122:125], v[130:133], v[188:191], v[122:125]
	v_mfma_f32_16x16x32_bf16 v[90:93], v[138:141], v[188:191], v[90:93]
	v_mfma_f32_16x16x32_bf16 v[118:121], v[130:133], v[196:199], v[118:121]
	v_mfma_f32_16x16x32_bf16 v[86:89], v[138:141], v[196:199], v[86:89]
	v_mfma_f32_16x16x32_bf16 v[114:117], v[130:133], v[204:207], v[114:117]
	v_mfma_f32_16x16x32_bf16 v[82:85], v[138:141], v[204:207], v[82:85]
	v_mfma_f32_16x16x32_bf16 v[126:129], v[134:137], v[184:187], v[126:129]
	v_mfma_f32_16x16x32_bf16 v[94:97], v[142:145], v[184:187], v[94:97]
	v_mfma_f32_16x16x32_bf16 v[122:125], v[134:137], v[192:195], v[122:125]
	v_mfma_f32_16x16x32_bf16 v[90:93], v[142:145], v[192:195], v[90:93]
	v_mfma_f32_16x16x32_bf16 v[118:121], v[134:137], v[200:203], v[118:121]
	v_mfma_f32_16x16x32_bf16 v[86:89], v[142:145], v[200:203], v[86:89]
	v_mfma_f32_16x16x32_bf16 v[114:117], v[134:137], v[208:211], v[114:117]
	v_mfma_f32_16x16x32_bf16 v[82:85], v[142:145], v[208:211], v[82:85]
	v_mfma_f32_16x16x32_bf16 v[62:65], v[146:149], v[180:183], v[62:65]
	v_mfma_f32_16x16x32_bf16 v[30:33], v[154:157], v[180:183], v[30:33]
	v_mfma_f32_16x16x32_bf16 v[58:61], v[146:149], v[188:191], v[58:61]
	v_mfma_f32_16x16x32_bf16 v[26:29], v[154:157], v[188:191], v[26:29]
	v_mfma_f32_16x16x32_bf16 v[54:57], v[146:149], v[196:199], v[54:57]
	v_mfma_f32_16x16x32_bf16 v[22:25], v[154:157], v[196:199], v[22:25]
	v_mfma_f32_16x16x32_bf16 v[50:53], v[146:149], v[204:207], v[50:53]
	v_mfma_f32_16x16x32_bf16 v[18:21], v[154:157], v[204:207], v[18:21]
	v_mfma_f32_16x16x32_bf16 v[62:65], v[150:153], v[184:187], v[62:65]
	v_mfma_f32_16x16x32_bf16 v[30:33], v[158:161], v[184:187], v[30:33]
	v_mfma_f32_16x16x32_bf16 v[58:61], v[150:153], v[192:195], v[58:61]
	v_mfma_f32_16x16x32_bf16 v[26:29], v[158:161], v[192:195], v[26:29]
	v_mfma_f32_16x16x32_bf16 v[54:57], v[150:153], v[200:203], v[54:57]
	v_mfma_f32_16x16x32_bf16 v[22:25], v[158:161], v[200:203], v[22:25]
	v_mfma_f32_16x16x32_bf16 v[50:53], v[150:153], v[208:211], v[50:53]
	v_mfma_f32_16x16x32_bf16 v[18:21], v[158:161], v[208:211], v[18:21]
	s_barrier
	s_setprio 0
	s_add_i32 s4, s59, s21
	s_mov_b32 m0, s4
	ds_read_b128 v[180:183], v219 offset:16384
	ds_read_b128 v[184:187], v219 offset:17408
	global_load_lds_dwordx4 v164, s[36:37]
	ds_read_b128 v[188:191], v219 offset:18432
	s_add_i32 m0, s4, 0x2000
	s_add_u32 s4, s36, 0x100000
	s_addc_u32 s5, s37, 0
	s_add_i32 s65, s60, s21
	global_load_lds_dwordx4 v168, s[36:37]
	ds_read_b128 v[192:195], v219 offset:19456
	s_mov_b32 m0, s65
	s_nop 0
	global_load_lds_dwordx4 v164, s[4:5]
	ds_read_b128 v[196:199], v219 offset:20480
	s_add_i32 m0, s65, 0x2000
	s_nop 0
	global_load_lds_dwordx4 v168, s[4:5]
	ds_read_b128 v[200:203], v219 offset:21504
	s_mov_b32 m0, s40
	s_nop 0
	global_load_lds_dwordx4 v162, s[38:39]
	ds_read_b128 v[204:207], v219 offset:22528
	s_mov_b32 m0, s41
	s_nop 0
	global_load_lds_dwordx4 v166, s[38:39]
	ds_read_b128 v[208:211], v219 offset:23552
	s_waitcnt vmcnt(8) lgkmcnt(0)
	s_barrier
	s_setprio 1
	v_mfma_f32_16x16x32_bf16 v[110:113], v[130:133], v[180:183], v[110:113]
	v_mfma_f32_16x16x32_bf16 v[78:81], v[138:141], v[180:183], v[78:81]
	v_mfma_f32_16x16x32_bf16 v[106:109], v[130:133], v[188:191], v[106:109]
	v_mfma_f32_16x16x32_bf16 v[74:77], v[138:141], v[188:191], v[74:77]
	v_mfma_f32_16x16x32_bf16 v[102:105], v[130:133], v[196:199], v[102:105]
	v_mfma_f32_16x16x32_bf16 v[70:73], v[138:141], v[196:199], v[70:73]
	v_mfma_f32_16x16x32_bf16 v[98:101], v[130:133], v[204:207], v[98:101]
	v_mfma_f32_16x16x32_bf16 v[66:69], v[138:141], v[204:207], v[66:69]
	v_mfma_f32_16x16x32_bf16 v[110:113], v[134:137], v[184:187], v[110:113]
	v_mfma_f32_16x16x32_bf16 v[78:81], v[142:145], v[184:187], v[78:81]
	v_mfma_f32_16x16x32_bf16 v[106:109], v[134:137], v[192:195], v[106:109]
	v_mfma_f32_16x16x32_bf16 v[74:77], v[142:145], v[192:195], v[74:77]
	v_mfma_f32_16x16x32_bf16 v[102:105], v[134:137], v[200:203], v[102:105]
	v_mfma_f32_16x16x32_bf16 v[70:73], v[142:145], v[200:203], v[70:73]
	v_mfma_f32_16x16x32_bf16 v[98:101], v[134:137], v[208:211], v[98:101]
	v_mfma_f32_16x16x32_bf16 v[66:69], v[142:145], v[208:211], v[66:69]
	v_mfma_f32_16x16x32_bf16 v[46:49], v[146:149], v[180:183], v[46:49]
	v_mfma_f32_16x16x32_bf16 v[14:17], v[154:157], v[180:183], v[14:17]
	v_mfma_f32_16x16x32_bf16 v[42:45], v[146:149], v[188:191], v[42:45]
	v_mfma_f32_16x16x32_bf16 v[10:13], v[154:157], v[188:191], v[10:13]
	v_mfma_f32_16x16x32_bf16 v[38:41], v[146:149], v[196:199], v[38:41]
	v_mfma_f32_16x16x32_bf16 v[6:9], v[154:157], v[196:199], v[6:9]
	v_mfma_f32_16x16x32_bf16 v[34:37], v[146:149], v[204:207], v[34:37]
	v_mfma_f32_16x16x32_bf16 v[2:5], v[154:157], v[204:207], v[2:5]
	v_mfma_f32_16x16x32_bf16 v[46:49], v[150:153], v[184:187], v[46:49]
	v_mfma_f32_16x16x32_bf16 v[14:17], v[158:161], v[184:187], v[14:17]
	v_mfma_f32_16x16x32_bf16 v[42:45], v[150:153], v[192:195], v[42:45]
	v_mfma_f32_16x16x32_bf16 v[10:13], v[158:161], v[192:195], v[10:13]
	v_mfma_f32_16x16x32_bf16 v[38:41], v[150:153], v[200:203], v[38:41]
	v_mfma_f32_16x16x32_bf16 v[6:9], v[158:161], v[200:203], v[6:9]
	v_mfma_f32_16x16x32_bf16 v[34:37], v[150:153], v[208:211], v[34:37]
	v_mfma_f32_16x16x32_bf16 v[2:5], v[158:161], v[208:211], v[2:5]
	s_barrier
; #define PG8_STAGE(bufoff, gbase, voff) do { _Pragma("unroll") for (int _i = 0; _i < 2; ++_i) \
;         __builtin_amdgcn_global_load_lds((const unsigned*)((const char*)(gbase) + (voff)[_i]), (LAS unsigned*)(lds + (bufoff) + ldsw + _i * 8192), 16, 0, 0); } while (0)
; #define PG8_LDA(dst, b, h) do { _Pragma("unroll") for (int m = 0; m < 4; ++m) _Pragma("unroll") for (int k = 0; k < 2; ++k) dst[m][k] = *(const LAS bf16x8*)(lds + PG8_SA(b, h) + aoff + m * 2048 + k * 1024); } while (0)
; #define PG8_LDB(dst, b, h) do { _Pragma("unroll") for (int n = 0; n < 2; ++n) _Pragma("unroll") for (int k = 0; k < 2; ++k) dst[n][k] = *(const LAS bf16x8*)(lds + PG8_SB(b, h) + boff + n * 2048 + k * 1024); } while (0)
; #define PG8_MMA(ai, bj, At, Bt) do { __builtin_amdgcn_s_setprio(1); _Pragma("unroll") for (int m = 0; m < 4; ++m) _Pragma("unroll") for (int n = 0; n < 2; ++n) _Pragma("unroll") for (int k = 0; k < 2; ++k) \
;         acc[ai][bj][m][n] = __builtin_amdgcn_mfma_f32_16x16x32_bf16(Bt[n][k], At[m][k], acc[ai][bj][m][n], 0, 0, 0); __builtin_amdgcn_s_setprio(0); } while (0)
; #define PG8_WAIT_V(n) asm volatile("s_waitcnt vmcnt(" #n ")" ::: "memory")
; #define PG8_WAIT_L(n) asm volatile("s_waitcnt lgkmcnt(" #n ")" ::: "memory")
; #define PG8_BAR __builtin_amdgcn_s_barrier()
; #define PG8_SCHED __builtin_amdgcn_sched_barrier(0)
; template <class Epi, class Sched, bool ALIGN_EPI, class Hook = NoHook>
; __device__ __forceinline__ void gemm_phase(LAS unsigned char* lds, const Gemm g, const Sched& S, const Epi& E, const Hook& H = Hook()) {
;     ...
;             PG8_LDB(B0, 1, 0); PG8_LDB(B1, 1, 1); PG8_SCHED; PG8_LDA(At, 1, 0); PG8_STAGE(PG8_SA(0, 1), a2 + hA, voffA);
;             PG8_WAIT_V(8); PG8_WAIT_L(0); PG8_BAR; PG8_MMA(0, 0, At, B0); PG8_MMA(0, 1, At, B1); PG8_BAR; PG8_SCHED;
;             PG8_LDA(At, 1, 1); PG8_STAGE(PG8_SB(1, 0), b3, voffB); PG8_STAGE(PG8_SB(1, 1), b3 + hB, voffB); PG8_STAGE(PG8_SA(1, 0), a3, voffA);
;             PG8_WAIT_V(8); PG8_WAIT_L(0); PG8_BAR; PG8_MMA(1, 0, At, B0); PG8_MMA(1, 1, At, B1); PG8_BAR; PG8_SCHED;
	s_setprio 0
	s_add_i32 s65, 0, 0x18000
	s_add_i32 s66, 0, 0x1c000
	v_add_u32_e32 v142, s65, v213
	v_add_u32_e32 v158, s66, v213
	ds_read_b128 v[130:133], v142
	ds_read_b128 v[134:137], v142 offset:1024
	s_add_u32 s4, s38, 0x8000
	s_addc_u32 s5, s39, 0
	s_mov_b32 m0, s42
	s_nop 0
	global_load_lds_dwordx4 v162, s[4:5]
	ds_read_b128 v[138:141], v142 offset:2048
	ds_read_b128 v[142:145], v142 offset:3072
	ds_read_b128 v[146:149], v158
	ds_read_b128 v[150:153], v158 offset:1024
	ds_read_b128 v[154:157], v158 offset:2048
	ds_read_b128 v[158:161], v158 offset:3072
	ds_read_b128 v[180:183], v219 offset:32768
	s_mov_b32 m0, s43
	s_nop 0
	global_load_lds_dwordx4 v166, s[4:5]
	ds_read_b128 v[184:187], v219 offset:33792
	ds_read_b128 v[188:191], v219 offset:34816
	ds_read_b128 v[192:195], v219 offset:35840
	ds_read_b128 v[196:199], v219 offset:36864
	ds_read_b128 v[200:203], v219 offset:37888
	ds_read_b128 v[204:207], v219 offset:38912
	ds_read_b128 v[208:211], v219 offset:39936
	s_waitcnt vmcnt(8) lgkmcnt(0)
	s_barrier
	s_setprio 1
	v_mfma_f32_16x16x32_bf16 v[126:129], v[130:133], v[180:183], v[126:129]
	v_mfma_f32_16x16x32_bf16 v[94:97], v[138:141], v[180:183], v[94:97]
	v_mfma_f32_16x16x32_bf16 v[122:125], v[130:133], v[188:191], v[122:125]
	v_mfma_f32_16x16x32_bf16 v[90:93], v[138:141], v[188:191], v[90:93]
	v_mfma_f32_16x16x32_bf16 v[118:121], v[130:133], v[196:199], v[118:121]
	v_mfma_f32_16x16x32_bf16 v[86:89], v[138:141], v[196:199], v[86:89]
	v_mfma_f32_16x16x32_bf16 v[114:117], v[130:133], v[204:207], v[114:117]
	v_mfma_f32_16x16x32_bf16 v[82:85], v[138:141], v[204:207], v[82:85]
	v_mfma_f32_16x16x32_bf16 v[126:129], v[134:137], v[184:187], v[126:129]
	v_mfma_f32_16x16x32_bf16 v[94:97], v[142:145], v[184:187], v[94:97]
	v_mfma_f32_16x16x32_bf16 v[122:125], v[134:137], v[192:195], v[122:125]
	v_mfma_f32_16x16x32_bf16 v[90:93], v[142:145], v[192:195], v[90:93]
	v_mfma_f32_16x16x32_bf16 v[118:121], v[134:137], v[200:203], v[118:121]
	v_mfma_f32_16x16x32_bf16 v[86:89], v[142:145], v[200:203], v[86:89]
	v_mfma_f32_16x16x32_bf16 v[114:117], v[134:137], v[208:211], v[114:117]
	v_mfma_f32_16x16x32_bf16 v[82:85], v[142:145], v[208:211], v[82:85]
	v_mfma_f32_16x16x32_bf16 v[62:65], v[146:149], v[180:183], v[62:65]
	v_mfma_f32_16x16x32_bf16 v[30:33], v[154:157], v[180:183], v[30:33]
	v_mfma_f32_16x16x32_bf16 v[58:61], v[146:149], v[188:191], v[58:61]
	v_mfma_f32_16x16x32_bf16 v[26:29], v[154:157], v[188:191], v[26:29]
	v_mfma_f32_16x16x32_bf16 v[54:57], v[146:149], v[196:199], v[54:57]
	v_mfma_f32_16x16x32_bf16 v[22:25], v[154:157], v[196:199], v[22:25]
	v_mfma_f32_16x16x32_bf16 v[50:53], v[146:149], v[204:207], v[50:53]
	v_mfma_f32_16x16x32_bf16 v[18:21], v[154:157], v[204:207], v[18:21]
	v_mfma_f32_16x16x32_bf16 v[62:65], v[150:153], v[184:187], v[62:65]
	v_mfma_f32_16x16x32_bf16 v[30:33], v[158:161], v[184:187], v[30:33]
	v_mfma_f32_16x16x32_bf16 v[58:61], v[150:153], v[192:195], v[58:61]
	v_mfma_f32_16x16x32_bf16 v[26:29], v[158:161], v[192:195], v[26:29]
	v_mfma_f32_16x16x32_bf16 v[54:57], v[150:153], v[200:203], v[54:57]
	v_mfma_f32_16x16x32_bf16 v[22:25], v[158:161], v[200:203], v[22:25]
	v_mfma_f32_16x16x32_bf16 v[50:53], v[150:153], v[208:211], v[50:53]
	v_mfma_f32_16x16x32_bf16 v[18:21], v[158:161], v[208:211], v[18:21]
	s_barrier
	s_setprio 0
	s_add_i32 s4, s65, s21
	s_add_u32 s68, s36, s14
	s_addc_u32 s69, s37, s15
	s_mov_b32 m0, s4
	ds_read_b128 v[180:183], v219 offset:49152
	ds_read_b128 v[184:187], v219 offset:50176
	global_load_lds_dwordx4 v164, s[68:69]
	ds_read_b128 v[188:191], v219 offset:51200
	s_add_i32 m0, s4, 0x2000
	s_add_u32 s4, s36, 0x100080
	s_addc_u32 s5, s37, 0
	s_add_i32 s36, s66, s21
	global_load_lds_dwordx4 v168, s[68:69]
	ds_read_b128 v[192:195], v219 offset:52224
	s_mov_b32 m0, s36
	s_nop 0
	global_load_lds_dwordx4 v164, s[4:5]
	ds_read_b128 v[196:199], v219 offset:53248
	s_add_i32 m0, s36, 0x2000
	s_nop 0
	global_load_lds_dwordx4 v168, s[4:5]
	ds_read_b128 v[200:203], v219 offset:54272
	s_add_u32 s70, s38, s14
	s_addc_u32 s71, s39, s15
	s_mov_b32 m0, s51
	s_nop 0
	global_load_lds_dwordx4 v162, s[70:71]
	ds_read_b128 v[204:207], v219 offset:55296
	s_mov_b32 m0, s52
	s_nop 0
	global_load_lds_dwordx4 v166, s[70:71]
	s_add_i32 s64, s64, 2
	s_add_u32 s31, s31, 0x100
	s_addc_u32 s63, s63, 0
	s_cmp_gt_u32 s64, 61
	s_mov_b64 s[4:5], s[34:35]
	ds_read_b128 v[208:211], v219 offset:56320
	s_waitcnt vmcnt(8) lgkmcnt(0)
	s_barrier
	s_setprio 1
	v_mfma_f32_16x16x32_bf16 v[110:113], v[130:133], v[180:183], v[110:113]
	v_mfma_f32_16x16x32_bf16 v[78:81], v[138:141], v[180:183], v[78:81]
	v_mfma_f32_16x16x32_bf16 v[106:109], v[130:133], v[188:191], v[106:109]
	v_mfma_f32_16x16x32_bf16 v[74:77], v[138:141], v[188:191], v[74:77]
	v_mfma_f32_16x16x32_bf16 v[102:105], v[130:133], v[196:199], v[102:105]
	v_mfma_f32_16x16x32_bf16 v[70:73], v[138:141], v[196:199], v[70:73]
	v_mfma_f32_16x16x32_bf16 v[98:101], v[130:133], v[204:207], v[98:101]
	v_mfma_f32_16x16x32_bf16 v[66:69], v[138:141], v[204:207], v[66:69]
	v_mfma_f32_16x16x32_bf16 v[110:113], v[134:137], v[184:187], v[110:113]
	v_mfma_f32_16x16x32_bf16 v[78:81], v[142:145], v[184:187], v[78:81]
	v_mfma_f32_16x16x32_bf16 v[106:109], v[134:137], v[192:195], v[106:109]
	v_mfma_f32_16x16x32_bf16 v[74:77], v[142:145], v[192:195], v[74:77]
	v_mfma_f32_16x16x32_bf16 v[102:105], v[134:137], v[200:203], v[102:105]
	v_mfma_f32_16x16x32_bf16 v[70:73], v[142:145], v[200:203], v[70:73]
	v_mfma_f32_16x16x32_bf16 v[98:101], v[134:137], v[208:211], v[98:101]
	v_mfma_f32_16x16x32_bf16 v[66:69], v[142:145], v[208:211], v[66:69]
	v_mfma_f32_16x16x32_bf16 v[46:49], v[146:149], v[180:183], v[46:49]
	v_mfma_f32_16x16x32_bf16 v[14:17], v[154:157], v[180:183], v[14:17]
	v_mfma_f32_16x16x32_bf16 v[42:45], v[146:149], v[188:191], v[42:45]
	v_mfma_f32_16x16x32_bf16 v[10:13], v[154:157], v[188:191], v[10:13]
	v_mfma_f32_16x16x32_bf16 v[38:41], v[146:149], v[196:199], v[38:41]
	v_mfma_f32_16x16x32_bf16 v[6:9], v[154:157], v[196:199], v[6:9]
	v_mfma_f32_16x16x32_bf16 v[34:37], v[146:149], v[204:207], v[34:37]
	v_mfma_f32_16x16x32_bf16 v[2:5], v[154:157], v[204:207], v[2:5]
	v_mfma_f32_16x16x32_bf16 v[46:49], v[150:153], v[184:187], v[46:49]
	v_mfma_f32_16x16x32_bf16 v[14:17], v[158:161], v[184:187], v[14:17]
	v_mfma_f32_16x16x32_bf16 v[42:45], v[150:153], v[192:195], v[42:45]
	v_mfma_f32_16x16x32_bf16 v[10:13], v[158:161], v[192:195], v[10:13]
	v_mfma_f32_16x16x32_bf16 v[38:41], v[150:153], v[200:203], v[38:41]
	v_mfma_f32_16x16x32_bf16 v[6:9], v[158:161], v[200:203], v[6:9]
	v_mfma_f32_16x16x32_bf16 v[34:37], v[150:153], v[208:211], v[34:37]
	v_mfma_f32_16x16x32_bf16 v[2:5], v[158:161], v[208:211], v[2:5]
	s_barrier
	s_setprio 0
	s_cbranch_scc0 .Lmy_d199B

; #define PG8_STAGE(bufoff, gbase, voff) do { _Pragma("unroll") for (int _i = 0; _i < 2; ++_i) \
;         __builtin_amdgcn_global_load_lds((const unsigned*)((const char*)(gbase) + (voff)[_i]), (LAS unsigned*)(lds + (bufoff) + ldsw + _i * 8192), 16, 0, 0); } while (0)
; #define PG8_LDA(dst, b, h) do { _Pragma("unroll") for (int m = 0; m < 4; ++m) _Pragma("unroll") for (int k = 0; k < 2; ++k) dst[m][k] = *(const LAS bf16x8*)(lds + PG8_SA(b, h) + aoff + m * 2048 + k * 1024); } while (0)
; #define PG8_LDB(dst, b, h) do { _Pragma("unroll") for (int n = 0; n < 2; ++n) _Pragma("unroll") for (int k = 0; k < 2; ++k) dst[n][k] = *(const LAS bf16x8*)(lds + PG8_SB(b, h) + boff + n * 2048 + k * 1024); } while (0)
; #define PG8_MMA(ai, bj, At, Bt) do { __builtin_amdgcn_s_setprio(1); _Pragma("unroll") for (int m = 0; m < 4; ++m) _Pragma("unroll") for (int n = 0; n < 2; ++n) _Pragma("unroll") for (int k = 0; k < 2; ++k) \
;         acc[ai][bj][m][n] = __builtin_amdgcn_mfma_f32_16x16x32_bf16(Bt[n][k], At[m][k], acc[ai][bj][m][n], 0, 0, 0); __builtin_amdgcn_s_setprio(0); } while (0)
; #define PG8_WAIT_V(n) asm volatile("s_waitcnt vmcnt(" #n ")" ::: "memory")
; #define PG8_WAIT_L(n) asm volatile("s_waitcnt lgkmcnt(" #n ")" ::: "memory")
; #define PG8_BAR __builtin_amdgcn_s_barrier()
; #define PG8_SCHED __builtin_amdgcn_sched_barrier(0)
; template <class Epi, class Sched, bool ALIGN_EPI, class Hook = NoHook>
; __device__ __forceinline__ void gemm_phase(LAS unsigned char* lds, const Gemm g, const Sched& S, const Epi& E, const Hook& H = Hook()) {
;     ...
;             PG8_LDB(B0, 0, 0); PG8_LDB(B1, 0, 1); PG8_SCHED; PG8_LDA(At, 0, 0); PG8_STAGE(PG8_SA(1, 1), a1 + hA, voffA);
;             PG8_WAIT_V(8); PG8_WAIT_L(0); PG8_BAR; PG8_MMA(0, 0, At, B0); PG8_MMA(0, 1, At, B1); PG8_BAR; PG8_SCHED;
;             PG8_LDA(At, 0, 1); PG8_STAGE(PG8_SB(0, 0), b2, voffB); PG8_STAGE(PG8_SB(0, 1), b2 + hB, voffB); PG8_STAGE(PG8_SA(0, 0), a2, voffA);
;             PG8_WAIT_V(8); PG8_WAIT_L(0); PG8_BAR; PG8_MMA(1, 0, At, B0); PG8_MMA(1, 1, At, B1); PG8_BAR; PG8_SCHED;
.LBB0_262:
	ds_read_b128 v[148:151], v145
	ds_read_b128 v[152:155], v145 offset:1024
	s_add_u32 s22, s20, 0xfff00080
	s_addc_u32 s23, s21, -1
	s_cmp_eq_u32 s50, 4
	s_cselect_b32 s25, s11, s23
	s_cselect_b32 s24, s13, s22
	s_cselect_b32 s23, s40, s43
	s_cselect_b32 s22, s41, s42
	s_add_i32 m0, s5, 0xc000
	s_nop 0
	global_load_lds_dwordx4 v136, s[20:21]
	ds_read_b128 v[156:159], v145 offset:2048
	ds_read_b128 v[160:163], v145 offset:3072
	ds_read_b128 v[164:167], v146
	ds_read_b128 v[168:171], v146 offset:1024
	ds_read_b128 v[172:175], v146 offset:2048
	ds_read_b128 v[176:179], v146 offset:3072
	ds_read_b128 v[180:183], v147
	s_add_i32 m0, s5, 0xe000
	s_nop 0
	global_load_lds_dwordx4 v138, s[20:21]
	ds_read_b128 v[184:187], v147 offset:1024
	ds_read_b128 v[188:191], v147 offset:2048
	ds_read_b128 v[192:195], v147 offset:3072
	ds_read_b128 v[196:199], v147 offset:4096
	ds_read_b128 v[200:203], v147 offset:5120
	ds_read_b128 v[204:207], v147 offset:6144
	ds_read_b128 v[208:211], v147 offset:7168
	s_waitcnt vmcnt(8) lgkmcnt(0)
	s_barrier
	s_setprio 1
	v_mfma_f32_16x16x32_bf16 v[126:129], v[148:151], v[180:183], v[126:129]
	v_mfma_f32_16x16x32_bf16 v[122:125], v[156:159], v[180:183], v[122:125]
	v_mfma_f32_16x16x32_bf16 v[118:121], v[148:151], v[188:191], v[118:121]
	v_mfma_f32_16x16x32_bf16 v[114:117], v[156:159], v[188:191], v[114:117]
	v_mfma_f32_16x16x32_bf16 v[106:109], v[148:151], v[196:199], v[106:109]
	v_mfma_f32_16x16x32_bf16 v[98:101], v[156:159], v[196:199], v[98:101]
	v_mfma_f32_16x16x32_bf16 v[90:93], v[148:151], v[204:207], v[90:93]
	v_mfma_f32_16x16x32_bf16 v[82:85], v[156:159], v[204:207], v[82:85]
	v_mfma_f32_16x16x32_bf16 v[126:129], v[152:155], v[184:187], v[126:129]
	v_mfma_f32_16x16x32_bf16 v[122:125], v[160:163], v[184:187], v[122:125]
	v_mfma_f32_16x16x32_bf16 v[118:121], v[152:155], v[192:195], v[118:121]
	v_mfma_f32_16x16x32_bf16 v[114:117], v[160:163], v[192:195], v[114:117]
	v_mfma_f32_16x16x32_bf16 v[106:109], v[152:155], v[200:203], v[106:109]
	v_mfma_f32_16x16x32_bf16 v[98:101], v[160:163], v[200:203], v[98:101]
	v_mfma_f32_16x16x32_bf16 v[90:93], v[152:155], v[208:211], v[90:93]
	v_mfma_f32_16x16x32_bf16 v[82:85], v[160:163], v[208:211], v[82:85]
	v_mfma_f32_16x16x32_bf16 v[110:113], v[164:167], v[180:183], v[110:113]
	v_mfma_f32_16x16x32_bf16 v[102:105], v[172:175], v[180:183], v[102:105]
	v_mfma_f32_16x16x32_bf16 v[94:97], v[164:167], v[188:191], v[94:97]
	v_mfma_f32_16x16x32_bf16 v[86:89], v[172:175], v[188:191], v[86:89]
	v_mfma_f32_16x16x32_bf16 v[78:81], v[164:167], v[196:199], v[78:81]
	v_mfma_f32_16x16x32_bf16 v[74:77], v[172:175], v[196:199], v[74:77]
	v_mfma_f32_16x16x32_bf16 v[70:73], v[164:167], v[204:207], v[70:73]
	v_mfma_f32_16x16x32_bf16 v[66:69], v[172:175], v[204:207], v[66:69]
	v_mfma_f32_16x16x32_bf16 v[110:113], v[168:171], v[184:187], v[110:113]
	v_mfma_f32_16x16x32_bf16 v[102:105], v[176:179], v[184:187], v[102:105]
	v_mfma_f32_16x16x32_bf16 v[94:97], v[168:171], v[192:195], v[94:97]
	v_mfma_f32_16x16x32_bf16 v[86:89], v[176:179], v[192:195], v[86:89]
	v_mfma_f32_16x16x32_bf16 v[78:81], v[168:171], v[200:203], v[78:81]
	v_mfma_f32_16x16x32_bf16 v[74:77], v[176:179], v[200:203], v[74:77]
	v_mfma_f32_16x16x32_bf16 v[70:73], v[168:171], v[208:211], v[70:73]
	v_mfma_f32_16x16x32_bf16 v[66:69], v[176:179], v[208:211], v[66:69]
	s_barrier
	s_setprio 0
	s_add_i32 s51, s38, s29
	s_mov_b32 m0, s51
	ds_read_b128 v[180:183], v147 offset:16384
	ds_read_b128 v[184:187], v147 offset:17408
	global_load_lds_dwordx4 v132, s[22:23]
	ds_read_b128 v[188:191], v147 offset:18432
	s_add_i32 m0, s51, 0x2000
	s_add_u32 s52, s22, 0x100000
	s_addc_u32 s53, s23, 0
	s_add_i32 s51, s39, s29
	global_load_lds_dwordx4 v130, s[22:23]
	ds_read_b128 v[192:195], v147 offset:19456
	s_mov_b32 m0, s51
	s_nop 0
	global_load_lds_dwordx4 v132, s[52:53]
	ds_read_b128 v[196:199], v147 offset:20480
	s_add_i32 m0, s51, 0x2000
	s_nop 0
	global_load_lds_dwordx4 v130, s[52:53]
	ds_read_b128 v[200:203], v147 offset:21504
	s_add_u32 s56, s24, s8
	s_addc_u32 s57, s25, s9
	s_mov_b32 m0, s5
	s_nop 0
	global_load_lds_dwordx4 v132, s[24:25]
	ds_read_b128 v[204:207], v147 offset:22528
	s_mov_b32 m0, s7
	s_nop 0
	global_load_lds_dwordx4 v130, s[24:25]
	ds_read_b128 v[208:211], v147 offset:23552
	s_waitcnt vmcnt(8) lgkmcnt(0)
	s_barrier
	s_setprio 1
	v_mfma_f32_16x16x32_bf16 v[62:65], v[148:151], v[180:183], v[62:65]
	v_mfma_f32_16x16x32_bf16 v[58:61], v[156:159], v[180:183], v[58:61]
	v_mfma_f32_16x16x32_bf16 v[54:57], v[148:151], v[188:191], v[54:57]
	v_mfma_f32_16x16x32_bf16 v[50:53], v[156:159], v[188:191], v[50:53]
	v_mfma_f32_16x16x32_bf16 v[38:41], v[148:151], v[196:199], v[38:41]
	v_mfma_f32_16x16x32_bf16 v[34:37], v[156:159], v[196:199], v[34:37]
	v_mfma_f32_16x16x32_bf16 v[22:25], v[148:151], v[204:207], v[22:25]
	v_mfma_f32_16x16x32_bf16 v[18:21], v[156:159], v[204:207], v[18:21]
	v_mfma_f32_16x16x32_bf16 v[62:65], v[152:155], v[184:187], v[62:65]
	v_mfma_f32_16x16x32_bf16 v[58:61], v[160:163], v[184:187], v[58:61]
	v_mfma_f32_16x16x32_bf16 v[54:57], v[152:155], v[192:195], v[54:57]
	v_mfma_f32_16x16x32_bf16 v[50:53], v[160:163], v[192:195], v[50:53]
	v_mfma_f32_16x16x32_bf16 v[38:41], v[152:155], v[200:203], v[38:41]
	v_mfma_f32_16x16x32_bf16 v[34:37], v[160:163], v[200:203], v[34:37]
	v_mfma_f32_16x16x32_bf16 v[22:25], v[152:155], v[208:211], v[22:25]
	v_mfma_f32_16x16x32_bf16 v[18:21], v[160:163], v[208:211], v[18:21]
	v_mfma_f32_16x16x32_bf16 v[46:49], v[164:167], v[180:183], v[46:49]
	v_mfma_f32_16x16x32_bf16 v[42:45], v[172:175], v[180:183], v[42:45]
	v_mfma_f32_16x16x32_bf16 v[30:33], v[164:167], v[188:191], v[30:33]
	v_mfma_f32_16x16x32_bf16 v[26:29], v[172:175], v[188:191], v[26:29]
	v_mfma_f32_16x16x32_bf16 v[14:17], v[164:167], v[196:199], v[14:17]
	v_mfma_f32_16x16x32_bf16 v[10:13], v[172:175], v[196:199], v[10:13]
	v_mfma_f32_16x16x32_bf16 v[6:9], v[164:167], v[204:207], v[6:9]
	v_mfma_f32_16x16x32_bf16 v[2:5], v[172:175], v[204:207], v[2:5]
	v_mfma_f32_16x16x32_bf16 v[46:49], v[168:171], v[184:187], v[46:49]
	v_mfma_f32_16x16x32_bf16 v[42:45], v[176:179], v[184:187], v[42:45]
	v_mfma_f32_16x16x32_bf16 v[30:33], v[168:171], v[192:195], v[30:33]
	v_mfma_f32_16x16x32_bf16 v[26:29], v[176:179], v[192:195], v[26:29]
	v_mfma_f32_16x16x32_bf16 v[14:17], v[168:171], v[200:203], v[14:17]
	v_mfma_f32_16x16x32_bf16 v[10:13], v[176:179], v[200:203], v[10:13]
	v_mfma_f32_16x16x32_bf16 v[6:9], v[168:171], v[208:211], v[6:9]
	v_mfma_f32_16x16x32_bf16 v[2:5], v[176:179], v[208:211], v[2:5]
	s_barrier
; #define PG8_STAGE(bufoff, gbase, voff) do { _Pragma("unroll") for (int _i = 0; _i < 2; ++_i) \
;         __builtin_amdgcn_global_load_lds((const unsigned*)((const char*)(gbase) + (voff)[_i]), (LAS unsigned*)(lds + (bufoff) + ldsw + _i * 8192), 16, 0, 0); } while (0)
; #define PG8_LDA(dst, b, h) do { _Pragma("unroll") for (int m = 0; m < 4; ++m) _Pragma("unroll") for (int k = 0; k < 2; ++k) dst[m][k] = *(const LAS bf16x8*)(lds + PG8_SA(b, h) + aoff + m * 2048 + k * 1024); } while (0)
; #define PG8_LDB(dst, b, h) do { _Pragma("unroll") for (int n = 0; n < 2; ++n) _Pragma("unroll") for (int k = 0; k < 2; ++k) dst[n][k] = *(const LAS bf16x8*)(lds + PG8_SB(b, h) + boff + n * 2048 + k * 1024); } while (0)
; #define PG8_MMA(ai, bj, At, Bt) do { __builtin_amdgcn_s_setprio(1); _Pragma("unroll") for (int m = 0; m < 4; ++m) _Pragma("unroll") for (int n = 0; n < 2; ++n) _Pragma("unroll") for (int k = 0; k < 2; ++k) \
;         acc[ai][bj][m][n] = __builtin_amdgcn_mfma_f32_16x16x32_bf16(Bt[n][k], At[m][k], acc[ai][bj][m][n], 0, 0, 0); __builtin_amdgcn_s_setprio(0); } while (0)
; #define PG8_WAIT_V(n) asm volatile("s_waitcnt vmcnt(" #n ")" ::: "memory")
; #define PG8_WAIT_L(n) asm volatile("s_waitcnt lgkmcnt(" #n ")" ::: "memory")
; #define PG8_BAR __builtin_amdgcn_s_barrier()
; #define PG8_SCHED __builtin_amdgcn_sched_barrier(0)
; template <class Epi, class Sched, bool ALIGN_EPI, class Hook = NoHook>
; __device__ __forceinline__ void gemm_phase(LAS unsigned char* lds, const Gemm g, const Sched& S, const Epi& E, const Hook& H = Hook()) {
;     ...
;             PG8_LDB(B0, 1, 0); PG8_LDB(B1, 1, 1); PG8_SCHED; PG8_LDA(At, 1, 0); PG8_STAGE(PG8_SA(0, 1), a2 + hA, voffA);
;             PG8_WAIT_V(8); PG8_WAIT_L(0); PG8_BAR; PG8_MMA(0, 0, At, B0); PG8_MMA(0, 1, At, B1); PG8_BAR; PG8_SCHED;
;             PG8_LDA(At, 1, 1); PG8_STAGE(PG8_SB(1, 0), b3, voffB); PG8_STAGE(PG8_SB(1, 1), b3 + hB, voffB); PG8_STAGE(PG8_SA(1, 0), a3, voffA);
;             PG8_WAIT_V(8); PG8_WAIT_L(0); PG8_BAR; PG8_MMA(1, 0, At, B0); PG8_MMA(1, 1, At, B1); PG8_BAR; PG8_SCHED;
	s_setprio 0
	s_add_i32 s51, 0, 0x18000
	s_add_i32 s52, 0, 0x1c000
	v_add_u32_e32 v160, s51, v144
	v_add_u32_e32 v176, s52, v144
	ds_read_b128 v[148:151], v160
	ds_read_b128 v[152:155], v160 offset:1024
	s_add_u32 s24, s24, 0x100000
	s_addc_u32 s25, s25, 0
	s_mov_b32 m0, s30
	s_nop 0
	global_load_lds_dwordx4 v132, s[24:25]
	ds_read_b128 v[156:159], v160 offset:2048
	ds_read_b128 v[160:163], v160 offset:3072
	ds_read_b128 v[164:167], v176
	ds_read_b128 v[168:171], v176 offset:1024
	ds_read_b128 v[172:175], v176 offset:2048
	ds_read_b128 v[176:179], v176 offset:3072
	ds_read_b128 v[180:183], v147 offset:32768
	s_mov_b32 m0, s31
	s_nop 0
	global_load_lds_dwordx4 v130, s[24:25]
	ds_read_b128 v[184:187], v147 offset:33792
	ds_read_b128 v[188:191], v147 offset:34816
	ds_read_b128 v[192:195], v147 offset:35840
	ds_read_b128 v[196:199], v147 offset:36864
	ds_read_b128 v[200:203], v147 offset:37888
	ds_read_b128 v[204:207], v147 offset:38912
	ds_read_b128 v[208:211], v147 offset:39936
	s_waitcnt vmcnt(8) lgkmcnt(0)
	s_barrier
	s_setprio 1
	v_mfma_f32_16x16x32_bf16 v[126:129], v[148:151], v[180:183], v[126:129]
	v_mfma_f32_16x16x32_bf16 v[122:125], v[156:159], v[180:183], v[122:125]
	v_mfma_f32_16x16x32_bf16 v[118:121], v[148:151], v[188:191], v[118:121]
	v_mfma_f32_16x16x32_bf16 v[114:117], v[156:159], v[188:191], v[114:117]
	v_mfma_f32_16x16x32_bf16 v[106:109], v[148:151], v[196:199], v[106:109]
	v_mfma_f32_16x16x32_bf16 v[98:101], v[156:159], v[196:199], v[98:101]
	v_mfma_f32_16x16x32_bf16 v[90:93], v[148:151], v[204:207], v[90:93]
	v_mfma_f32_16x16x32_bf16 v[82:85], v[156:159], v[204:207], v[82:85]
	v_mfma_f32_16x16x32_bf16 v[126:129], v[152:155], v[184:187], v[126:129]
	v_mfma_f32_16x16x32_bf16 v[122:125], v[160:163], v[184:187], v[122:125]
	v_mfma_f32_16x16x32_bf16 v[118:121], v[152:155], v[192:195], v[118:121]
	v_mfma_f32_16x16x32_bf16 v[114:117], v[160:163], v[192:195], v[114:117]
	v_mfma_f32_16x16x32_bf16 v[106:109], v[152:155], v[200:203], v[106:109]
	v_mfma_f32_16x16x32_bf16 v[98:101], v[160:163], v[200:203], v[98:101]
	v_mfma_f32_16x16x32_bf16 v[90:93], v[152:155], v[208:211], v[90:93]
	v_mfma_f32_16x16x32_bf16 v[82:85], v[160:163], v[208:211], v[82:85]
	v_mfma_f32_16x16x32_bf16 v[110:113], v[164:167], v[180:183], v[110:113]
	v_mfma_f32_16x16x32_bf16 v[102:105], v[172:175], v[180:183], v[102:105]
	v_mfma_f32_16x16x32_bf16 v[94:97], v[164:167], v[188:191], v[94:97]
	v_mfma_f32_16x16x32_bf16 v[86:89], v[172:175], v[188:191], v[86:89]
	v_mfma_f32_16x16x32_bf16 v[78:81], v[164:167], v[196:199], v[78:81]
	v_mfma_f32_16x16x32_bf16 v[74:77], v[172:175], v[196:199], v[74:77]
	v_mfma_f32_16x16x32_bf16 v[70:73], v[164:167], v[204:207], v[70:73]
	v_mfma_f32_16x16x32_bf16 v[66:69], v[172:175], v[204:207], v[66:69]
	v_mfma_f32_16x16x32_bf16 v[110:113], v[168:171], v[184:187], v[110:113]
	v_mfma_f32_16x16x32_bf16 v[102:105], v[176:179], v[184:187], v[102:105]
	v_mfma_f32_16x16x32_bf16 v[94:97], v[168:171], v[192:195], v[94:97]
	v_mfma_f32_16x16x32_bf16 v[86:89], v[176:179], v[192:195], v[86:89]
	v_mfma_f32_16x16x32_bf16 v[78:81], v[168:171], v[200:203], v[78:81]
	v_mfma_f32_16x16x32_bf16 v[74:77], v[176:179], v[200:203], v[74:77]
	v_mfma_f32_16x16x32_bf16 v[70:73], v[168:171], v[208:211], v[70:73]
	v_mfma_f32_16x16x32_bf16 v[66:69], v[176:179], v[208:211], v[66:69]
	s_barrier
	s_setprio 0
	s_add_i32 s24, s51, s29
	s_add_u32 s54, s22, s8
	s_addc_u32 s55, s23, s9
	s_mov_b32 m0, s24
	ds_read_b128 v[180:183], v147 offset:49152
	ds_read_b128 v[184:187], v147 offset:50176
	global_load_lds_dwordx4 v132, s[54:55]
	ds_read_b128 v[188:191], v147 offset:51200
	s_add_i32 m0, s24, 0x2000
	s_add_u32 s22, s22, 0x100080
	s_addc_u32 s23, s23, 0
	s_add_i32 s24, s52, s29
	global_load_lds_dwordx4 v130, s[54:55]
	ds_read_b128 v[192:195], v147 offset:52224
	s_mov_b32 m0, s24
	s_nop 0
	global_load_lds_dwordx4 v132, s[22:23]
	ds_read_b128 v[196:199], v147 offset:53248
	s_add_i32 m0, s24, 0x2000
	s_nop 0
	global_load_lds_dwordx4 v130, s[22:23]
	ds_read_b128 v[200:203], v147 offset:54272
	s_mov_b32 m0, s35
	s_nop 0
	global_load_lds_dwordx4 v132, s[56:57]
	ds_read_b128 v[204:207], v147 offset:55296
	s_mov_b32 m0, s36
	s_nop 0
	global_load_lds_dwordx4 v130, s[56:57]
	s_add_i32 s50, s50, 2
	s_add_u32 s20, s20, 0x100
	s_addc_u32 s21, s21, 0
	s_add_u32 s42, s42, 0x100
	s_addc_u32 s43, s43, 0
	s_cmp_gt_u32 s50, 5
	ds_read_b128 v[208:211], v147 offset:56320
	s_waitcnt vmcnt(8) lgkmcnt(0)
	s_barrier
; #define PG8_MMA(ai, bj, At, Bt) do { __builtin_amdgcn_s_setprio(1); _Pragma("unroll") for (int m = 0; m < 4; ++m) _Pragma("unroll") for (int n = 0; n < 2; ++n) _Pragma("unroll") for (int k = 0; k < 2; ++k) \
;         acc[ai][bj][m][n] = __builtin_amdgcn_mfma_f32_16x16x32_bf16(Bt[n][k], At[m][k], acc[ai][bj][m][n], 0, 0, 0); __builtin_amdgcn_s_setprio(0); } while (0)
; #define PG8_WAIT_V(n) asm volatile("s_waitcnt vmcnt(" #n ")" ::: "memory")
; #define PG8_WAIT_L(n) asm volatile("s_waitcnt lgkmcnt(" #n ")" ::: "memory")
; #define PG8_BAR __builtin_amdgcn_s_barrier()
; #define PG8_SCHED __builtin_amdgcn_sched_barrier(0)
;     __device__ __forceinline__ void operator()(const f32x4 (&acc)[2][2][4][2], const Unit& u, int wr, int wc, int fr, int fq) const {
;         float* base = C + (size_t)(u.ka / kslab) * slab_stride;
;         const int row0 = u.pm * BM + wr * 64 + fr, col0 = wc * 32 + 4 * fq;
; #pragma unroll
;         for (int ai = 0; ai < 2; ++ai)
; #pragma unroll
;             for (int m = 0; m < 4; ++m) { float* rowp = base + (size_t)(row0 + ai * HALF + m * 16) * 256 + col0;
; #pragma unroll
;                 for (int bj = 0; bj < 2; ++bj)
; #pragma unroll
;                     for (int n = 0; n < 2; ++n) *(f32x4*)(rowp + bj * HALF + n * 16) = acc[ai][bj][m][n]; }
;     }
; template <class Epi, class Sched, bool ALIGN_EPI, class Hook = NoHook>
; __device__ __forceinline__ void gemm_phase(LAS unsigned char* lds, const Gemm g, const Sched& S, const Epi& E, const Hook& H = Hook()) {
;     ...
;             PG8_WAIT_V(8); PG8_WAIT_L(0); PG8_BAR; PG8_MMA(1, 0, At, B0); PG8_MMA(1, 1, At, B1); PG8_BAR; PG8_SCHED;
;         }
;         if constexpr (Hook::ON) H.after(te, acc, cur, wr, wc, fr, fq);
;         }
;         if constexpr (ALIGN_EPI) { if (wr == 0) PG8_BAR; }
;         if constexpr (!Epi::AFTER_DRAIN) { E(acc, cur, wr, wc, fr, fq); S.done(cur); }
;         if (!has_next) break;
	s_setprio 1
	v_mfma_f32_16x16x32_bf16 v[62:65], v[148:151], v[180:183], v[62:65]
	v_mfma_f32_16x16x32_bf16 v[58:61], v[156:159], v[180:183], v[58:61]
	v_mfma_f32_16x16x32_bf16 v[54:57], v[148:151], v[188:191], v[54:57]
	v_mfma_f32_16x16x32_bf16 v[50:53], v[156:159], v[188:191], v[50:53]
	v_mfma_f32_16x16x32_bf16 v[38:41], v[148:151], v[196:199], v[38:41]
	v_mfma_f32_16x16x32_bf16 v[34:37], v[156:159], v[196:199], v[34:37]
	v_mfma_f32_16x16x32_bf16 v[22:25], v[148:151], v[204:207], v[22:25]
	v_mfma_f32_16x16x32_bf16 v[18:21], v[156:159], v[204:207], v[18:21]
	v_mfma_f32_16x16x32_bf16 v[62:65], v[152:155], v[184:187], v[62:65]
	v_mfma_f32_16x16x32_bf16 v[58:61], v[160:163], v[184:187], v[58:61]
	v_mfma_f32_16x16x32_bf16 v[54:57], v[152:155], v[192:195], v[54:57]
	v_mfma_f32_16x16x32_bf16 v[50:53], v[160:163], v[192:195], v[50:53]
	v_mfma_f32_16x16x32_bf16 v[38:41], v[152:155], v[200:203], v[38:41]
	v_mfma_f32_16x16x32_bf16 v[34:37], v[160:163], v[200:203], v[34:37]
	v_mfma_f32_16x16x32_bf16 v[22:25], v[152:155], v[208:211], v[22:25]
	v_mfma_f32_16x16x32_bf16 v[18:21], v[160:163], v[208:211], v[18:21]
	v_mfma_f32_16x16x32_bf16 v[46:49], v[164:167], v[180:183], v[46:49]
	v_mfma_f32_16x16x32_bf16 v[42:45], v[172:175], v[180:183], v[42:45]
	v_mfma_f32_16x16x32_bf16 v[30:33], v[164:167], v[188:191], v[30:33]
	v_mfma_f32_16x16x32_bf16 v[26:29], v[172:175], v[188:191], v[26:29]
	v_mfma_f32_16x16x32_bf16 v[14:17], v[164:167], v[196:199], v[14:17]
	v_mfma_f32_16x16x32_bf16 v[10:13], v[172:175], v[196:199], v[10:13]
	v_mfma_f32_16x16x32_bf16 v[6:9], v[164:167], v[204:207], v[6:9]
	v_mfma_f32_16x16x32_bf16 v[2:5], v[172:175], v[204:207], v[2:5]
	v_mfma_f32_16x16x32_bf16 v[46:49], v[168:171], v[184:187], v[46:49]
	v_mfma_f32_16x16x32_bf16 v[42:45], v[176:179], v[184:187], v[42:45]
	v_mfma_f32_16x16x32_bf16 v[30:33], v[168:171], v[192:195], v[30:33]
	v_mfma_f32_16x16x32_bf16 v[26:29], v[176:179], v[192:195], v[26:29]
	v_mfma_f32_16x16x32_bf16 v[14:17], v[168:171], v[200:203], v[14:17]
	v_mfma_f32_16x16x32_bf16 v[10:13], v[176:179], v[200:203], v[10:13]
	v_mfma_f32_16x16x32_bf16 v[6:9], v[168:171], v[208:211], v[6:9]
	v_mfma_f32_16x16x32_bf16 v[2:5], v[176:179], v[208:211], v[2:5]
	s_barrier
	s_setprio 0
	s_cbranch_scc0 .LBB0_262
	s_ashr_i32 s11, s6, 31
	s_lshr_b32 s11, s11, 23
	s_add_i32 s6, s6, s11
	s_ashr_i32 s20, s6, 9
	s_ashr_i32 s21, s20, 31
	v_lshl_add_u32 v148, s4, 8, v1
	s_lshl_b64 s[20:21], s[20:21], 23
	v_ashrrev_i32_e32 v149, 31, v148
	v_lshl_add_u64 v[150:151], v[134:135], 0, s[20:21]
	v_lshlrev_b64 v[152:153], 10, v[148:149]
	v_lshl_add_u64 v[152:153], v[150:151], 0, v[152:153]
	global_store_dwordx4 v[152:153], v[126:129], off
	global_store_dwordx4 v[152:153], v[122:125], off offset:64
	global_store_dwordx4 v[152:153], v[110:113], off offset:512
	global_store_dwordx4 v[152:153], v[102:105], off offset:576
	s_mov_b32 s4, 0x20000
	s_mov_b64 s[20:21], 0x20000
	v_or_b32_e32 v102, 16, v148
	v_ashrrev_i32_e32 v103, 31, v102
	v_lshlrev_b64 v[102:103], 10, v[102:103]
	v_lshl_add_u64 v[102:103], v[150:151], 0, v[102:103]
	global_store_dwordx4 v[102:103], v[118:121], off
	global_store_dwordx4 v[102:103], v[114:117], off offset:64
	global_store_dwordx4 v[102:103], v[94:97], off offset:512
	global_store_dwordx4 v[102:103], v[86:89], off offset:576
	s_mov_b32 s6, s12
	s_mov_b64 s[22:23], s[18:19]
	v_or_b32_e32 v86, 32, v148
	v_ashrrev_i32_e32 v87, 31, v86
	v_lshlrev_b64 v[86:87], 10, v[86:87]
	v_lshl_add_u64 v[86:87], v[150:151], 0, v[86:87]
	global_store_dwordx4 v[86:87], v[106:109], off
	global_store_dwordx4 v[86:87], v[98:101], off offset:64
	global_store_dwordx4 v[86:87], v[78:81], off offset:512
	global_store_dwordx4 v[86:87], v[74:77], off offset:576
	s_nop 1
	v_or_b32_e32 v74, 48, v148
	v_ashrrev_i32_e32 v75, 31, v74
	v_lshlrev_b64 v[74:75], 10, v[74:75]
	v_lshl_add_u64 v[74:75], v[150:151], 0, v[74:75]
	global_store_dwordx4 v[74:75], v[90:93], off
	global_store_dwordx4 v[74:75], v[82:85], off offset:64
	global_store_dwordx4 v[74:75], v[70:73], off offset:512
	global_store_dwordx4 v[74:75], v[66:69], off offset:576
	s_nop 1
	v_add_co_u32_e32 v68, vcc, s4, v152
	s_mov_b32 s4, 0x24000
	s_nop 0
	v_addc_co_u32_e32 v69, vcc, 0, v153, vcc
	v_lshl_add_u64 v[66:67], v[152:153], 0, s[20:21]
	global_store_dwordx4 v[68:69], v[62:65], off
	global_store_dwordx4 v[66:67], v[58:61], off offset:64
	global_store_dwordx4 v[66:67], v[46:49], off offset:512
	global_store_dwordx4 v[66:67], v[42:45], off offset:576
	s_mov_b64 s[20:21], 0x24000
	s_nop 0
	v_add_co_u32_e32 v44, vcc, s4, v152
	s_mov_b32 s4, 0x28000
	s_nop 0
	v_addc_co_u32_e32 v45, vcc, 0, v153, vcc
	v_lshl_add_u64 v[42:43], v[152:153], 0, s[20:21]
	global_store_dwordx4 v[44:45], v[54:57], off
	global_store_dwordx4 v[42:43], v[50:53], off offset:64
	global_store_dwordx4 v[42:43], v[30:33], off offset:512
	global_store_dwordx4 v[42:43], v[26:29], off offset:576
	s_mov_b64 s[20:21], 0x28000
	s_nop 0
	v_add_co_u32_e32 v28, vcc, s4, v152
	v_lshl_add_u64 v[26:27], v[152:153], 0, s[20:21]
	s_nop 0
	v_addc_co_u32_e32 v29, vcc, 0, v153, vcc
	global_store_dwordx4 v[28:29], v[38:41], off
	global_store_dwordx4 v[26:27], v[34:37], off offset:64
	global_store_dwordx4 v[26:27], v[14:17], off offset:512
	global_store_dwordx4 v[26:27], v[10:13], off offset:576
	s_mov_b64 s[20:21], 0x2c000
	s_mov_b32 s4, s10
	v_add_co_u32_e32 v12, vcc, 0x2c000, v152
	v_lshl_add_u64 v[10:11], v[152:153], 0, s[20:21]
	s_nop 0
	v_addc_co_u32_e32 v13, vcc, 0, v153, vcc
	s_and_b64 vcc, exec, s[2:3]
	s_mov_b64 s[20:21], s[14:15]
	global_store_dwordx4 v[12:13], v[22:25], off
	global_store_dwordx4 v[10:11], v[18:21], off offset:64
	global_store_dwordx4 v[10:11], v[6:9], off offset:512
	global_store_dwordx4 v[10:11], v[2:5], off offset:576
	s_cbranch_vccz .LBB0_259
	s_waitcnt vmcnt(0)
	s_cmpk_gt_u32 s26, 0xff
	s_cbranch_scc1 .LBB0_266
	s_barrier

; #define PG8_STAGE(bufoff, gbase, voff) do { _Pragma("unroll") for (int _i = 0; _i < 2; ++_i) \
;         __builtin_amdgcn_global_load_lds((const unsigned*)((const char*)(gbase) + (voff)[_i]), (LAS unsigned*)(lds + (bufoff) + ldsw + _i * 8192), 16, 0, 0); } while (0)
; #define PG8_LDA(dst, b, h) do { _Pragma("unroll") for (int m = 0; m < 4; ++m) _Pragma("unroll") for (int k = 0; k < 2; ++k) dst[m][k] = *(const LAS bf16x8*)(lds + PG8_SA(b, h) + aoff + m * 2048 + k * 1024); } while (0)
; #define PG8_LDB(dst, b, h) do { _Pragma("unroll") for (int n = 0; n < 2; ++n) _Pragma("unroll") for (int k = 0; k < 2; ++k) dst[n][k] = *(const LAS bf16x8*)(lds + PG8_SB(b, h) + boff + n * 2048 + k * 1024); } while (0)
; #define PG8_MMA(ai, bj, At, Bt) do { __builtin_amdgcn_s_setprio(1); _Pragma("unroll") for (int m = 0; m < 4; ++m) _Pragma("unroll") for (int n = 0; n < 2; ++n) _Pragma("unroll") for (int k = 0; k < 2; ++k) \
;         acc[ai][bj][m][n] = __builtin_amdgcn_mfma_f32_16x16x32_bf16(Bt[n][k], At[m][k], acc[ai][bj][m][n], 0, 0, 0); __builtin_amdgcn_s_setprio(0); } while (0)
; #define PG8_WAIT_V(n) asm volatile("s_waitcnt vmcnt(" #n ")" ::: "memory")
; #define PG8_WAIT_L(n) asm volatile("s_waitcnt lgkmcnt(" #n ")" ::: "memory")
; #define PG8_BAR __builtin_amdgcn_s_barrier()
; #define PG8_SCHED __builtin_amdgcn_sched_barrier(0)
; template <class Epi, class Sched, bool ALIGN_EPI, class Hook = NoHook>
; __device__ __forceinline__ void gemm_phase(LAS unsigned char* lds, const Gemm g, const Sched& S, const Epi& E, const Hook& H = Hook()) {
;     ...
;             const char* a1 = cA + (size_t)(t + 1) * kstep;
;             const char* a2 = last ? nA : cA + (size_t)(t + 2) * kstep; const char* b2 = last ? nB : cB + (size_t)(t + 2) * kstep;
;             const char* a3 = a2 + kstep; const char* b3 = b2 + kstep;
;             if (last && has_next) S.a_ready(nxt);
;             PG8_LDB(B0, 0, 0); PG8_LDB(B1, 0, 1); PG8_SCHED; PG8_LDA(At, 0, 0); PG8_STAGE(PG8_SA(1, 1), a1 + hA, voffA);
;             PG8_WAIT_V(8); PG8_WAIT_L(0); PG8_BAR; PG8_MMA(0, 0, At, B0); PG8_MMA(0, 1, At, B1); PG8_BAR; PG8_SCHED;
;             PG8_LDA(At, 0, 1); PG8_STAGE(PG8_SB(0, 0), b2, voffB); PG8_STAGE(PG8_SB(0, 1), b2 + hB, voffB); PG8_STAGE(PG8_SA(0, 0), a2, voffA);
;             PG8_WAIT_V(8); PG8_WAIT_L(0); PG8_BAR; PG8_MMA(1, 0, At, B0); PG8_MMA(1, 1, At, B1); PG8_BAR; PG8_SCHED;
.LBB0_783:
	v_add_u32_e32 v3, s56, v222
	s_add_i32 s67, s67, 2
	ds_read_b128 v[126:129], v3
	ds_read_b128 v[130:133], v3 offset:1024
	ds_read_b128 v[142:145], v3 offset:2048
	ds_read_b128 v[146:149], v3 offset:3072
	v_add_u32_e32 v3, s57, v222
	s_add_u32 s28, s22, s26
	s_addc_u32 s29, s23, s27
	s_add_u32 s28, s28, 0x100
	s_addc_u32 s29, s29, 0
	s_add_u32 s68, s63, s26
	s_addc_u32 s69, s64, s27
	s_cmpk_eq_i32 s26, 0x5f00
	s_cselect_b32 s31, s5, s29
	s_cselect_b32 s30, s4, s28
	s_cselect_b32 s29, s21, s69
	s_cselect_b32 s28, s20, s68
	ds_read_b128 v[150:153], v3
	ds_read_b128 v[154:157], v3 offset:1024
	ds_read_b128 v[158:161], v3 offset:2048
	ds_read_b128 v[162:165], v3 offset:3072
	v_lshl_add_u64 v[4:5], v[182:183], 0, s[26:27]
	s_add_i32 m0, s37, 0xc000
	s_nop 0
	global_load_lds_dwordx4 v[4:5], off
	ds_read_b128 v[186:189], v224
	ds_read_b128 v[190:193], v224 offset:1024
	ds_read_b128 v[194:197], v224 offset:2048
	ds_read_b128 v[198:201], v224 offset:3072
	ds_read_b128 v[202:205], v224 offset:4096
	ds_read_b128 v[206:209], v224 offset:5120
	ds_read_b128 v[210:213], v224 offset:6144
	ds_read_b128 v[214:217], v224 offset:7168
	v_lshl_add_u64 v[4:5], v[184:185], 0, s[26:27]
	s_add_i32 m0, s37, 0xe000
	s_nop 0
	global_load_lds_dwordx4 v[4:5], off
	s_waitcnt vmcnt(8) lgkmcnt(0)
	s_barrier
	s_setprio 1
	v_mfma_f32_16x16x32_bf16 v[138:141], v[126:129], v[186:189], v[138:141]
	v_mfma_f32_16x16x32_bf16 v[134:137], v[142:145], v[186:189], v[134:137]
	v_mfma_f32_16x16x32_bf16 v[122:125], v[126:129], v[194:197], v[122:125]
	v_mfma_f32_16x16x32_bf16 v[118:121], v[142:145], v[194:197], v[118:121]
	v_mfma_f32_16x16x32_bf16 v[114:117], v[126:129], v[202:205], v[114:117]
	v_mfma_f32_16x16x32_bf16 v[110:113], v[142:145], v[202:205], v[110:113]
	v_mfma_f32_16x16x32_bf16 v[106:109], v[126:129], v[210:213], v[106:109]
	v_mfma_f32_16x16x32_bf16 v[102:105], v[142:145], v[210:213], v[102:105]
	v_mfma_f32_16x16x32_bf16 v[138:141], v[130:133], v[190:193], v[138:141]
	v_mfma_f32_16x16x32_bf16 v[134:137], v[146:149], v[190:193], v[134:137]
	v_mfma_f32_16x16x32_bf16 v[122:125], v[130:133], v[198:201], v[122:125]
	v_mfma_f32_16x16x32_bf16 v[118:121], v[146:149], v[198:201], v[118:121]
	v_mfma_f32_16x16x32_bf16 v[114:117], v[130:133], v[206:209], v[114:117]
	v_mfma_f32_16x16x32_bf16 v[110:113], v[146:149], v[206:209], v[110:113]
	v_mfma_f32_16x16x32_bf16 v[106:109], v[130:133], v[214:217], v[106:109]
	v_mfma_f32_16x16x32_bf16 v[102:105], v[146:149], v[214:217], v[102:105]
	v_mfma_f32_16x16x32_bf16 v[66:69], v[150:153], v[186:189], v[66:69]
	v_mfma_f32_16x16x32_bf16 v[62:65], v[158:161], v[186:189], v[62:65]
	v_mfma_f32_16x16x32_bf16 v[58:61], v[150:153], v[194:197], v[58:61]
	v_mfma_f32_16x16x32_bf16 v[54:57], v[158:161], v[194:197], v[54:57]
	v_mfma_f32_16x16x32_bf16 v[50:53], v[150:153], v[202:205], v[50:53]
	v_mfma_f32_16x16x32_bf16 v[46:49], v[158:161], v[202:205], v[46:49]
	v_mfma_f32_16x16x32_bf16 v[42:45], v[150:153], v[210:213], v[42:45]
	v_mfma_f32_16x16x32_bf16 v[38:41], v[158:161], v[210:213], v[38:41]
	v_mfma_f32_16x16x32_bf16 v[66:69], v[154:157], v[190:193], v[66:69]
	v_mfma_f32_16x16x32_bf16 v[62:65], v[162:165], v[190:193], v[62:65]
	v_mfma_f32_16x16x32_bf16 v[58:61], v[154:157], v[198:201], v[58:61]
	v_mfma_f32_16x16x32_bf16 v[54:57], v[162:165], v[198:201], v[54:57]
	v_mfma_f32_16x16x32_bf16 v[50:53], v[154:157], v[206:209], v[50:53]
	v_mfma_f32_16x16x32_bf16 v[46:49], v[162:165], v[206:209], v[46:49]
	v_mfma_f32_16x16x32_bf16 v[42:45], v[154:157], v[214:217], v[42:45]
	v_mfma_f32_16x16x32_bf16 v[38:41], v[162:165], v[214:217], v[38:41]
	s_barrier
	s_setprio 0
	s_add_i32 s68, s56, s35
	s_mov_b32 m0, s68
	ds_read_b128 v[186:189], v224 offset:16384
	ds_read_b128 v[190:193], v224 offset:17408
	global_load_lds_dwordx4 v168, s[28:29]
	ds_read_b128 v[194:197], v224 offset:18432
	s_add_i32 m0, s68, 0x2000
	s_add_u32 s68, s28, 0x300000
	s_addc_u32 s69, s29, 0
	s_add_i32 s70, s57, s35
	global_load_lds_dwordx4 v172, s[28:29]
	ds_read_b128 v[198:201], v224 offset:19456
	s_mov_b32 m0, s70
	s_add_u32 s74, s30, s14
	s_addc_u32 s75, s31, s15
	global_load_lds_dwordx4 v168, s[68:69]
	ds_read_b128 v[202:205], v224 offset:20480
	s_add_i32 m0, s70, 0x2000
	s_nop 0
	global_load_lds_dwordx4 v172, s[68:69]
	ds_read_b128 v[206:209], v224 offset:21504
	s_mov_b32 m0, s37
	s_nop 0
	global_load_lds_dwordx4 v166, s[30:31]
	ds_read_b128 v[210:213], v224 offset:22528
	s_mov_b32 m0, s38
	s_nop 0
	global_load_lds_dwordx4 v170, s[30:31]
	ds_read_b128 v[214:217], v224 offset:23552
	s_waitcnt vmcnt(8) lgkmcnt(0)
	s_barrier
; #define PG8_STAGE(bufoff, gbase, voff) do { _Pragma("unroll") for (int _i = 0; _i < 2; ++_i) \
;         __builtin_amdgcn_global_load_lds((const unsigned*)((const char*)(gbase) + (voff)[_i]), (LAS unsigned*)(lds + (bufoff) + ldsw + _i * 8192), 16, 0, 0); } while (0)
; #define PG8_LDA(dst, b, h) do { _Pragma("unroll") for (int m = 0; m < 4; ++m) _Pragma("unroll") for (int k = 0; k < 2; ++k) dst[m][k] = *(const LAS bf16x8*)(lds + PG8_SA(b, h) + aoff + m * 2048 + k * 1024); } while (0)
; #define PG8_LDB(dst, b, h) do { _Pragma("unroll") for (int n = 0; n < 2; ++n) _Pragma("unroll") for (int k = 0; k < 2; ++k) dst[n][k] = *(const LAS bf16x8*)(lds + PG8_SB(b, h) + boff + n * 2048 + k * 1024); } while (0)
; #define PG8_MMA(ai, bj, At, Bt) do { __builtin_amdgcn_s_setprio(1); _Pragma("unroll") for (int m = 0; m < 4; ++m) _Pragma("unroll") for (int n = 0; n < 2; ++n) _Pragma("unroll") for (int k = 0; k < 2; ++k) \
;         acc[ai][bj][m][n] = __builtin_amdgcn_mfma_f32_16x16x32_bf16(Bt[n][k], At[m][k], acc[ai][bj][m][n], 0, 0, 0); __builtin_amdgcn_s_setprio(0); } while (0)
; #define PG8_WAIT_V(n) asm volatile("s_waitcnt vmcnt(" #n ")" ::: "memory")
; #define PG8_WAIT_L(n) asm volatile("s_waitcnt lgkmcnt(" #n ")" ::: "memory")
; #define PG8_BAR __builtin_amdgcn_s_barrier()
; #define PG8_SCHED __builtin_amdgcn_sched_barrier(0)
; template <class Epi, class Sched, bool ALIGN_EPI, class Hook = NoHook>
; __device__ __forceinline__ void gemm_phase(LAS unsigned char* lds, const Gemm g, const Sched& S, const Epi& E, const Hook& H = Hook()) {
;     ...
;             PG8_WAIT_V(8); PG8_WAIT_L(0); PG8_BAR; PG8_MMA(1, 0, At, B0); PG8_MMA(1, 1, At, B1); PG8_BAR; PG8_SCHED;
;             PG8_LDB(B0, 1, 0); PG8_LDB(B1, 1, 1); PG8_SCHED; PG8_LDA(At, 1, 0); PG8_STAGE(PG8_SA(0, 1), a2 + hA, voffA);
;             PG8_WAIT_V(8); PG8_WAIT_L(0); PG8_BAR; PG8_MMA(0, 0, At, B0); PG8_MMA(0, 1, At, B1); PG8_BAR; PG8_SCHED;
	s_setprio 1
	v_mfma_f32_16x16x32_bf16 v[98:101], v[126:129], v[186:189], v[98:101]
	v_mfma_f32_16x16x32_bf16 v[94:97], v[142:145], v[186:189], v[94:97]
	v_mfma_f32_16x16x32_bf16 v[90:93], v[126:129], v[194:197], v[90:93]
	v_mfma_f32_16x16x32_bf16 v[86:89], v[142:145], v[194:197], v[86:89]
	v_mfma_f32_16x16x32_bf16 v[82:85], v[126:129], v[202:205], v[82:85]
	v_mfma_f32_16x16x32_bf16 v[78:81], v[142:145], v[202:205], v[78:81]
	v_mfma_f32_16x16x32_bf16 v[74:77], v[126:129], v[210:213], v[74:77]
	v_mfma_f32_16x16x32_bf16 v[70:73], v[142:145], v[210:213], v[70:73]
	v_mfma_f32_16x16x32_bf16 v[98:101], v[130:133], v[190:193], v[98:101]
	v_mfma_f32_16x16x32_bf16 v[94:97], v[146:149], v[190:193], v[94:97]
	v_mfma_f32_16x16x32_bf16 v[90:93], v[130:133], v[198:201], v[90:93]
	v_mfma_f32_16x16x32_bf16 v[86:89], v[146:149], v[198:201], v[86:89]
	v_mfma_f32_16x16x32_bf16 v[82:85], v[130:133], v[206:209], v[82:85]
	v_mfma_f32_16x16x32_bf16 v[78:81], v[146:149], v[206:209], v[78:81]
	v_mfma_f32_16x16x32_bf16 v[74:77], v[130:133], v[214:217], v[74:77]
	v_mfma_f32_16x16x32_bf16 v[70:73], v[146:149], v[214:217], v[70:73]
	v_mfma_f32_16x16x32_bf16 v[34:37], v[150:153], v[186:189], v[34:37]
	v_mfma_f32_16x16x32_bf16 v[30:33], v[158:161], v[186:189], v[30:33]
	v_mfma_f32_16x16x32_bf16 v[26:29], v[150:153], v[194:197], v[26:29]
	v_mfma_f32_16x16x32_bf16 v[22:25], v[158:161], v[194:197], v[22:25]
	v_mfma_f32_16x16x32_bf16 v[18:21], v[150:153], v[202:205], v[18:21]
	v_mfma_f32_16x16x32_bf16 v[14:17], v[158:161], v[202:205], v[14:17]
	v_mfma_f32_16x16x32_bf16 v[10:13], v[150:153], v[210:213], v[10:13]
	v_mfma_f32_16x16x32_bf16 v[4:7], v[158:161], v[210:213], v[6:9]
	v_mfma_f32_16x16x32_bf16 v[34:37], v[154:157], v[190:193], v[34:37]
	v_mfma_f32_16x16x32_bf16 v[30:33], v[162:165], v[190:193], v[30:33]
	v_mfma_f32_16x16x32_bf16 v[26:29], v[154:157], v[198:201], v[26:29]
	v_mfma_f32_16x16x32_bf16 v[22:25], v[162:165], v[198:201], v[22:25]
	v_mfma_f32_16x16x32_bf16 v[18:21], v[154:157], v[206:209], v[18:21]
	v_mfma_f32_16x16x32_bf16 v[14:17], v[162:165], v[206:209], v[14:17]
	v_mfma_f32_16x16x32_bf16 v[10:13], v[154:157], v[214:217], v[10:13]
	v_mfma_f32_16x16x32_bf16 v[4:7], v[162:165], v[214:217], v[4:7]
	s_barrier
	s_setprio 0
	s_add_i32 s68, 0, 0x18000
	v_add_u32_e32 v3, s68, v222
	s_add_i32 s69, 0, 0x1c000
	ds_read_b128 v[126:129], v3
	ds_read_b128 v[130:133], v3 offset:1024
	ds_read_b128 v[142:145], v3 offset:2048
	ds_read_b128 v[146:149], v3 offset:3072
	v_add_u32_e32 v3, s69, v222
	s_add_u32 s30, s30, 0x300000
	s_addc_u32 s31, s31, 0
	s_mov_b32 m0, s39
	s_nop 0
	global_load_lds_dwordx4 v166, s[30:31]
	ds_read_b128 v[150:153], v3
	ds_read_b128 v[154:157], v3 offset:1024
	ds_read_b128 v[158:161], v3 offset:2048
	ds_read_b128 v[162:165], v3 offset:3072
	ds_read_b128 v[186:189], v224 offset:32768
	ds_read_b128 v[190:193], v224 offset:33792
	ds_read_b128 v[194:197], v224 offset:34816
	s_mov_b32 m0, s40
	s_nop 0
	global_load_lds_dwordx4 v170, s[30:31]
	ds_read_b128 v[198:201], v224 offset:35840
	ds_read_b128 v[202:205], v224 offset:36864
	ds_read_b128 v[206:209], v224 offset:37888
	ds_read_b128 v[210:213], v224 offset:38912
	ds_read_b128 v[214:217], v224 offset:39936
	s_waitcnt vmcnt(8) lgkmcnt(0)
	s_barrier
	s_setprio 1
	v_mfma_f32_16x16x32_bf16 v[138:141], v[126:129], v[186:189], v[138:141]
	v_mfma_f32_16x16x32_bf16 v[134:137], v[142:145], v[186:189], v[134:137]
	v_mfma_f32_16x16x32_bf16 v[122:125], v[126:129], v[194:197], v[122:125]
	v_mfma_f32_16x16x32_bf16 v[118:121], v[142:145], v[194:197], v[118:121]
	v_mfma_f32_16x16x32_bf16 v[114:117], v[126:129], v[202:205], v[114:117]
	v_mfma_f32_16x16x32_bf16 v[110:113], v[142:145], v[202:205], v[110:113]
	v_mfma_f32_16x16x32_bf16 v[106:109], v[126:129], v[210:213], v[106:109]
	v_mfma_f32_16x16x32_bf16 v[102:105], v[142:145], v[210:213], v[102:105]
	v_mfma_f32_16x16x32_bf16 v[138:141], v[130:133], v[190:193], v[138:141]
	v_mfma_f32_16x16x32_bf16 v[134:137], v[146:149], v[190:193], v[134:137]
	v_mfma_f32_16x16x32_bf16 v[122:125], v[130:133], v[198:201], v[122:125]
	v_mfma_f32_16x16x32_bf16 v[118:121], v[146:149], v[198:201], v[118:121]
	v_mfma_f32_16x16x32_bf16 v[114:117], v[130:133], v[206:209], v[114:117]
	v_mfma_f32_16x16x32_bf16 v[110:113], v[146:149], v[206:209], v[110:113]
	v_mfma_f32_16x16x32_bf16 v[106:109], v[130:133], v[214:217], v[106:109]
	v_mfma_f32_16x16x32_bf16 v[102:105], v[146:149], v[214:217], v[102:105]
	v_mfma_f32_16x16x32_bf16 v[66:69], v[150:153], v[186:189], v[66:69]
	v_mfma_f32_16x16x32_bf16 v[62:65], v[158:161], v[186:189], v[62:65]
	v_mfma_f32_16x16x32_bf16 v[58:61], v[150:153], v[194:197], v[58:61]
	v_mfma_f32_16x16x32_bf16 v[54:57], v[158:161], v[194:197], v[54:57]
	v_mfma_f32_16x16x32_bf16 v[50:53], v[150:153], v[202:205], v[50:53]
	v_mfma_f32_16x16x32_bf16 v[46:49], v[158:161], v[202:205], v[46:49]
	v_mfma_f32_16x16x32_bf16 v[42:45], v[150:153], v[210:213], v[42:45]
	v_mfma_f32_16x16x32_bf16 v[38:41], v[158:161], v[210:213], v[38:41]
	v_mfma_f32_16x16x32_bf16 v[66:69], v[154:157], v[190:193], v[66:69]
	v_mfma_f32_16x16x32_bf16 v[62:65], v[162:165], v[190:193], v[62:65]
	v_mfma_f32_16x16x32_bf16 v[58:61], v[154:157], v[198:201], v[58:61]
	v_mfma_f32_16x16x32_bf16 v[54:57], v[162:165], v[198:201], v[54:57]
	v_mfma_f32_16x16x32_bf16 v[50:53], v[154:157], v[206:209], v[50:53]
	v_mfma_f32_16x16x32_bf16 v[46:49], v[162:165], v[206:209], v[46:49]
	v_mfma_f32_16x16x32_bf16 v[42:45], v[154:157], v[214:217], v[42:45]
	v_mfma_f32_16x16x32_bf16 v[38:41], v[162:165], v[214:217], v[38:41]
	s_barrier
; #define PG8_STAGE(bufoff, gbase, voff) do { _Pragma("unroll") for (int _i = 0; _i < 2; ++_i) \
;         __builtin_amdgcn_global_load_lds((const unsigned*)((const char*)(gbase) + (voff)[_i]), (LAS unsigned*)(lds + (bufoff) + ldsw + _i * 8192), 16, 0, 0); } while (0)
; #define PG8_LDA(dst, b, h) do { _Pragma("unroll") for (int m = 0; m < 4; ++m) _Pragma("unroll") for (int k = 0; k < 2; ++k) dst[m][k] = *(const LAS bf16x8*)(lds + PG8_SA(b, h) + aoff + m * 2048 + k * 1024); } while (0)
; #define PG8_MMA(ai, bj, At, Bt) do { __builtin_amdgcn_s_setprio(1); _Pragma("unroll") for (int m = 0; m < 4; ++m) _Pragma("unroll") for (int n = 0; n < 2; ++n) _Pragma("unroll") for (int k = 0; k < 2; ++k) \
;         acc[ai][bj][m][n] = __builtin_amdgcn_mfma_f32_16x16x32_bf16(Bt[n][k], At[m][k], acc[ai][bj][m][n], 0, 0, 0); __builtin_amdgcn_s_setprio(0); } while (0)
; #define PG8_WAIT_V(n) asm volatile("s_waitcnt vmcnt(" #n ")" ::: "memory")
; #define PG8_WAIT_L(n) asm volatile("s_waitcnt lgkmcnt(" #n ")" ::: "memory")
; #define PG8_BAR __builtin_amdgcn_s_barrier()
; #define PG8_SCHED __builtin_amdgcn_sched_barrier(0)
;     __device__ __forceinline__ void after(int te, f32x4 (&acc)[2][2][4][2], const Unit& u, int wr, int wc, int fr, int fq) const {
;         if (te > D_INNER / BK) return;
;         const int g = (te >> 4) - 1;
;         asm volatile("" : "+v"(fr), "+v"(fq));
; #pragma unroll
;         for (int ai = 0; ai < 2; ++ai)
; #pragma unroll
;             for (int m = 0; m < 4; ++m) { const float f = tab[(ai * HALF + wr * 64 + m * 16 + fr) * 8 + g];
; #pragma unroll
;                 for (int bj = 0; bj < 2; ++bj)
; #pragma unroll
;                     for (int n = 0; n < 2; ++n) acc[ai][bj][m][n] *= f; }
; template <class Epi, class Sched, bool ALIGN_EPI, class Hook = NoHook>
; __device__ __forceinline__ void gemm_phase(LAS unsigned char* lds, const Gemm g, const Sched& S, const Epi& E, const Hook& H = Hook()) {
;     ...
;             PG8_LDA(At, 1, 1); PG8_STAGE(PG8_SB(1, 0), b3, voffB); PG8_STAGE(PG8_SB(1, 1), b3 + hB, voffB); PG8_STAGE(PG8_SA(1, 0), a3, voffA);
;             PG8_WAIT_V(8); PG8_WAIT_L(0); PG8_BAR; PG8_MMA(1, 0, At, B0); PG8_MMA(1, 1, At, B1); PG8_BAR; PG8_SCHED;
;         }
;         if constexpr (Hook::ON) H.after(te, acc, cur, wr, wc, fr, fq);
	s_setprio 0
	s_add_i32 s30, s68, s35
	s_add_u32 s72, s28, s14
	s_addc_u32 s73, s29, s15
	s_mov_b32 m0, s30
	ds_read_b128 v[186:189], v224 offset:49152
	ds_read_b128 v[190:193], v224 offset:50176
	global_load_lds_dwordx4 v168, s[72:73]
	ds_read_b128 v[194:197], v224 offset:51200
	s_add_i32 m0, s30, 0x2000
	s_add_u32 s28, s28, 0x300080
	s_addc_u32 s29, s29, 0
	s_add_i32 s30, s69, s35
	global_load_lds_dwordx4 v172, s[72:73]
	ds_read_b128 v[198:201], v224 offset:52224
	s_mov_b32 m0, s30
	s_nop 0
	global_load_lds_dwordx4 v168, s[28:29]
	ds_read_b128 v[202:205], v224 offset:53248
	s_add_i32 m0, s30, 0x2000
	s_nop 0
	global_load_lds_dwordx4 v172, s[28:29]
	ds_read_b128 v[206:209], v224 offset:54272
	s_mov_b32 m0, s45
	s_nop 0
	global_load_lds_dwordx4 v166, s[74:75]
	ds_read_b128 v[210:213], v224 offset:55296
	s_mov_b32 m0, s46
	s_nop 0
	global_load_lds_dwordx4 v170, s[74:75]
	s_add_u32 s26, s26, 0x100
	s_addc_u32 s27, s27, 0
	s_cmp_ge_u32 s67, s66
	ds_read_b128 v[214:217], v224 offset:56320
	s_waitcnt vmcnt(8) lgkmcnt(0)
	s_barrier
	s_setprio 1
	v_mfma_f32_16x16x32_bf16 v[98:101], v[126:129], v[186:189], v[98:101]
	v_mfma_f32_16x16x32_bf16 v[94:97], v[142:145], v[186:189], v[94:97]
	v_mfma_f32_16x16x32_bf16 v[90:93], v[126:129], v[194:197], v[90:93]
	v_mfma_f32_16x16x32_bf16 v[86:89], v[142:145], v[194:197], v[86:89]
	v_mfma_f32_16x16x32_bf16 v[82:85], v[126:129], v[202:205], v[82:85]
	v_mfma_f32_16x16x32_bf16 v[78:81], v[142:145], v[202:205], v[78:81]
	v_mfma_f32_16x16x32_bf16 v[74:77], v[126:129], v[210:213], v[74:77]
	v_mfma_f32_16x16x32_bf16 v[70:73], v[142:145], v[210:213], v[70:73]
	v_mfma_f32_16x16x32_bf16 v[98:101], v[130:133], v[190:193], v[98:101]
	v_mfma_f32_16x16x32_bf16 v[94:97], v[146:149], v[190:193], v[94:97]
	v_mfma_f32_16x16x32_bf16 v[90:93], v[130:133], v[198:201], v[90:93]
	v_mfma_f32_16x16x32_bf16 v[86:89], v[146:149], v[198:201], v[86:89]
	v_mfma_f32_16x16x32_bf16 v[82:85], v[130:133], v[206:209], v[82:85]
	v_mfma_f32_16x16x32_bf16 v[78:81], v[146:149], v[206:209], v[78:81]
	v_mfma_f32_16x16x32_bf16 v[74:77], v[130:133], v[214:217], v[74:77]
	v_mfma_f32_16x16x32_bf16 v[70:73], v[146:149], v[214:217], v[70:73]
	v_mfma_f32_16x16x32_bf16 v[34:37], v[150:153], v[186:189], v[34:37]
	v_mfma_f32_16x16x32_bf16 v[30:33], v[158:161], v[186:189], v[30:33]
	v_mfma_f32_16x16x32_bf16 v[26:29], v[150:153], v[194:197], v[26:29]
	v_mfma_f32_16x16x32_bf16 v[22:25], v[158:161], v[194:197], v[22:25]
	v_mfma_f32_16x16x32_bf16 v[18:21], v[150:153], v[202:205], v[18:21]
	v_mfma_f32_16x16x32_bf16 v[14:17], v[158:161], v[202:205], v[14:17]
	v_mfma_f32_16x16x32_bf16 v[8:11], v[150:153], v[210:213], v[10:13]
	v_mfma_f32_16x16x32_bf16 v[4:7], v[158:161], v[210:213], v[4:7]
	v_mfma_f32_16x16x32_bf16 v[34:37], v[154:157], v[190:193], v[34:37]
	v_mfma_f32_16x16x32_bf16 v[30:33], v[162:165], v[190:193], v[30:33]
	v_mfma_f32_16x16x32_bf16 v[26:29], v[154:157], v[198:201], v[26:29]
	v_mfma_f32_16x16x32_bf16 v[22:25], v[162:165], v[198:201], v[22:25]
	v_mfma_f32_16x16x32_bf16 v[18:21], v[154:157], v[206:209], v[18:21]
	v_mfma_f32_16x16x32_bf16 v[14:17], v[162:165], v[206:209], v[14:17]
	v_mfma_f32_16x16x32_bf16 v[10:13], v[154:157], v[214:217], v[8:11]
	v_mfma_f32_16x16x32_bf16 v[6:9], v[162:165], v[214:217], v[4:7]
	s_barrier
	s_setprio 0
	s_cbranch_scc0 .LBB0_783
	s_cmpk_gt_u32 s65, 0x7f
	s_cbranch_scc1 .LBB0_787
	s_lshr_b32 s26, s66, 4
	s_add_i32 s26, s26, -1
	v_mov_b32_e32 v3, v1
	v_mov_b32_e32 v4, v220
	s_lshl_b32 s27, s26, 2
	s_add_i32 s28, s27, s48
	v_lshlrev_b32_e32 v5, 5, v3
	v_add_u32_e32 v126, s28, v5
	ds_read_b32 v126, v126
	s_add_i32 s28, s27, s49
	s_waitcnt lgkmcnt(0)
	v_pk_mul_f32 v[140:141], v[140:141], v[126:127] op_sel_hi:[1,0]
	v_pk_mul_f32 v[138:139], v[138:139], v[126:127] op_sel_hi:[1,0]
	v_pk_mul_f32 v[136:137], v[136:137], v[126:127] op_sel_hi:[1,0]
	v_pk_mul_f32 v[134:135], v[134:135], v[126:127] op_sel_hi:[1,0]
	v_pk_mul_f32 v[68:69], v[68:69], v[126:127] op_sel_hi:[1,0]
	v_pk_mul_f32 v[66:67], v[66:67], v[126:127] op_sel_hi:[1,0]
	v_pk_mul_f32 v[64:65], v[64:65], v[126:127] op_sel_hi:[1,0]
	v_pk_mul_f32 v[62:63], v[62:63], v[126:127] op_sel_hi:[1,0]
	v_add_u32_e32 v126, s28, v5
	ds_read_b32 v126, v126
	s_add_i32 s28, s27, s50
	s_waitcnt lgkmcnt(0)
	v_pk_mul_f32 v[124:125], v[124:125], v[126:127] op_sel_hi:[1,0]
	v_pk_mul_f32 v[122:123], v[122:123], v[126:127] op_sel_hi:[1,0]
	v_pk_mul_f32 v[120:121], v[120:121], v[126:127] op_sel_hi:[1,0]
	v_pk_mul_f32 v[118:119], v[118:119], v[126:127] op_sel_hi:[1,0]
	v_pk_mul_f32 v[60:61], v[60:61], v[126:127] op_sel_hi:[1,0]
	v_pk_mul_f32 v[58:59], v[58:59], v[126:127] op_sel_hi:[1,0]
	v_pk_mul_f32 v[56:57], v[56:57], v[126:127] op_sel_hi:[1,0]
	v_pk_mul_f32 v[54:55], v[54:55], v[126:127] op_sel_hi:[1,0]
	v_add_u32_e32 v126, s28, v5
	ds_read_b32 v126, v126
	s_add_i32 s28, s27, s51
	s_waitcnt lgkmcnt(0)
	v_pk_mul_f32 v[116:117], v[116:117], v[126:127] op_sel_hi:[1,0]
	v_pk_mul_f32 v[114:115], v[114:115], v[126:127] op_sel_hi:[1,0]
	v_pk_mul_f32 v[112:113], v[112:113], v[126:127] op_sel_hi:[1,0]
	v_pk_mul_f32 v[110:111], v[110:111], v[126:127] op_sel_hi:[1,0]
	v_pk_mul_f32 v[52:53], v[52:53], v[126:127] op_sel_hi:[1,0]
	v_pk_mul_f32 v[50:51], v[50:51], v[126:127] op_sel_hi:[1,0]
	v_pk_mul_f32 v[48:49], v[48:49], v[126:127] op_sel_hi:[1,0]
	v_pk_mul_f32 v[46:47], v[46:47], v[126:127] op_sel_hi:[1,0]
	v_add_u32_e32 v126, s28, v5
	ds_read_b32 v126, v126
	s_add_i32 s28, s27, s52
	s_waitcnt lgkmcnt(0)
;     __device__ __forceinline__ void after(int te, f32x4 (&acc)[2][2][4][2], const Unit& u, int wr, int wc, int fr, int fq) const {
;     ...
; #pragma unroll
;         for (int ai = 0; ai < 2; ++ai)
; #pragma unroll
;             for (int m = 0; m < 4; ++m) { const float f = tab[(ai * HALF + wr * 64 + m * 16 + fr) * 8 + g];
; #pragma unroll
;                 for (int bj = 0; bj < 2; ++bj)
; #pragma unroll
;                     for (int n = 0; n < 2; ++n) acc[ai][bj][m][n] *= f; }
;         if (g == 7) {
;             const int row0 = u.pm * BM + wr * 64 + fr, col0 = u.pn * BM + wc * 32 + 8 * fq;
; #pragma unroll
;             for (int bj = 0; bj < 2; ++bj) { const int c = col0 + bj * HALF;
;                 const f32x4 s0 = *(const f32x4*)(gb + c), s1 = *(const f32x4*)(gb + c + 4), a0 = *(const f32x4*)(gb + D_MODEL + c), a1 = *(const f32x4*)(gb + D_MODEL + c + 4);
; #pragma unroll
;                 for (int ai = 0; ai < 2; ++ai) {
;                     u32x4 gs[4], ga[4];
; #pragma unroll
;                     for (int m = 0; m < 4; ++m) { const size_t r = (size_t)(row0 + ai * HALF + m * 16); gs[m] = *(const u32x4*)(proj + r * LDP + PGS + c); ga[m] = *(const u32x4*)(proj + r * LDP + PGA + c); }
	v_pk_mul_f32 v[108:109], v[108:109], v[126:127] op_sel_hi:[1,0]
	v_pk_mul_f32 v[106:107], v[106:107], v[126:127] op_sel_hi:[1,0]
	v_pk_mul_f32 v[104:105], v[104:105], v[126:127] op_sel_hi:[1,0]
	v_pk_mul_f32 v[102:103], v[102:103], v[126:127] op_sel_hi:[1,0]
	v_pk_mul_f32 v[44:45], v[44:45], v[126:127] op_sel_hi:[1,0]
	v_pk_mul_f32 v[42:43], v[42:43], v[126:127] op_sel_hi:[1,0]
	v_pk_mul_f32 v[40:41], v[40:41], v[126:127] op_sel_hi:[1,0]
	v_pk_mul_f32 v[38:39], v[38:39], v[126:127] op_sel_hi:[1,0]
	v_add_u32_e32 v126, s28, v5
	ds_read_b32 v126, v126
	s_add_i32 s28, s27, s53
	s_waitcnt lgkmcnt(0)
	v_pk_mul_f32 v[100:101], v[100:101], v[126:127] op_sel_hi:[1,0]
	v_pk_mul_f32 v[98:99], v[98:99], v[126:127] op_sel_hi:[1,0]
	v_pk_mul_f32 v[96:97], v[96:97], v[126:127] op_sel_hi:[1,0]
	v_pk_mul_f32 v[94:95], v[94:95], v[126:127] op_sel_hi:[1,0]
	v_pk_mul_f32 v[36:37], v[36:37], v[126:127] op_sel_hi:[1,0]
	v_pk_mul_f32 v[34:35], v[34:35], v[126:127] op_sel_hi:[1,0]
	v_pk_mul_f32 v[32:33], v[32:33], v[126:127] op_sel_hi:[1,0]
	v_pk_mul_f32 v[30:31], v[30:31], v[126:127] op_sel_hi:[1,0]
	v_add_u32_e32 v126, s28, v5
	ds_read_b32 v126, v126
	s_add_i32 s28, s27, s54
	s_add_i32 s27, s27, s55
	s_cmp_lg_u32 s26, 7
	s_waitcnt lgkmcnt(0)
	v_pk_mul_f32 v[92:93], v[92:93], v[126:127] op_sel_hi:[1,0]
	v_pk_mul_f32 v[90:91], v[90:91], v[126:127] op_sel_hi:[1,0]
	v_pk_mul_f32 v[88:89], v[88:89], v[126:127] op_sel_hi:[1,0]
	v_pk_mul_f32 v[86:87], v[86:87], v[126:127] op_sel_hi:[1,0]
	v_pk_mul_f32 v[28:29], v[28:29], v[126:127] op_sel_hi:[1,0]
	v_pk_mul_f32 v[26:27], v[26:27], v[126:127] op_sel_hi:[1,0]
	v_pk_mul_f32 v[24:25], v[24:25], v[126:127] op_sel_hi:[1,0]
	v_pk_mul_f32 v[22:23], v[22:23], v[126:127] op_sel_hi:[1,0]
	v_add_u32_e32 v126, s28, v5
	ds_read_b32 v126, v126
	v_add_u32_e32 v5, s27, v5
	s_waitcnt lgkmcnt(0)
	v_pk_mul_f32 v[84:85], v[84:85], v[126:127] op_sel_hi:[1,0]
	v_pk_mul_f32 v[82:83], v[82:83], v[126:127] op_sel_hi:[1,0]
	v_pk_mul_f32 v[80:81], v[80:81], v[126:127] op_sel_hi:[1,0]
	v_pk_mul_f32 v[78:79], v[78:79], v[126:127] op_sel_hi:[1,0]
	v_pk_mul_f32 v[20:21], v[20:21], v[126:127] op_sel_hi:[1,0]
	v_pk_mul_f32 v[18:19], v[18:19], v[126:127] op_sel_hi:[1,0]
	v_pk_mul_f32 v[16:17], v[16:17], v[126:127] op_sel_hi:[1,0]
	v_pk_mul_f32 v[14:15], v[14:15], v[126:127] op_sel_hi:[1,0]
	ds_read_b32 v126, v5
	s_waitcnt lgkmcnt(0)
	v_pk_mul_f32 v[76:77], v[76:77], v[126:127] op_sel_hi:[1,0]
	v_pk_mul_f32 v[74:75], v[74:75], v[126:127] op_sel_hi:[1,0]
	v_pk_mul_f32 v[72:73], v[72:73], v[126:127] op_sel_hi:[1,0]
	v_pk_mul_f32 v[70:71], v[70:71], v[126:127] op_sel_hi:[1,0]
	v_pk_mul_f32 v[12:13], v[12:13], v[126:127] op_sel_hi:[1,0]
	v_pk_mul_f32 v[10:11], v[10:11], v[126:127] op_sel_hi:[1,0]
	v_pk_mul_f32 v[8:9], v[8:9], v[126:127] op_sel_hi:[1,0]
	v_pk_mul_f32 v[6:7], v[6:7], v[126:127] op_sel_hi:[1,0]
	s_cbranch_scc1 .LBB0_787
	v_add_u32_e32 v126, s62, v3
	v_ashrrev_i32_e32 v127, 31, v126
	v_lshl_add_u32 v4, v4, 3, s61
	v_lshlrev_b64 v[126:127], 14, v[126:127]
	v_ashrrev_i32_e32 v5, 31, v4
	v_lshl_add_u64 v[126:127], s[76:77], 0, v[126:127]
	v_lshl_add_u64 v[192:193], v[4:5], 1, v[126:127]
	v_readlane_b32 s68, v254, 20
	global_load_dwordx4 v[204:207], v[192:193], off
	v_add_co_u32_e32 v126, vcc, s41, v192
	v_lshlrev_b64 v[4:5], 2, v[4:5]
	v_readlane_b32 s70, v254, 22
	v_readlane_b32 s71, v254, 23
	v_addc_co_u32_e32 v127, vcc, 0, v193, vcc
	s_nop 0
	v_lshl_add_u64 v[196:197], s[70:71], 0, v[4:5]
	global_load_dwordx4 v[208:211], v[126:127], off
	global_load_dwordx4 v[142:145], v[196:197], off
	s_nop 0
	global_load_dwordx4 v[126:129], v[196:197], off offset:16
	v_lshl_add_u64 v[198:199], s[12:13], 0, v[4:5]
	global_load_dwordx4 v[146:149], v[198:199], off
	global_load_dwordx4 v[130:133], v[198:199], off offset:16
	s_mov_b64 s[26:27], 0x40000
	v_lshl_add_u64 v[4:5], v[192:193], 0, s[26:27]
	s_mov_b32 s26, 0x40000
	v_add_co_u32_e32 v150, vcc, s26, v192
	s_mov_b64 s[26:27], 0x42000
	s_nop 0
	v_addc_co_u32_e32 v151, vcc, 0, v193, vcc
	v_lshl_add_u64 v[186:187], v[192:193], 0, s[26:27]
	s_mov_b32 s26, 0x42000
	v_add_co_u32_e32 v152, vcc, s26, v192
	s_mov_b64 s[26:27], 0x80000
	s_nop 0
	v_addc_co_u32_e32 v153, vcc, 0, v193, vcc
	v_lshl_add_u64 v[188:189], v[192:193], 0, s[26:27]
	s_mov_b32 s26, 0x80000
	v_add_co_u32_e32 v154, vcc, s26, v192
	s_mov_b64 s[26:27], 0x82000
	s_nop 0
	v_addc_co_u32_e32 v155, vcc, 0, v193, vcc
	v_lshl_add_u64 v[190:191], v[192:193], 0, s[26:27]
	s_mov_b32 s26, 0x82000
	v_add_co_u32_e32 v156, vcc, s26, v192
	s_mov_b64 s[26:27], 0xc0000
	s_nop 0
	v_addc_co_u32_e32 v157, vcc, 0, v193, vcc
	v_lshl_add_u64 v[194:195], v[192:193], 0, s[26:27]
	s_mov_b32 s26, 0xc0000
	v_add_co_u32_e32 v228, vcc, s26, v192
	s_mov_b64 s[26:27], 0xc2000
	s_nop 0
	v_addc_co_u32_e32 v229, vcc, 0, v193, vcc
	v_lshl_add_u64 v[200:201], v[192:193], 0, s[26:27]
	s_mov_b32 s26, 0xc2000
	v_add_co_u32_e32 v230, vcc, s26, v192
	s_mov_b32 s26, 0x200000
	s_nop 0
	v_addc_co_u32_e32 v231, vcc, 0, v193, vcc
	global_load_dwordx4 v[212:215], v[150:151], off
	global_load_dwordx4 v[216:219], v[152:153], off
	global_load_dwordx4 v[162:165], v[154:155], off
	global_load_dwordx4 v[158:161], v[156:157], off
	s_nop 0
	global_load_dwordx4 v[154:157], v[228:229], off
	global_load_dwordx4 v[150:153], v[230:231], off
	v_lshl_add_u64 v[202:203], v[192:193], 0, s[18:19]
	v_readlane_b32 s76, v254, 28
	v_readlane_b32 s77, v254, 29
	v_readlane_b32 s76, v255, 8
	v_readlane_b32 s77, v255, 9
	v_readlane_b32 s69, v254, 21
	v_readlane_b32 s72, v254, 24
	v_readlane_b32 s73, v254, 25
	v_readlane_b32 s74, v254, 26
	v_readlane_b32 s75, v254, 27
	v_readlane_b32 s78, v254, 30
	v_readlane_b32 s79, v254, 31
	v_readlane_b32 s80, v254, 32
	v_readlane_b32 s81, v254, 33
	v_readlane_b32 s82, v254, 34
	v_readlane_b32 s83, v254, 35
	s_waitcnt vmcnt(0)
; __device__ __forceinline__ void unpack8(const u32x4 w, float (&v)[8]) { v[0] = bf_lo(w.x); v[1] = bf_hi(w.x); v[2] = bf_lo(w.y); v[3] = bf_hi(w.y); v[4] = bf_lo(w.z); v[5] = bf_hi(w.z); v[6] = bf_lo(w.w); v[7] = bf_hi(w.w); }
;     __device__ __forceinline__ void after(int te, f32x4 (&acc)[2][2][4][2], const Unit& u, int wr, int wc, int fr, int fq) const {
;     ...
;                     for (int m = 0; m < 4; ++m) { const size_t r = (size_t)(row0 + ai * HALF + m * 16); gs[m] = *(const u32x4*)(proj + r * LDP + PGS + c); ga[m] = *(const u32x4*)(proj + r * LDP + PGA + c); }
; #pragma unroll
;                     for (int m = 0; m < 4; ++m) { float vs[8], va[8]; unpack8(gs[m], vs); unpack8(ga[m], va);
; #pragma unroll
;                         for (int e = 0; e < 4; ++e) {
;                             acc[ai][bj][m][0][e] *= (1.f + __expf(-(va[e] + a0[e]))) * __builtin_amdgcn_rcpf(1.f + __expf(-(vs[e] + s0[e])));
;                             acc[ai][bj][m][1][e] *= (1.f + __expf(-(va[4 + e] + a1[e]))) * __builtin_amdgcn_rcpf(1.f + __expf(-(vs[4 + e] + s1[e]))); } }
	v_lshlrev_b32_e32 v3, 16, v204
	v_and_b32_e32 v204, 0xffff0000, v204
	v_lshlrev_b32_e32 v225, 16, v205
	v_and_b32_e32 v227, 0xffff0000, v205
	v_lshlrev_b32_e32 v205, 16, v206
	v_and_b32_e32 v228, 0xffff0000, v206
	v_lshlrev_b32_e32 v229, 16, v207
	v_and_b32_e32 v233, 0xffff0000, v207
	v_add_f32_e32 v3, v142, v3
	v_add_f32_e32 v204, v143, v204
	v_mul_f32_e32 v3, 0xbfb8aa3b, v3
	v_mul_f32_e32 v204, 0xbfb8aa3b, v204
	v_exp_f32_e32 v3, v3
	v_lshlrev_b32_e32 v230, 16, v209
	v_and_b32_e32 v231, 0xffff0000, v209
	v_exp_f32_e32 v209, v204
	v_lshlrev_b32_e32 v206, 16, v208
	v_and_b32_e32 v207, 0xffff0000, v208
	v_lshlrev_b32_e32 v208, 16, v210
	v_add_f32_e32 v206, v146, v206
	v_add_f32_e32 v208, v130, v208
	v_mul_f32_e32 v206, 0xbfb8aa3b, v206
	v_mul_f32_e32 v208, 0xbfb8aa3b, v208
	v_add_f32_e32 v3, 1.0, v3
	v_exp_f32_e32 v204, v206
	v_exp_f32_e32 v206, v208
	v_rcp_f32_e32 v208, v3
	v_add_f32_e32 v3, 1.0, v209
	v_rcp_f32_e32 v209, v3
	v_add_f32_e32 v3, v127, v228
	v_mul_f32_e32 v3, 0xbfb8aa3b, v3
	v_exp_f32_e32 v3, v3
	v_lshlrev_b32_e32 v234, 16, v211
	v_and_b32_e32 v235, 0xffff0000, v211
	v_add_f32_e32 v205, v126, v205
	v_add_f32_e32 v3, 1.0, v3
	v_rcp_f32_e32 v211, v3
	v_add_f32_e32 v3, v144, v225
	v_mul_f32_e32 v3, 0xbfb8aa3b, v3
	v_exp_f32_e32 v3, v3
	v_mul_f32_e32 v205, 0xbfb8aa3b, v205
	v_exp_f32_e32 v205, v205
	v_add_f32_e32 v225, v148, v230
	v_add_f32_e32 v3, 1.0, v3
	v_rcp_f32_e32 v230, v3
	v_add_f32_e32 v3, v128, v229
	v_mul_f32_e32 v3, 0xbfb8aa3b, v3
	v_add_f32_e32 v227, v145, v227
	v_mul_f32_e32 v225, 0xbfb8aa3b, v225
	v_exp_f32_e32 v3, v3
	v_mul_f32_e32 v227, 0xbfb8aa3b, v227
	v_add_f32_e32 v207, v147, v207
	v_exp_f32_e32 v228, v225
	v_add_f32_e32 v225, v132, v234
	v_exp_f32_e32 v227, v227
	v_and_b32_e32 v232, 0xffff0000, v210
	v_mul_f32_e32 v207, 0xbfb8aa3b, v207
	v_add_f32_e32 v205, 1.0, v205
	v_mul_f32_e32 v225, 0xbfb8aa3b, v225
	v_rcp_f32_e32 v210, v205
	v_exp_f32_e32 v205, v207
	v_add_f32_e32 v207, v131, v232
	v_exp_f32_e32 v232, v225
	v_add_f32_e32 v225, v149, v231
	v_add_f32_e32 v3, 1.0, v3
	v_mul_f32_e32 v225, 0xbfb8aa3b, v225
	v_exp_f32_e32 v229, v225
	v_rcp_f32_e32 v234, v3
	v_add_f32_e32 v3, 1.0, v227
	v_rcp_f32_e32 v231, v3
	v_pk_add_f32 v[228:229], v[228:229], 1.0 op_sel_hi:[1,0]
	v_pk_add_f32 v[204:205], v[204:205], 1.0 op_sel_hi:[1,0]
	v_add_f32_e32 v3, v133, v235
	v_pk_mul_f32 v[204:205], v[204:205], v[208:209]
	v_pk_mul_f32 v[208:209], v[228:229], v[230:231]
	v_mul_f32_e32 v3, 0xbfb8aa3b, v3
	v_pk_mul_f32 v[140:141], v[140:141], v[208:209]
	v_add_f32_e32 v208, v129, v233
	v_mul_f32_e32 v208, 0xbfb8aa3b, v208
	v_exp_f32_e32 v208, v208
	v_exp_f32_e32 v233, v3
	v_mul_f32_e32 v207, 0xbfb8aa3b, v207
	v_exp_f32_e32 v207, v207
	v_add_f32_e32 v3, 1.0, v208
	v_rcp_f32_e32 v235, v3
	v_lshlrev_b32_e32 v3, 16, v212
	v_add_f32_e32 v3, v142, v3
	v_mul_f32_e32 v3, 0xbfb8aa3b, v3
	v_exp_f32_e32 v3, v3
	v_pk_add_f32 v[206:207], v[206:207], 1.0 op_sel_hi:[1,0]
	v_pk_mul_f32 v[138:139], v[138:139], v[204:205]
	v_pk_mul_f32 v[206:207], v[206:207], v[210:211]
	v_add_f32_e32 v3, 1.0, v3
	v_pk_mul_f32 v[134:135], v[134:135], v[206:207]
	v_lshlrev_b32_e32 v207, 16, v214
	v_rcp_f32_e32 v206, v3
	v_add_f32_e32 v3, v126, v207
	v_mul_f32_e32 v3, 0xbfb8aa3b, v3
	v_exp_f32_e32 v3, v3
	v_pk_add_f32 v[204:205], v[232:233], 1.0 op_sel_hi:[1,0]
	v_lshlrev_b32_e32 v208, 16, v218
	v_pk_mul_f32 v[204:205], v[204:205], v[234:235]
	v_add_f32_e32 v3, 1.0, v3
	v_pk_mul_f32 v[136:137], v[136:137], v[204:205]
	v_and_b32_e32 v205, 0xffff0000, v212
	v_rcp_f32_e32 v210, v3
	v_add_f32_e32 v3, v143, v205
	v_mul_f32_e32 v3, 0xbfb8aa3b, v3
	v_exp_f32_e32 v3, v3
	v_add_f32_e32 v207, v130, v208
	v_and_b32_e32 v209, 0xffff0000, v214
	v_mul_f32_e32 v207, 0xbfb8aa3b, v207
	v_add_f32_e32 v3, 1.0, v3
	v_exp_f32_e32 v208, v207
	v_rcp_f32_e32 v207, v3
	v_add_f32_e32 v3, v127, v209
	v_mul_f32_e32 v3, 0xbfb8aa3b, v3
	v_exp_f32_e32 v3, v3
	v_lshlrev_b32_e32 v212, 16, v213
	v_and_b32_e32 v211, 0xffff0000, v216
	v_add_f32_e32 v205, v147, v211
	v_add_f32_e32 v3, 1.0, v3
	v_rcp_f32_e32 v211, v3
	v_add_f32_e32 v3, v144, v212
	v_mul_f32_e32 v3, 0xbfb8aa3b, v3
	v_exp_f32_e32 v3, v3
	v_lshlrev_b32_e32 v225, 16, v215
	v_lshlrev_b32_e32 v214, 16, v217
	v_and_b32_e32 v213, 0xffff0000, v213
	v_add_f32_e32 v3, 1.0, v3
	v_add_f32_e32 v212, v148, v214
	v_rcp_f32_e32 v214, v3
	v_add_f32_e32 v3, v128, v225
	v_mul_f32_e32 v3, 0xbfb8aa3b, v3
	v_add_f32_e32 v213, v145, v213
	v_and_b32_e32 v227, 0xffff0000, v215
	v_lshlrev_b32_e32 v204, 16, v216
	v_and_b32_e32 v215, 0xffff0000, v217
	v_and_b32_e32 v216, 0xffff0000, v218
	v_lshlrev_b32_e32 v217, 16, v219
	v_exp_f32_e32 v3, v3
	v_mul_f32_e32 v213, 0xbfb8aa3b, v213
	v_add_f32_e32 v209, v131, v216
	v_add_f32_e32 v216, v132, v217
	v_exp_f32_e32 v217, v213
	v_add_f32_e32 v204, v146, v204
	v_add_f32_e32 v215, v149, v215
	v_mul_f32_e32 v204, 0xbfb8aa3b, v204
	v_mul_f32_e32 v205, 0xbfb8aa3b, v205
	v_mul_f32_e32 v212, 0xbfb8aa3b, v212
	v_add_f32_e32 v3, 1.0, v3
	v_mul_f32_e32 v213, 0xbfb8aa3b, v215
	v_exp_f32_e32 v204, v204
	v_exp_f32_e32 v205, v205
	v_exp_f32_e32 v212, v212
	v_exp_f32_e32 v213, v213
	v_rcp_f32_e32 v218, v3
	v_add_f32_e32 v3, 1.0, v217
	v_rcp_f32_e32 v215, v3
	v_pk_add_f32 v[212:213], v[212:213], 1.0 op_sel_hi:[1,0]
	v_pk_add_f32 v[204:205], v[204:205], 1.0 op_sel_hi:[1,0]
	v_and_b32_e32 v219, 0xffff0000, v219
	v_pk_mul_f32 v[204:205], v[204:205], v[206:207]
	v_pk_mul_f32 v[206:207], v[212:213], v[214:215]
	v_add_f32_e32 v3, v133, v219
	v_pk_mul_f32 v[124:125], v[124:125], v[206:207]
	v_add_f32_e32 v206, v129, v227
	v_mul_f32_e32 v206, 0xbfb8aa3b, v206
	v_exp_f32_e32 v206, v206
	v_mul_f32_e32 v3, 0xbfb8aa3b, v3
	v_exp_f32_e32 v217, v3
; __device__ __forceinline__ void unpack8(const u32x4 w, float (&v)[8]) { v[0] = bf_lo(w.x); v[1] = bf_hi(w.x); v[2] = bf_lo(w.y); v[3] = bf_hi(w.y); v[4] = bf_lo(w.z); v[5] = bf_hi(w.z); v[6] = bf_lo(w.w); v[7] = bf_hi(w.w); }
;     __device__ __forceinline__ void after(int te, f32x4 (&acc)[2][2][4][2], const Unit& u, int wr, int wc, int fr, int fq) const {
;     ...
;                     for (int m = 0; m < 4; ++m) { const size_t r = (size_t)(row0 + ai * HALF + m * 16); gs[m] = *(const u32x4*)(proj + r * LDP + PGS + c); ga[m] = *(const u32x4*)(proj + r * LDP + PGA + c); }
; #pragma unroll
;                     for (int m = 0; m < 4; ++m) { float vs[8], va[8]; unpack8(gs[m], vs); unpack8(ga[m], va);
; #pragma unroll
;                         for (int e = 0; e < 4; ++e) {
;                             acc[ai][bj][m][0][e] *= (1.f + __expf(-(va[e] + a0[e]))) * __builtin_amdgcn_rcpf(1.f + __expf(-(vs[e] + s0[e])));
;                             acc[ai][bj][m][1][e] *= (1.f + __expf(-(va[4 + e] + a1[e]))) * __builtin_amdgcn_rcpf(1.f + __expf(-(vs[4 + e] + s1[e]))); } }
	v_mul_f32_e32 v216, 0xbfb8aa3b, v216
	v_add_f32_e32 v3, 1.0, v206
	v_rcp_f32_e32 v219, v3
	v_lshlrev_b32_e32 v3, 16, v162
	v_mul_f32_e32 v209, 0xbfb8aa3b, v209
	v_exp_f32_e32 v216, v216
	v_add_f32_e32 v3, v142, v3
	v_exp_f32_e32 v209, v209
	v_mul_f32_e32 v3, 0xbfb8aa3b, v3
	v_exp_f32_e32 v3, v3
	v_pk_mul_f32 v[122:123], v[122:123], v[204:205]
	v_pk_add_f32 v[204:205], v[216:217], 1.0 op_sel_hi:[1,0]
	v_pk_add_f32 v[206:207], v[208:209], 1.0 op_sel_hi:[1,0]
	v_pk_mul_f32 v[204:205], v[204:205], v[218:219]
	v_pk_mul_f32 v[206:207], v[206:207], v[210:211]
	v_pk_mul_f32 v[120:121], v[120:121], v[204:205]
	v_and_b32_e32 v204, 0xffff0000, v162
	v_lshlrev_b32_e32 v162, 16, v164
	v_add_f32_e32 v3, 1.0, v3
	v_pk_mul_f32 v[118:119], v[118:119], v[206:207]
	v_lshlrev_b32_e32 v206, 16, v159
	v_and_b32_e32 v210, 0xffff0000, v159
	v_lshlrev_b32_e32 v159, 16, v160
	v_and_b32_e32 v211, 0xffff0000, v160
	v_rcp_f32_e32 v160, v3
	v_add_f32_e32 v3, v126, v162
	v_mul_f32_e32 v3, 0xbfb8aa3b, v3
	v_exp_f32_e32 v3, v3
	v_lshlrev_b32_e32 v205, 16, v163
	v_and_b32_e32 v207, 0xffff0000, v163
	v_and_b32_e32 v163, 0xffff0000, v164
	v_lshlrev_b32_e32 v164, 16, v158
	v_add_f32_e32 v3, 1.0, v3
	v_lshlrev_b32_e32 v208, 16, v165
	v_and_b32_e32 v209, 0xffff0000, v165
	v_and_b32_e32 v165, 0xffff0000, v158
	v_add_f32_e32 v158, v146, v164
	v_rcp_f32_e32 v164, v3
	v_add_f32_e32 v3, v143, v204
	v_mul_f32_e32 v3, 0xbfb8aa3b, v3
	v_exp_f32_e32 v3, v3
	v_lshlrev_b32_e32 v212, 16, v161
	v_and_b32_e32 v213, 0xffff0000, v161
	v_add_f32_e32 v159, v130, v159
	v_add_f32_e32 v3, 1.0, v3
	v_rcp_f32_e32 v161, v3
	v_add_f32_e32 v3, v127, v163
	v_mul_f32_e32 v3, 0xbfb8aa3b, v3
	v_exp_f32_e32 v3, v3
	v_mul_f32_e32 v159, 0xbfb8aa3b, v159
	v_exp_f32_e32 v162, v159
	v_add_f32_e32 v159, v147, v165
	v_add_f32_e32 v3, 1.0, v3
	v_rcp_f32_e32 v165, v3
	v_add_f32_e32 v3, v144, v205
	v_mul_f32_e32 v3, 0xbfb8aa3b, v3
	v_exp_f32_e32 v3, v3
	v_add_f32_e32 v204, v148, v206
	v_add_f32_e32 v207, v145, v207
	v_mul_f32_e32 v207, 0xbfb8aa3b, v207
	v_add_f32_e32 v3, 1.0, v3
	v_rcp_f32_e32 v206, v3
	v_add_f32_e32 v3, v128, v208
	v_mul_f32_e32 v3, 0xbfb8aa3b, v3
	v_exp_f32_e32 v3, v3
	v_add_f32_e32 v205, v132, v212
	v_exp_f32_e32 v207, v207
	v_mul_f32_e32 v205, 0xbfb8aa3b, v205
	v_exp_f32_e32 v208, v205
	v_add_f32_e32 v205, v149, v210
	v_mul_f32_e32 v158, 0xbfb8aa3b, v158
	v_mul_f32_e32 v159, 0xbfb8aa3b, v159
	v_mul_f32_e32 v204, 0xbfb8aa3b, v204
	v_add_f32_e32 v3, 1.0, v3
	v_mul_f32_e32 v205, 0xbfb8aa3b, v205
	v_exp_f32_e32 v158, v158
	v_exp_f32_e32 v159, v159
	v_exp_f32_e32 v204, v204
	v_exp_f32_e32 v205, v205
	v_rcp_f32_e32 v210, v3
	v_add_f32_e32 v3, 1.0, v207
	v_rcp_f32_e32 v207, v3
	v_pk_add_f32 v[204:205], v[204:205], 1.0 op_sel_hi:[1,0]
	v_pk_add_f32 v[158:159], v[158:159], 1.0 op_sel_hi:[1,0]
	v_add_f32_e32 v3, v133, v213
	v_pk_mul_f32 v[158:159], v[158:159], v[160:161]
	v_pk_mul_f32 v[160:161], v[204:205], v[206:207]
	v_mul_f32_e32 v3, 0xbfb8aa3b, v3
	v_pk_mul_f32 v[116:117], v[116:117], v[160:161]
	v_add_f32_e32 v160, v129, v209
	v_mul_f32_e32 v160, 0xbfb8aa3b, v160
	v_exp_f32_e32 v160, v160
	v_exp_f32_e32 v209, v3
	v_add_f32_e32 v163, v131, v211
	v_mul_f32_e32 v163, 0xbfb8aa3b, v163
	v_add_f32_e32 v3, 1.0, v160
	v_rcp_f32_e32 v211, v3
	v_lshlrev_b32_e32 v3, 16, v154
	v_add_f32_e32 v3, v142, v3
	v_exp_f32_e32 v163, v163
	v_mul_f32_e32 v3, 0xbfb8aa3b, v3
	v_exp_f32_e32 v3, v3
	v_pk_mul_f32 v[114:115], v[114:115], v[158:159]
	v_pk_add_f32 v[158:159], v[208:209], 1.0 op_sel_hi:[1,0]
	v_pk_add_f32 v[160:161], v[162:163], 1.0 op_sel_hi:[1,0]
	v_pk_mul_f32 v[158:159], v[158:159], v[210:211]
	v_pk_mul_f32 v[160:161], v[160:161], v[164:165]
	v_pk_mul_f32 v[112:113], v[112:113], v[158:159]
	v_and_b32_e32 v158, 0xffff0000, v154
	v_lshlrev_b32_e32 v154, 16, v156
	v_add_f32_e32 v3, 1.0, v3
	v_pk_mul_f32 v[110:111], v[110:111], v[160:161]
	v_lshlrev_b32_e32 v160, 16, v151
	v_and_b32_e32 v204, 0xffff0000, v151
	v_lshlrev_b32_e32 v151, 16, v152
	v_and_b32_e32 v162, 0xffff0000, v152
	v_rcp_f32_e32 v152, v3
	v_add_f32_e32 v3, v126, v154
	v_mul_f32_e32 v3, 0xbfb8aa3b, v3
	v_exp_f32_e32 v3, v3
	v_lshlrev_b32_e32 v159, 16, v155
	v_and_b32_e32 v161, 0xffff0000, v155
	v_and_b32_e32 v155, 0xffff0000, v156
	v_lshlrev_b32_e32 v156, 16, v150
	v_add_f32_e32 v3, 1.0, v3
	v_lshlrev_b32_e32 v164, 16, v157
	v_and_b32_e32 v165, 0xffff0000, v157
	v_and_b32_e32 v157, 0xffff0000, v150
	v_add_f32_e32 v150, v146, v156
	v_rcp_f32_e32 v156, v3
	v_add_f32_e32 v3, v143, v158
	v_mul_f32_e32 v3, 0xbfb8aa3b, v3
	v_exp_f32_e32 v3, v3
	v_lshlrev_b32_e32 v205, 16, v153
	v_and_b32_e32 v206, 0xffff0000, v153
	v_add_f32_e32 v151, v130, v151
	v_add_f32_e32 v3, 1.0, v3
	v_rcp_f32_e32 v153, v3
	v_add_f32_e32 v3, v127, v155
	v_add_f32_e32 v155, v131, v162
	v_add_co_u32_e32 v162, vcc, s26, v192
	v_mul_f32_e32 v3, 0xbfb8aa3b, v3
	s_nop 0
	v_addc_co_u32_e32 v163, vcc, 0, v193, vcc
	global_load_dwordx4 v[228:231], v[162:163], off
	v_exp_f32_e32 v3, v3
	v_mul_f32_e32 v151, 0xbfb8aa3b, v151
	s_mov_b32 s26, 0x202000
	v_exp_f32_e32 v154, v151
	v_add_f32_e32 v3, 1.0, v3
	v_add_f32_e32 v151, v147, v157
	v_rcp_f32_e32 v157, v3
	v_add_f32_e32 v3, v144, v159
	v_add_co_u32_e32 v162, vcc, s26, v192
	v_mul_f32_e32 v3, 0xbfb8aa3b, v3
	s_nop 0
	v_addc_co_u32_e32 v163, vcc, 0, v193, vcc
	v_exp_f32_e32 v3, v3
	global_load_dwordx4 v[232:235], v[162:163], off
	v_add_f32_e32 v158, v148, v160
	v_add_f32_e32 v161, v145, v161
	v_add_f32_e32 v3, 1.0, v3
	v_rcp_f32_e32 v160, v3
	v_add_f32_e32 v3, v128, v164
	v_mul_f32_e32 v3, 0xbfb8aa3b, v3
	v_exp_f32_e32 v3, v3
	v_mul_f32_e32 v161, 0xbfb8aa3b, v161
	v_add_f32_e32 v159, v132, v205
	v_exp_f32_e32 v161, v161
	v_mul_f32_e32 v159, 0xbfb8aa3b, v159
; __device__ __forceinline__ void unpack8(const u32x4 w, float (&v)[8]) { v[0] = bf_lo(w.x); v[1] = bf_hi(w.x); v[2] = bf_lo(w.y); v[3] = bf_hi(w.y); v[4] = bf_lo(w.z); v[5] = bf_hi(w.z); v[6] = bf_lo(w.w); v[7] = bf_hi(w.w); }
;     __device__ __forceinline__ void after(int te, f32x4 (&acc)[2][2][4][2], const Unit& u, int wr, int wc, int fr, int fq) const {
;     ...
;                     for (int m = 0; m < 4; ++m) { const size_t r = (size_t)(row0 + ai * HALF + m * 16); gs[m] = *(const u32x4*)(proj + r * LDP + PGS + c); ga[m] = *(const u32x4*)(proj + r * LDP + PGA + c); }
; #pragma unroll
;                     for (int m = 0; m < 4; ++m) { float vs[8], va[8]; unpack8(gs[m], vs); unpack8(ga[m], va);
; #pragma unroll
;                         for (int e = 0; e < 4; ++e) {
;                             acc[ai][bj][m][0][e] *= (1.f + __expf(-(va[e] + a0[e]))) * __builtin_amdgcn_rcpf(1.f + __expf(-(vs[e] + s0[e])));
;                             acc[ai][bj][m][1][e] *= (1.f + __expf(-(va[4 + e] + a1[e]))) * __builtin_amdgcn_rcpf(1.f + __expf(-(vs[4 + e] + s1[e]))); } }
	v_exp_f32_e32 v162, v159
	v_add_f32_e32 v159, v149, v204
	v_mul_f32_e32 v150, 0xbfb8aa3b, v150
	v_mul_f32_e32 v151, 0xbfb8aa3b, v151
	v_mul_f32_e32 v158, 0xbfb8aa3b, v158
	v_add_f32_e32 v3, 1.0, v3
	v_mul_f32_e32 v159, 0xbfb8aa3b, v159
	v_exp_f32_e32 v150, v150
	v_exp_f32_e32 v151, v151
	v_exp_f32_e32 v158, v158
	v_exp_f32_e32 v159, v159
	v_rcp_f32_e32 v164, v3
	v_add_f32_e32 v3, 1.0, v161
	v_rcp_f32_e32 v161, v3
	v_pk_add_f32 v[158:159], v[158:159], 1.0 op_sel_hi:[1,0]
	v_pk_add_f32 v[150:151], v[150:151], 1.0 op_sel_hi:[1,0]
	v_add_f32_e32 v3, v133, v206
	v_pk_mul_f32 v[150:151], v[150:151], v[152:153]
	v_pk_mul_f32 v[152:153], v[158:159], v[160:161]
	v_mul_f32_e32 v3, 0xbfb8aa3b, v3
	v_pk_mul_f32 v[108:109], v[108:109], v[152:153]
	v_add_f32_e32 v152, v129, v165
	v_mul_f32_e32 v152, 0xbfb8aa3b, v152
	v_exp_f32_e32 v152, v152
	v_exp_f32_e32 v163, v3
	v_mul_f32_e32 v155, 0xbfb8aa3b, v155
	v_exp_f32_e32 v155, v155
	v_add_f32_e32 v3, 1.0, v152
	v_rcp_f32_e32 v165, v3
	s_mov_b64 s[26:27], 0x200000
	v_lshl_add_u64 v[218:219], v[192:193], 0, s[26:27]
	s_mov_b64 s[26:27], 0x202000
	v_pk_mul_f32 v[106:107], v[106:107], v[150:151]
	v_pk_add_f32 v[150:151], v[162:163], 1.0 op_sel_hi:[1,0]
	v_lshl_add_u64 v[216:217], v[192:193], 0, s[26:27]
	s_mov_b64 s[26:27], 0x240000
	v_pk_mul_f32 v[150:151], v[150:151], v[164:165]
	v_lshl_add_u64 v[204:205], v[192:193], 0, s[26:27]
	s_mov_b32 s26, 0x240000
	v_pk_add_f32 v[152:153], v[154:155], 1.0 op_sel_hi:[1,0]
	v_pk_mul_f32 v[104:105], v[104:105], v[150:151]
	v_add_co_u32_e32 v150, vcc, s26, v192
	s_mov_b64 s[26:27], 0x242000
	v_pk_mul_f32 v[152:153], v[152:153], v[156:157]
	v_addc_co_u32_e32 v151, vcc, 0, v193, vcc
	v_lshl_add_u64 v[206:207], v[192:193], 0, s[26:27]
	s_mov_b32 s26, 0x242000
	v_pk_mul_f32 v[102:103], v[102:103], v[152:153]
	v_add_co_u32_e32 v152, vcc, s26, v192
	s_mov_b64 s[26:27], 0x280000
	s_nop 0
	v_addc_co_u32_e32 v153, vcc, 0, v193, vcc
	global_load_dwordx4 v[236:239], v[150:151], off
	global_load_dwordx4 v[240:243], v[152:153], off
	s_waitcnt vmcnt(3)
	v_lshlrev_b32_e32 v3, 16, v228
	v_add_f32_e32 v3, v142, v3
	v_mul_f32_e32 v3, 0xbfb8aa3b, v3
	v_exp_f32_e32 v3, v3
	v_lshlrev_b32_e32 v227, 16, v229
	v_and_b32_e32 v245, 0xffff0000, v229
	v_lshlrev_b32_e32 v229, 16, v230
	v_add_f32_e32 v3, 1.0, v3
	v_and_b32_e32 v246, 0xffff0000, v230
	v_rcp_f32_e32 v230, v3
	v_add_f32_e32 v3, v126, v229
	v_mul_f32_e32 v3, 0xbfb8aa3b, v3
	v_exp_f32_e32 v3, v3
	v_lshl_add_u64 v[208:209], v[192:193], 0, s[26:27]
	s_mov_b32 s26, 0x280000
	v_add_co_u32_e32 v150, vcc, s26, v192
	s_mov_b64 s[26:27], 0x282000
	s_nop 0
	v_addc_co_u32_e32 v151, vcc, 0, v193, vcc
	v_lshl_add_u64 v[210:211], v[192:193], 0, s[26:27]
	s_mov_b32 s26, 0x282000
	v_add_co_u32_e32 v152, vcc, s26, v192
	v_and_b32_e32 v225, 0xffff0000, v228
	v_add_f32_e32 v3, 1.0, v3
	v_addc_co_u32_e32 v153, vcc, 0, v193, vcc
	global_load_dwordx4 v[162:165], v[150:151], off
	global_load_dwordx4 v[158:161], v[152:153], off
	v_lshlrev_b32_e32 v247, 16, v231
	v_and_b32_e32 v251, 0xffff0000, v231
	s_waitcnt vmcnt(4)
	v_lshlrev_b32_e32 v228, 16, v232
	v_and_b32_e32 v231, 0xffff0000, v232
	v_lshlrev_b32_e32 v248, 16, v233
	v_and_b32_e32 v249, 0xffff0000, v233
	v_lshlrev_b32_e32 v232, 16, v234
	v_and_b32_e32 v233, 0xffff0000, v234
	v_rcp_f32_e32 v234, v3
	v_add_f32_e32 v3, v143, v225
	v_mul_f32_e32 v3, 0xbfb8aa3b, v3
	v_exp_f32_e32 v3, v3
	v_add_f32_e32 v225, v147, v231
	v_lshlrev_b32_e32 v250, 16, v235
	v_and_b32_e32 v253, 0xffff0000, v235
	v_add_f32_e32 v3, 1.0, v3
	v_rcp_f32_e32 v231, v3
	v_add_f32_e32 v3, v127, v246
	v_mul_f32_e32 v3, 0xbfb8aa3b, v3
	v_exp_f32_e32 v3, v3
	v_add_f32_e32 v229, v130, v232
	v_mul_f32_e32 v229, 0xbfb8aa3b, v229
	v_mul_f32_e32 v225, 0xbfb8aa3b, v225
	v_add_f32_e32 v3, 1.0, v3
	v_rcp_f32_e32 v235, v3
	v_add_f32_e32 v3, v144, v227
	v_mul_f32_e32 v3, 0xbfb8aa3b, v3
	v_exp_f32_e32 v3, v3
	v_exp_f32_e32 v232, v229
	v_exp_f32_e32 v229, v225
	v_add_f32_e32 v225, v131, v233
	v_mul_f32_e32 v225, 0xbfb8aa3b, v225
	v_exp_f32_e32 v233, v225
	v_add_f32_e32 v225, v148, v248
	v_mul_f32_e32 v225, 0xbfb8aa3b, v225
	v_add_f32_e32 v3, 1.0, v3
	v_exp_f32_e32 v246, v225
	v_rcp_f32_e32 v248, v3
	v_add_f32_e32 v3, v128, v247
	v_add_f32_e32 v225, v132, v250
	v_mul_f32_e32 v3, 0xbfb8aa3b, v3
	v_mul_f32_e32 v225, 0xbfb8aa3b, v225
	v_add_f32_e32 v227, v145, v245
	v_exp_f32_e32 v3, v3
	v_exp_f32_e32 v250, v225
	v_add_f32_e32 v225, v149, v249
	v_mul_f32_e32 v227, 0xbfb8aa3b, v227
	v_exp_f32_e32 v227, v227
	v_mul_f32_e32 v225, 0xbfb8aa3b, v225
	v_exp_f32_e32 v247, v225
	v_add_f32_e32 v225, v129, v251
	v_mul_f32_e32 v225, 0xbfb8aa3b, v225
	v_add_f32_e32 v3, 1.0, v3
	v_exp_f32_e32 v225, v225
	v_rcp_f32_e32 v252, v3
	v_add_f32_e32 v3, 1.0, v227
	v_add_f32_e32 v228, v146, v228
	v_rcp_f32_e32 v249, v3
	v_add_f32_e32 v3, v133, v253
	v_mul_f32_e32 v228, 0xbfb8aa3b, v228
	v_mul_f32_e32 v3, 0xbfb8aa3b, v3
	v_exp_f32_e32 v228, v228
	v_exp_f32_e32 v251, v3
	v_add_f32_e32 v3, 1.0, v225
	v_rcp_f32_e32 v253, v3
	s_waitcnt vmcnt(3)
; __device__ __forceinline__ void unpack8(const u32x4 w, float (&v)[8]) { v[0] = bf_lo(w.x); v[1] = bf_hi(w.x); v[2] = bf_lo(w.y); v[3] = bf_hi(w.y); v[4] = bf_lo(w.z); v[5] = bf_hi(w.z); v[6] = bf_lo(w.w); v[7] = bf_hi(w.w); }
;     __device__ __forceinline__ void after(int te, f32x4 (&acc)[2][2][4][2], const Unit& u, int wr, int wc, int fr, int fq) const {
;     ...
;                     for (int m = 0; m < 4; ++m) { const size_t r = (size_t)(row0 + ai * HALF + m * 16); gs[m] = *(const u32x4*)(proj + r * LDP + PGS + c); ga[m] = *(const u32x4*)(proj + r * LDP + PGA + c); }
; #pragma unroll
;                     for (int m = 0; m < 4; ++m) { float vs[8], va[8]; unpack8(gs[m], vs); unpack8(ga[m], va);
; #pragma unroll
;                         for (int e = 0; e < 4; ++e) {
;                             acc[ai][bj][m][0][e] *= (1.f + __expf(-(va[e] + a0[e]))) * __builtin_amdgcn_rcpf(1.f + __expf(-(vs[e] + s0[e])));
;                             acc[ai][bj][m][1][e] *= (1.f + __expf(-(va[4 + e] + a1[e]))) * __builtin_amdgcn_rcpf(1.f + __expf(-(vs[4 + e] + s1[e]))); } }
	v_lshlrev_b32_e32 v3, 16, v236
	v_add_f32_e32 v3, v142, v3
	v_mul_f32_e32 v3, 0xbfb8aa3b, v3
	v_pk_add_f32 v[228:229], v[228:229], 1.0 op_sel_hi:[1,0]
	v_exp_f32_e32 v3, v3
	v_pk_add_f32 v[246:247], v[246:247], 1.0 op_sel_hi:[1,0]
	v_pk_mul_f32 v[228:229], v[228:229], v[230:231]
	v_pk_mul_f32 v[230:231], v[246:247], v[248:249]
	v_pk_mul_f32 v[98:99], v[98:99], v[228:229]
	v_pk_add_f32 v[228:229], v[250:251], 1.0 op_sel_hi:[1,0]
	v_pk_mul_f32 v[100:101], v[100:101], v[230:231]
	v_pk_add_f32 v[230:231], v[232:233], 1.0 op_sel_hi:[1,0]
	v_pk_mul_f32 v[228:229], v[228:229], v[252:253]
	v_pk_mul_f32 v[230:231], v[230:231], v[234:235]
	v_pk_mul_f32 v[96:97], v[96:97], v[228:229]
	v_lshlrev_b32_e32 v229, 16, v238
	v_add_f32_e32 v3, 1.0, v3
	v_pk_mul_f32 v[94:95], v[94:95], v[230:231]
	v_rcp_f32_e32 v230, v3
	v_add_f32_e32 v3, v126, v229
	v_mul_f32_e32 v3, 0xbfb8aa3b, v3
	v_exp_f32_e32 v3, v3
	v_and_b32_e32 v225, 0xffff0000, v236
	s_mov_b64 s[26:27], 0x2c0000
	v_lshl_add_u64 v[212:213], v[192:193], 0, s[26:27]
	v_add_f32_e32 v3, 1.0, v3
	v_rcp_f32_e32 v234, v3
	v_add_f32_e32 v3, v143, v225
	v_mul_f32_e32 v3, 0xbfb8aa3b, v3
	v_exp_f32_e32 v3, v3
	s_mov_b32 s26, 0x2c0000
	v_add_co_u32_e32 v150, vcc, s26, v192
	s_mov_b64 s[26:27], 0x2c2000
	s_nop 0
	v_addc_co_u32_e32 v151, vcc, 0, v193, vcc
	v_lshl_add_u64 v[214:215], v[192:193], 0, s[26:27]
	s_mov_b32 s26, 0x2c2000
	v_and_b32_e32 v233, 0xffff0000, v238
	s_waitcnt vmcnt(2)
	v_and_b32_e32 v231, 0xffff0000, v240
	v_add_f32_e32 v3, 1.0, v3
	v_add_co_u32_e32 v152, vcc, s26, v192
	v_add_f32_e32 v225, v147, v231
	v_rcp_f32_e32 v231, v3
	v_add_f32_e32 v3, v127, v233
	v_addc_co_u32_e32 v153, vcc, 0, v193, vcc
	v_mul_f32_e32 v3, 0xbfb8aa3b, v3
	global_load_dwordx4 v[154:157], v[150:151], off
	s_nop 0
	global_load_dwordx4 v[150:153], v[152:153], off
	v_exp_f32_e32 v3, v3
	v_lshlrev_b32_e32 v232, 16, v242
	v_add_f32_e32 v229, v130, v232
	v_lshlrev_b32_e32 v227, 16, v237
	v_and_b32_e32 v235, 0xffff0000, v242
	v_mul_f32_e32 v229, 0xbfb8aa3b, v229
	v_mul_f32_e32 v225, 0xbfb8aa3b, v225
	v_add_f32_e32 v3, 1.0, v3
	v_exp_f32_e32 v232, v229
	v_exp_f32_e32 v229, v225
	v_add_f32_e32 v225, v131, v235
	v_rcp_f32_e32 v235, v3
	v_add_f32_e32 v3, v144, v227
	v_mul_f32_e32 v3, 0xbfb8aa3b, v3
	v_exp_f32_e32 v3, v3
	v_lshlrev_b32_e32 v236, 16, v241
	v_mul_f32_e32 v225, 0xbfb8aa3b, v225
	v_exp_f32_e32 v233, v225
	v_add_f32_e32 v225, v148, v236
	v_lshlrev_b32_e32 v245, 16, v239
	v_lshlrev_b32_e32 v228, 16, v240
	v_lshlrev_b32_e32 v240, 16, v243
	v_mul_f32_e32 v225, 0xbfb8aa3b, v225
	v_add_f32_e32 v3, 1.0, v3
	v_and_b32_e32 v237, 0xffff0000, v237
	v_exp_f32_e32 v236, v225
	v_rcp_f32_e32 v238, v3
	v_add_f32_e32 v3, v128, v245
	v_add_f32_e32 v225, v132, v240
	v_and_b32_e32 v246, 0xffff0000, v239
	v_and_b32_e32 v239, 0xffff0000, v241
	v_mul_f32_e32 v3, 0xbfb8aa3b, v3
	v_mul_f32_e32 v225, 0xbfb8aa3b, v225
	v_add_f32_e32 v227, v145, v237
	v_exp_f32_e32 v3, v3
	v_exp_f32_e32 v240, v225
	v_add_f32_e32 v225, v149, v239
	v_mul_f32_e32 v227, 0xbfb8aa3b, v227
	v_exp_f32_e32 v227, v227
	v_mul_f32_e32 v225, 0xbfb8aa3b, v225
	v_exp_f32_e32 v237, v225
	v_add_f32_e32 v225, v129, v246
	v_mul_f32_e32 v225, 0xbfb8aa3b, v225
	v_add_f32_e32 v3, 1.0, v3
	v_exp_f32_e32 v225, v225
	v_and_b32_e32 v241, 0xffff0000, v243
	v_rcp_f32_e32 v242, v3
	v_add_f32_e32 v3, 1.0, v227
	v_rcp_f32_e32 v239, v3
	v_add_f32_e32 v3, v133, v241
	v_add_f32_e32 v228, v146, v228
	v_mul_f32_e32 v3, 0xbfb8aa3b, v3
	v_mul_f32_e32 v228, 0xbfb8aa3b, v228
	v_exp_f32_e32 v241, v3
	v_add_f32_e32 v3, 1.0, v225
	v_exp_f32_e32 v228, v228
	v_rcp_f32_e32 v243, v3
	s_waitcnt vmcnt(3)
	v_lshlrev_b32_e32 v3, 16, v162
	v_add_f32_e32 v3, v142, v3
	v_mul_f32_e32 v3, 0xbfb8aa3b, v3
	v_exp_f32_e32 v3, v3
	v_pk_add_f32 v[236:237], v[236:237], 1.0 op_sel_hi:[1,0]
	v_pk_add_f32 v[228:229], v[228:229], 1.0 op_sel_hi:[1,0]
	v_and_b32_e32 v225, 0xffff0000, v162
	v_pk_mul_f32 v[228:229], v[228:229], v[230:231]
	v_pk_mul_f32 v[230:231], v[236:237], v[238:239]
	v_pk_mul_f32 v[90:91], v[90:91], v[228:229]
	v_pk_mul_f32 v[92:93], v[92:93], v[230:231]
	v_pk_add_f32 v[228:229], v[240:241], 1.0 op_sel_hi:[1,0]
	v_pk_add_f32 v[230:231], v[232:233], 1.0 op_sel_hi:[1,0]
	v_pk_mul_f32 v[228:229], v[228:229], v[242:243]
	v_pk_mul_f32 v[230:231], v[230:231], v[234:235]
	v_lshlrev_b32_e32 v162, 16, v164
	v_add_f32_e32 v3, 1.0, v3
	v_pk_mul_f32 v[88:89], v[88:89], v[228:229]
	v_pk_mul_f32 v[86:87], v[86:87], v[230:231]
	s_waitcnt vmcnt(2)
; __device__ __forceinline__ void unpack8(const u32x4 w, float (&v)[8]) { v[0] = bf_lo(w.x); v[1] = bf_hi(w.x); v[2] = bf_lo(w.y); v[3] = bf_hi(w.y); v[4] = bf_lo(w.z); v[5] = bf_hi(w.z); v[6] = bf_lo(w.w); v[7] = bf_hi(w.w); }
;     __device__ __forceinline__ void after(int te, f32x4 (&acc)[2][2][4][2], const Unit& u, int wr, int wc, int fr, int fq) const {
;     ...
;                     for (int m = 0; m < 4; ++m) { const size_t r = (size_t)(row0 + ai * HALF + m * 16); gs[m] = *(const u32x4*)(proj + r * LDP + PGS + c); ga[m] = *(const u32x4*)(proj + r * LDP + PGA + c); }
; #pragma unroll
;                     for (int m = 0; m < 4; ++m) { float vs[8], va[8]; unpack8(gs[m], vs); unpack8(ga[m], va);
; #pragma unroll
;                         for (int e = 0; e < 4; ++e) {
;                             acc[ai][bj][m][0][e] *= (1.f + __expf(-(va[e] + a0[e]))) * __builtin_amdgcn_rcpf(1.f + __expf(-(vs[e] + s0[e])));
;                             acc[ai][bj][m][1][e] *= (1.f + __expf(-(va[4 + e] + a1[e]))) * __builtin_amdgcn_rcpf(1.f + __expf(-(vs[4 + e] + s1[e]))); } }
	v_lshlrev_b32_e32 v228, 16, v159
	v_and_b32_e32 v234, 0xffff0000, v159
	v_lshlrev_b32_e32 v159, 16, v160
	v_and_b32_e32 v230, 0xffff0000, v160
	v_rcp_f32_e32 v160, v3
	v_add_f32_e32 v3, v126, v162
	v_mul_f32_e32 v3, 0xbfb8aa3b, v3
	v_exp_f32_e32 v3, v3
	v_lshlrev_b32_e32 v227, 16, v163
	v_and_b32_e32 v229, 0xffff0000, v163
	v_and_b32_e32 v163, 0xffff0000, v164
	v_lshlrev_b32_e32 v164, 16, v158
	v_add_f32_e32 v3, 1.0, v3
	v_lshlrev_b32_e32 v231, 16, v165
	v_and_b32_e32 v233, 0xffff0000, v165
	v_and_b32_e32 v165, 0xffff0000, v158
	v_add_f32_e32 v158, v146, v164
	v_rcp_f32_e32 v164, v3
	v_add_f32_e32 v3, v143, v225
	v_mul_f32_e32 v3, 0xbfb8aa3b, v3
	v_exp_f32_e32 v3, v3
	v_lshlrev_b32_e32 v232, 16, v161
	v_and_b32_e32 v235, 0xffff0000, v161
	v_add_f32_e32 v159, v130, v159
	v_add_f32_e32 v3, 1.0, v3
	v_rcp_f32_e32 v161, v3
	v_add_f32_e32 v3, v127, v163
	v_mul_f32_e32 v3, 0xbfb8aa3b, v3
	v_exp_f32_e32 v3, v3
	v_mul_f32_e32 v159, 0xbfb8aa3b, v159
	v_exp_f32_e32 v162, v159
	v_add_f32_e32 v159, v147, v165
	v_add_f32_e32 v3, 1.0, v3
	v_rcp_f32_e32 v165, v3
	v_add_f32_e32 v3, v144, v227
	v_mul_f32_e32 v3, 0xbfb8aa3b, v3
	v_exp_f32_e32 v3, v3
	v_add_f32_e32 v163, v131, v230
	v_add_f32_e32 v225, v148, v228
	v_add_f32_e32 v227, v145, v229
	v_add_f32_e32 v3, 1.0, v3
	v_rcp_f32_e32 v230, v3
	v_add_f32_e32 v3, v128, v231
	v_mul_f32_e32 v3, 0xbfb8aa3b, v3
	v_mul_f32_e32 v225, 0xbfb8aa3b, v225
	v_exp_f32_e32 v3, v3
	v_mul_f32_e32 v227, 0xbfb8aa3b, v227
	v_exp_f32_e32 v228, v225
	v_add_f32_e32 v225, v132, v232
	v_exp_f32_e32 v227, v227
	v_mul_f32_e32 v225, 0xbfb8aa3b, v225
	v_exp_f32_e32 v232, v225
	v_add_f32_e32 v225, v149, v234
	v_mul_f32_e32 v158, 0xbfb8aa3b, v158
	v_mul_f32_e32 v159, 0xbfb8aa3b, v159
	v_add_f32_e32 v3, 1.0, v3
	v_mul_f32_e32 v225, 0xbfb8aa3b, v225
	v_exp_f32_e32 v158, v158
	v_exp_f32_e32 v159, v159
	v_exp_f32_e32 v229, v225
	v_rcp_f32_e32 v234, v3
	v_add_f32_e32 v3, 1.0, v227
	v_rcp_f32_e32 v231, v3
	v_pk_add_f32 v[228:229], v[228:229], 1.0 op_sel_hi:[1,0]
	v_pk_add_f32 v[158:159], v[158:159], 1.0 op_sel_hi:[1,0]
	v_add_f32_e32 v3, v133, v235
	v_pk_mul_f32 v[158:159], v[158:159], v[160:161]
	v_pk_mul_f32 v[160:161], v[228:229], v[230:231]
	v_mul_f32_e32 v3, 0xbfb8aa3b, v3
	v_pk_mul_f32 v[84:85], v[84:85], v[160:161]
	v_add_f32_e32 v160, v129, v233
	v_mul_f32_e32 v160, 0xbfb8aa3b, v160
	v_exp_f32_e32 v160, v160
	v_exp_f32_e32 v233, v3
	s_waitcnt vmcnt(1)
	v_lshlrev_b32_e32 v225, 16, v155
	v_and_b32_e32 v227, 0xffff0000, v155
	v_add_f32_e32 v3, 1.0, v160
	v_rcp_f32_e32 v235, v3
	v_lshlrev_b32_e32 v3, 16, v154
	v_add_f32_e32 v3, v142, v3
	v_mul_f32_e32 v3, 0xbfb8aa3b, v3
	v_exp_f32_e32 v3, v3
	v_lshlrev_b32_e32 v155, 16, v156
	v_and_b32_e32 v236, 0xffff0000, v156
	s_waitcnt vmcnt(0)
	v_lshlrev_b32_e32 v156, 16, v150
	v_add_f32_e32 v3, 1.0, v3
	v_mul_f32_e32 v163, 0xbfb8aa3b, v163
	v_add_f32_e32 v142, v146, v156
	v_rcp_f32_e32 v146, v3
	v_add_f32_e32 v3, v126, v155
	v_exp_f32_e32 v163, v163
	v_mul_f32_e32 v3, 0xbfb8aa3b, v3
	v_exp_f32_e32 v3, v3
	v_pk_mul_f32 v[82:83], v[82:83], v[158:159]
	v_pk_add_f32 v[158:159], v[232:233], 1.0 op_sel_hi:[1,0]
	v_pk_add_f32 v[160:161], v[162:163], 1.0 op_sel_hi:[1,0]
	v_pk_mul_f32 v[158:159], v[158:159], v[234:235]
	v_pk_mul_f32 v[160:161], v[160:161], v[164:165]
	v_and_b32_e32 v150, 0xffff0000, v150
	v_lshlrev_b32_e32 v239, 16, v151
	v_and_b32_e32 v240, 0xffff0000, v151
	v_lshlrev_b32_e32 v151, 16, v152
	global_load_dwordx4 v[228:231], v[192:193], off offset:256
	global_load_dwordx4 v[232:235], v[202:203], off offset:256
	v_add_f32_e32 v3, 1.0, v3
	v_pk_mul_f32 v[80:81], v[80:81], v[158:159]
	v_pk_mul_f32 v[78:79], v[78:79], v[160:161]
	v_and_b32_e32 v241, 0xffff0000, v152
	v_lshlrev_b32_e32 v242, 16, v153
	v_and_b32_e32 v243, 0xffff0000, v153
	v_add_f32_e32 v126, v130, v151
	v_rcp_f32_e32 v130, v3
	v_add_f32_e32 v3, v147, v150
	global_load_dwordx4 v[150:153], v[196:197], off offset:528
	global_load_dwordx4 v[158:161], v[196:197], off offset:512
	v_and_b32_e32 v154, 0xffff0000, v154
	v_lshlrev_b32_e32 v237, 16, v157
	v_and_b32_e32 v238, 0xffff0000, v157
	v_add_f32_e32 v143, v143, v154
	global_load_dwordx4 v[154:157], v[198:199], off offset:528
	global_load_dwordx4 v[162:165], v[198:199], off offset:512
	v_mul_f32_e32 v143, 0xbfb8aa3b, v143
	v_exp_f32_e32 v147, v143
	v_mul_f32_e32 v3, 0xbfb8aa3b, v3
	v_exp_f32_e32 v143, v3
	v_add_f32_e32 v145, v145, v227
	v_add_f32_e32 v3, 1.0, v147
	v_rcp_f32_e32 v147, v3
	v_add_f32_e32 v3, v127, v236
	v_mul_f32_e32 v3, 0xbfb8aa3b, v3
	v_exp_f32_e32 v3, v3
	v_add_f32_e32 v127, v131, v241
	v_mul_f32_e32 v145, 0xbfb8aa3b, v145
	v_add_f32_e32 v129, v129, v238
	v_add_f32_e32 v3, 1.0, v3
	v_rcp_f32_e32 v131, v3
	v_add_f32_e32 v3, v144, v225
	v_mul_f32_e32 v3, 0xbfb8aa3b, v3
	v_exp_f32_e32 v3, v3
	v_add_f32_e32 v144, v148, v239
	v_mul_f32_e32 v129, 0xbfb8aa3b, v129
	v_mul_f32_e32 v142, 0xbfb8aa3b, v142
	v_add_f32_e32 v3, 1.0, v3
	v_rcp_f32_e32 v148, v3
	v_add_f32_e32 v3, v128, v237
	v_mul_f32_e32 v3, 0xbfb8aa3b, v3
	v_exp_f32_e32 v3, v3
	v_add_f32_e32 v128, v132, v242
	v_add_f32_e32 v132, v149, v240
	v_exp_f32_e32 v149, v145
	v_add_f32_e32 v3, 1.0, v3
	v_mul_f32_e32 v132, 0xbfb8aa3b, v132
	v_exp_f32_e32 v145, v132
	v_rcp_f32_e32 v132, v3
	v_add_f32_e32 v3, 1.0, v149
	v_rcp_f32_e32 v149, v3
	v_add_f32_e32 v3, v133, v243
	v_exp_f32_e32 v133, v129
	v_mul_f32_e32 v126, 0xbfb8aa3b, v126
	v_mul_f32_e32 v127, 0xbfb8aa3b, v127
	v_mul_f32_e32 v144, 0xbfb8aa3b, v144
	v_mul_f32_e32 v128, 0xbfb8aa3b, v128
	v_mul_f32_e32 v3, 0xbfb8aa3b, v3
	v_exp_f32_e32 v142, v142
	v_exp_f32_e32 v126, v126
	v_exp_f32_e32 v127, v127
	v_exp_f32_e32 v144, v144
	v_exp_f32_e32 v128, v128
	v_exp_f32_e32 v129, v3
	v_add_f32_e32 v3, 1.0, v133
	v_rcp_f32_e32 v133, v3
	v_pk_add_f32 v[144:145], v[144:145], 1.0 op_sel_hi:[1,0]
	v_pk_add_f32 v[142:143], v[142:143], 1.0 op_sel_hi:[1,0]
	v_pk_add_f32 v[128:129], v[128:129], 1.0 op_sel_hi:[1,0]
	v_pk_add_f32 v[126:127], v[126:127], 1.0 op_sel_hi:[1,0]
	v_pk_mul_f32 v[142:143], v[142:143], v[146:147]
	v_pk_mul_f32 v[144:145], v[144:145], v[148:149]
	v_pk_mul_f32 v[126:127], v[126:127], v[130:131]
	v_pk_mul_f32 v[128:129], v[128:129], v[132:133]
	v_pk_mul_f32 v[76:77], v[76:77], v[144:145]
	v_pk_mul_f32 v[74:75], v[74:75], v[142:143]
	v_pk_mul_f32 v[72:73], v[72:73], v[128:129]
	v_pk_mul_f32 v[70:71], v[70:71], v[126:127]
	global_load_dwordx4 v[196:199], v[4:5], off offset:256
	global_load_dwordx4 v[236:239], v[186:187], off offset:256
	global_load_dwordx4 v[146:149], v[188:189], off offset:256
	global_load_dwordx4 v[142:145], v[190:191], off offset:256
	global_load_dwordx4 v[130:133], v[194:195], off offset:256
	global_load_dwordx4 v[126:129], v[200:201], off offset:256
	s_waitcnt vmcnt(11)
; __device__ __forceinline__ void unpack8(const u32x4 w, float (&v)[8]) { v[0] = bf_lo(w.x); v[1] = bf_hi(w.x); v[2] = bf_lo(w.y); v[3] = bf_hi(w.y); v[4] = bf_lo(w.z); v[5] = bf_hi(w.z); v[6] = bf_lo(w.w); v[7] = bf_hi(w.w); }
;     __device__ __forceinline__ void after(int te, f32x4 (&acc)[2][2][4][2], const Unit& u, int wr, int wc, int fr, int fq) const {
;     ...
;                     for (int m = 0; m < 4; ++m) { const size_t r = (size_t)(row0 + ai * HALF + m * 16); gs[m] = *(const u32x4*)(proj + r * LDP + PGS + c); ga[m] = *(const u32x4*)(proj + r * LDP + PGA + c); }
; #pragma unroll
;                     for (int m = 0; m < 4; ++m) { float vs[8], va[8]; unpack8(gs[m], vs); unpack8(ga[m], va);
; #pragma unroll
;                         for (int e = 0; e < 4; ++e) {
;                             acc[ai][bj][m][0][e] *= (1.f + __expf(-(va[e] + a0[e]))) * __builtin_amdgcn_rcpf(1.f + __expf(-(vs[e] + s0[e])));
;                             acc[ai][bj][m][1][e] *= (1.f + __expf(-(va[4 + e] + a1[e]))) * __builtin_amdgcn_rcpf(1.f + __expf(-(vs[4 + e] + s1[e]))); } }
	v_lshlrev_b32_e32 v3, 16, v228
	v_lshlrev_b32_e32 v187, 16, v230
	v_and_b32_e32 v5, 0xffff0000, v228
	s_waitcnt vmcnt(10)
	v_lshlrev_b32_e32 v188, 16, v234
	v_and_b32_e32 v189, 0xffff0000, v230
	v_lshlrev_b32_e32 v192, 16, v229
	v_and_b32_e32 v191, 0xffff0000, v232
	v_lshlrev_b32_e32 v195, 16, v231
	v_lshlrev_b32_e32 v194, 16, v233
	v_and_b32_e32 v193, 0xffff0000, v229
	v_lshlrev_b32_e32 v203, 16, v235
	s_waitcnt vmcnt(8)
	v_add_f32_e32 v3, v158, v3
	v_mul_f32_e32 v3, 0xbfb8aa3b, v3
	v_exp_f32_e32 v3, v3
	v_add_f32_e32 v193, v161, v193
	v_mul_f32_e32 v193, 0xbfb8aa3b, v193
	v_lshlrev_b32_e32 v4, 16, v232
	v_add_f32_e32 v3, 1.0, v3
	v_rcp_f32_e32 v186, v3
	v_add_f32_e32 v3, v150, v187
	v_mul_f32_e32 v3, 0xbfb8aa3b, v3
	v_exp_f32_e32 v3, v3
	s_waitcnt vmcnt(7)
	v_add_f32_e32 v187, v154, v188
	v_mul_f32_e32 v187, 0xbfb8aa3b, v187
	v_exp_f32_e32 v188, v187
	v_add_f32_e32 v3, 1.0, v3
	v_rcp_f32_e32 v190, v3
	v_add_f32_e32 v3, v159, v5
	v_mul_f32_e32 v3, 0xbfb8aa3b, v3
	v_exp_f32_e32 v3, v3
	s_waitcnt vmcnt(6)
	v_add_f32_e32 v5, v163, v191
	v_and_b32_e32 v202, 0xffff0000, v233
	v_and_b32_e32 v200, 0xffff0000, v234
	v_add_f32_e32 v3, 1.0, v3
	v_rcp_f32_e32 v187, v3
	v_add_f32_e32 v3, v151, v189
	v_mul_f32_e32 v3, 0xbfb8aa3b, v3
	v_exp_f32_e32 v3, v3
	v_add_f32_e32 v4, v162, v4
	v_add_f32_e32 v189, v155, v200
	v_mul_f32_e32 v4, 0xbfb8aa3b, v4
	v_add_f32_e32 v3, 1.0, v3
	v_rcp_f32_e32 v191, v3
	v_add_f32_e32 v3, v160, v192
	v_mul_f32_e32 v3, 0xbfb8aa3b, v3
	v_exp_f32_e32 v3, v3
	v_add_f32_e32 v192, v164, v194
	v_mul_f32_e32 v5, 0xbfb8aa3b, v5
	v_mul_f32_e32 v192, 0xbfb8aa3b, v192
	v_add_f32_e32 v3, 1.0, v3
	v_rcp_f32_e32 v194, v3
	v_add_f32_e32 v3, v152, v195
	v_mul_f32_e32 v3, 0xbfb8aa3b, v3
	v_exp_f32_e32 v3, v3
	v_add_f32_e32 v195, v156, v203
	v_exp_f32_e32 v203, v193
	v_mul_f32_e32 v195, 0xbfb8aa3b, v195
	v_exp_f32_e32 v200, v195
	v_add_f32_e32 v195, v165, v202
	v_add_f32_e32 v3, 1.0, v3
	v_mul_f32_e32 v193, 0xbfb8aa3b, v195
	v_exp_f32_e32 v4, v4
	v_exp_f32_e32 v5, v5
	v_exp_f32_e32 v192, v192
	v_exp_f32_e32 v193, v193
	v_rcp_f32_e32 v202, v3
	v_add_f32_e32 v3, 1.0, v203
	v_rcp_f32_e32 v195, v3
	v_pk_add_f32 v[192:193], v[192:193], 1.0 op_sel_hi:[1,0]
	v_pk_add_f32 v[4:5], v[4:5], 1.0 op_sel_hi:[1,0]
	v_and_b32_e32 v201, 0xffff0000, v231
	v_pk_mul_f32 v[4:5], v[4:5], v[186:187]
	v_pk_mul_f32 v[186:187], v[192:193], v[194:195]
	v_and_b32_e32 v225, 0xffff0000, v235
	v_pk_mul_f32 v[68:69], v[68:69], v[186:187]
	v_add_f32_e32 v186, v153, v201
	v_mul_f32_e32 v186, 0xbfb8aa3b, v186
	v_exp_f32_e32 v186, v186
	v_add_f32_e32 v3, v157, v225
	v_mul_f32_e32 v3, 0xbfb8aa3b, v3
	v_exp_f32_e32 v201, v3
	v_add_f32_e32 v3, 1.0, v186
	v_mul_f32_e32 v189, 0xbfb8aa3b, v189
	v_rcp_f32_e32 v203, v3
	s_waitcnt vmcnt(5)
	v_lshlrev_b32_e32 v3, 16, v196
	v_exp_f32_e32 v189, v189
	v_add_f32_e32 v3, v158, v3
	v_mul_f32_e32 v3, 0xbfb8aa3b, v3
	v_exp_f32_e32 v3, v3
	v_pk_add_f32 v[186:187], v[188:189], 1.0 op_sel_hi:[1,0]
	v_pk_mul_f32 v[66:67], v[66:67], v[4:5]
	v_pk_mul_f32 v[186:187], v[186:187], v[190:191]
	v_add_f32_e32 v3, 1.0, v3
	v_pk_mul_f32 v[62:63], v[62:63], v[186:187]
	v_lshlrev_b32_e32 v187, 16, v198
	v_rcp_f32_e32 v186, v3
	v_add_f32_e32 v3, v150, v187
	v_mul_f32_e32 v3, 0xbfb8aa3b, v3
	v_exp_f32_e32 v3, v3
	v_pk_add_f32 v[4:5], v[200:201], 1.0 op_sel_hi:[1,0]
	s_waitcnt vmcnt(4)
	v_lshlrev_b32_e32 v188, 16, v238
	v_pk_mul_f32 v[4:5], v[4:5], v[202:203]
	v_add_f32_e32 v3, 1.0, v3
	v_pk_mul_f32 v[64:65], v[64:65], v[4:5]
	v_and_b32_e32 v5, 0xffff0000, v196
	v_rcp_f32_e32 v190, v3
	v_add_f32_e32 v3, v159, v5
	v_mul_f32_e32 v3, 0xbfb8aa3b, v3
	v_exp_f32_e32 v3, v3
	v_add_f32_e32 v187, v154, v188
	v_and_b32_e32 v189, 0xffff0000, v198
	v_mul_f32_e32 v187, 0xbfb8aa3b, v187
	v_add_f32_e32 v3, 1.0, v3
	v_exp_f32_e32 v188, v187
	v_rcp_f32_e32 v187, v3
	v_add_f32_e32 v3, v151, v189
	v_mul_f32_e32 v3, 0xbfb8aa3b, v3
	v_exp_f32_e32 v3, v3
	v_lshlrev_b32_e32 v192, 16, v197
	v_and_b32_e32 v191, 0xffff0000, v236
	v_add_f32_e32 v5, v163, v191
	v_add_f32_e32 v3, 1.0, v3
	v_rcp_f32_e32 v191, v3
	v_add_f32_e32 v3, v160, v192
	v_mul_f32_e32 v3, 0xbfb8aa3b, v3
	v_exp_f32_e32 v3, v3
	v_lshlrev_b32_e32 v195, 16, v199
	v_lshlrev_b32_e32 v194, 16, v237
	v_and_b32_e32 v193, 0xffff0000, v197
	v_add_f32_e32 v3, 1.0, v3
	v_add_f32_e32 v192, v164, v194
	v_rcp_f32_e32 v194, v3
	v_add_f32_e32 v3, v152, v195
	v_mul_f32_e32 v3, 0xbfb8aa3b, v3
	v_add_f32_e32 v193, v161, v193
	v_and_b32_e32 v197, 0xffff0000, v199
	v_lshlrev_b32_e32 v199, 16, v239
	v_exp_f32_e32 v3, v3
	v_mul_f32_e32 v193, 0xbfb8aa3b, v193
	v_add_f32_e32 v195, v156, v199
	v_exp_f32_e32 v199, v193
	v_lshlrev_b32_e32 v4, 16, v236
	v_and_b32_e32 v198, 0xffff0000, v237
	v_and_b32_e32 v196, 0xffff0000, v238
	v_mul_f32_e32 v195, 0xbfb8aa3b, v195
	v_add_f32_e32 v4, v162, v4
	v_add_f32_e32 v189, v155, v196
	v_exp_f32_e32 v196, v195
	v_add_f32_e32 v195, v165, v198
	v_mul_f32_e32 v4, 0xbfb8aa3b, v4
	v_mul_f32_e32 v5, 0xbfb8aa3b, v5
	v_mul_f32_e32 v192, 0xbfb8aa3b, v192
	v_add_f32_e32 v3, 1.0, v3
	v_mul_f32_e32 v193, 0xbfb8aa3b, v195
	v_exp_f32_e32 v4, v4
	v_exp_f32_e32 v5, v5
	v_exp_f32_e32 v192, v192
	v_exp_f32_e32 v193, v193
	v_rcp_f32_e32 v198, v3
	v_add_f32_e32 v3, 1.0, v199
	v_rcp_f32_e32 v195, v3
	v_pk_add_f32 v[192:193], v[192:193], 1.0 op_sel_hi:[1,0]
	v_pk_add_f32 v[4:5], v[4:5], 1.0 op_sel_hi:[1,0]
	v_and_b32_e32 v200, 0xffff0000, v239
	v_pk_mul_f32 v[4:5], v[4:5], v[186:187]
	v_pk_mul_f32 v[186:187], v[192:193], v[194:195]
	v_add_f32_e32 v3, v157, v200
	v_pk_mul_f32 v[60:61], v[60:61], v[186:187]
	v_add_f32_e32 v186, v153, v197
	v_mul_f32_e32 v186, 0xbfb8aa3b, v186
	v_exp_f32_e32 v186, v186
	v_mul_f32_e32 v3, 0xbfb8aa3b, v3
	v_exp_f32_e32 v197, v3
	v_mul_f32_e32 v189, 0xbfb8aa3b, v189
	v_add_f32_e32 v3, 1.0, v186
	v_rcp_f32_e32 v199, v3
	s_waitcnt vmcnt(3)
; __device__ __forceinline__ void unpack8(const u32x4 w, float (&v)[8]) { v[0] = bf_lo(w.x); v[1] = bf_hi(w.x); v[2] = bf_lo(w.y); v[3] = bf_hi(w.y); v[4] = bf_lo(w.z); v[5] = bf_hi(w.z); v[6] = bf_lo(w.w); v[7] = bf_hi(w.w); }
;     __device__ __forceinline__ void after(int te, f32x4 (&acc)[2][2][4][2], const Unit& u, int wr, int wc, int fr, int fq) const {
;     ...
;                     for (int m = 0; m < 4; ++m) { const size_t r = (size_t)(row0 + ai * HALF + m * 16); gs[m] = *(const u32x4*)(proj + r * LDP + PGS + c); ga[m] = *(const u32x4*)(proj + r * LDP + PGA + c); }
; #pragma unroll
;                     for (int m = 0; m < 4; ++m) { float vs[8], va[8]; unpack8(gs[m], vs); unpack8(ga[m], va);
; #pragma unroll
;                         for (int e = 0; e < 4; ++e) {
;                             acc[ai][bj][m][0][e] *= (1.f + __expf(-(va[e] + a0[e]))) * __builtin_amdgcn_rcpf(1.f + __expf(-(vs[e] + s0[e])));
;                             acc[ai][bj][m][1][e] *= (1.f + __expf(-(va[4 + e] + a1[e]))) * __builtin_amdgcn_rcpf(1.f + __expf(-(vs[4 + e] + s1[e]))); } }
	v_lshlrev_b32_e32 v3, 16, v146
	v_add_f32_e32 v3, v158, v3
	v_exp_f32_e32 v189, v189
	v_mul_f32_e32 v3, 0xbfb8aa3b, v3
	v_exp_f32_e32 v3, v3
	v_pk_mul_f32 v[58:59], v[58:59], v[4:5]
	v_pk_add_f32 v[4:5], v[196:197], 1.0 op_sel_hi:[1,0]
	v_pk_add_f32 v[186:187], v[188:189], 1.0 op_sel_hi:[1,0]
	v_pk_mul_f32 v[4:5], v[4:5], v[198:199]
	v_pk_mul_f32 v[186:187], v[186:187], v[190:191]
	v_pk_mul_f32 v[56:57], v[56:57], v[4:5]
	v_and_b32_e32 v5, 0xffff0000, v146
	v_lshlrev_b32_e32 v146, 16, v148
	v_add_f32_e32 v3, 1.0, v3
	v_pk_mul_f32 v[54:55], v[54:55], v[186:187]
	v_lshlrev_b32_e32 v186, 16, v147
	v_and_b32_e32 v187, 0xffff0000, v147
	v_and_b32_e32 v147, 0xffff0000, v148
	s_waitcnt vmcnt(2)
	v_lshlrev_b32_e32 v4, 16, v142
	v_and_b32_e32 v148, 0xffff0000, v142
	v_rcp_f32_e32 v142, v3
	v_add_f32_e32 v3, v150, v146
	v_mul_f32_e32 v3, 0xbfb8aa3b, v3
	v_exp_f32_e32 v3, v3
	v_lshlrev_b32_e32 v188, 16, v149
	v_and_b32_e32 v189, 0xffff0000, v149
	v_lshlrev_b32_e32 v149, 16, v143
	v_add_f32_e32 v3, 1.0, v3
	v_rcp_f32_e32 v146, v3
	v_add_f32_e32 v3, v159, v5
	v_mul_f32_e32 v3, 0xbfb8aa3b, v3
	v_exp_f32_e32 v3, v3
	v_and_b32_e32 v190, 0xffff0000, v143
	v_lshlrev_b32_e32 v143, 16, v144
	v_add_f32_e32 v143, v154, v143
	v_mul_f32_e32 v143, 0xbfb8aa3b, v143
	v_add_f32_e32 v3, 1.0, v3
	v_and_b32_e32 v191, 0xffff0000, v144
	v_exp_f32_e32 v144, v143
	v_rcp_f32_e32 v143, v3
	v_add_f32_e32 v3, v151, v147
	v_mul_f32_e32 v3, 0xbfb8aa3b, v3
	v_exp_f32_e32 v3, v3
	v_add_f32_e32 v187, v161, v187
	v_lshlrev_b32_e32 v192, 16, v145
	v_mul_f32_e32 v187, 0xbfb8aa3b, v187
	v_add_f32_e32 v3, 1.0, v3
	v_rcp_f32_e32 v147, v3
	v_add_f32_e32 v3, v160, v186
	v_mul_f32_e32 v3, 0xbfb8aa3b, v3
	v_exp_f32_e32 v3, v3
	v_add_f32_e32 v5, v163, v148
	v_add_f32_e32 v148, v164, v149
	v_add_f32_e32 v149, v156, v192
	v_add_f32_e32 v3, 1.0, v3
	v_rcp_f32_e32 v186, v3
	v_add_f32_e32 v3, v152, v188
	v_mul_f32_e32 v3, 0xbfb8aa3b, v3
	v_exp_f32_e32 v3, v3
	v_exp_f32_e32 v187, v187
	v_mul_f32_e32 v149, 0xbfb8aa3b, v149
	v_add_f32_e32 v4, v162, v4
	v_exp_f32_e32 v188, v149
	v_add_f32_e32 v149, v165, v190
	v_mul_f32_e32 v4, 0xbfb8aa3b, v4
	v_mul_f32_e32 v5, 0xbfb8aa3b, v5
	v_mul_f32_e32 v148, 0xbfb8aa3b, v148
	v_add_f32_e32 v3, 1.0, v3
	v_mul_f32_e32 v149, 0xbfb8aa3b, v149
	v_exp_f32_e32 v4, v4
	v_exp_f32_e32 v5, v5
	v_exp_f32_e32 v148, v148
	v_exp_f32_e32 v149, v149
	v_rcp_f32_e32 v190, v3
	v_add_f32_e32 v3, 1.0, v187
	v_rcp_f32_e32 v187, v3
	v_pk_add_f32 v[148:149], v[148:149], 1.0 op_sel_hi:[1,0]
	v_pk_add_f32 v[4:5], v[4:5], 1.0 op_sel_hi:[1,0]
	v_and_b32_e32 v193, 0xffff0000, v145
	v_pk_mul_f32 v[4:5], v[4:5], v[142:143]
	v_pk_mul_f32 v[142:143], v[148:149], v[186:187]
	v_add_f32_e32 v3, v157, v193
	v_pk_mul_f32 v[52:53], v[52:53], v[142:143]
	v_add_f32_e32 v142, v153, v189
	v_mul_f32_e32 v142, 0xbfb8aa3b, v142
	v_mul_f32_e32 v3, 0xbfb8aa3b, v3
	v_exp_f32_e32 v142, v142
	v_exp_f32_e32 v189, v3
	v_pk_mul_f32 v[50:51], v[50:51], v[4:5]
	v_add_f32_e32 v3, 1.0, v142
	v_pk_add_f32 v[4:5], v[188:189], 1.0 op_sel_hi:[1,0]
	global_load_dwordx4 v[186:189], v[218:219], off offset:256
	v_add_f32_e32 v145, v155, v191
	v_rcp_f32_e32 v191, v3
	s_waitcnt vmcnt(2)
	v_lshlrev_b32_e32 v3, 16, v130
	v_mul_f32_e32 v145, 0xbfb8aa3b, v145
	v_add_f32_e32 v3, v158, v3
	v_exp_f32_e32 v145, v145
	v_mul_f32_e32 v3, 0xbfb8aa3b, v3
	v_exp_f32_e32 v3, v3
	v_pk_mul_f32 v[4:5], v[4:5], v[190:191]
	v_pk_add_f32 v[142:143], v[144:145], 1.0 op_sel_hi:[1,0]
	v_pk_mul_f32 v[48:49], v[48:49], v[4:5]
	v_pk_mul_f32 v[142:143], v[142:143], v[146:147]
	v_and_b32_e32 v5, 0xffff0000, v130
	v_lshlrev_b32_e32 v130, 16, v132
	v_add_f32_e32 v3, 1.0, v3
	v_pk_mul_f32 v[46:47], v[46:47], v[142:143]
	v_lshlrev_b32_e32 v142, 16, v131
	v_and_b32_e32 v143, 0xffff0000, v131
	v_and_b32_e32 v131, 0xffff0000, v132
	s_waitcnt vmcnt(1)
	v_lshlrev_b32_e32 v4, 16, v126
	v_and_b32_e32 v132, 0xffff0000, v126
	v_rcp_f32_e32 v126, v3
	v_add_f32_e32 v3, v150, v130
	v_mul_f32_e32 v3, 0xbfb8aa3b, v3
	v_exp_f32_e32 v3, v3
	global_load_dwordx4 v[190:193], v[216:217], off offset:256
	v_lshlrev_b32_e32 v144, 16, v133
	v_and_b32_e32 v145, 0xffff0000, v133
	v_add_f32_e32 v3, 1.0, v3
	v_rcp_f32_e32 v130, v3
	v_add_f32_e32 v3, v159, v5
	v_mul_f32_e32 v3, 0xbfb8aa3b, v3
	v_exp_f32_e32 v3, v3
	v_lshlrev_b32_e32 v133, 16, v127
	v_and_b32_e32 v146, 0xffff0000, v127
	v_lshlrev_b32_e32 v127, 16, v128
	v_add_f32_e32 v127, v154, v127
	v_mul_f32_e32 v127, 0xbfb8aa3b, v127
	v_add_f32_e32 v3, 1.0, v3
	v_and_b32_e32 v147, 0xffff0000, v128
	v_exp_f32_e32 v128, v127
	v_rcp_f32_e32 v127, v3
	v_add_f32_e32 v3, v151, v131
	v_mul_f32_e32 v3, 0xbfb8aa3b, v3
	v_exp_f32_e32 v3, v3
	v_add_f32_e32 v143, v161, v143
	v_lshlrev_b32_e32 v148, 16, v129
	v_mul_f32_e32 v143, 0xbfb8aa3b, v143
	v_add_f32_e32 v3, 1.0, v3
	v_rcp_f32_e32 v131, v3
	v_add_f32_e32 v3, v160, v142
	v_mul_f32_e32 v3, 0xbfb8aa3b, v3
	v_exp_f32_e32 v3, v3
	v_add_f32_e32 v5, v163, v132
	v_add_f32_e32 v132, v164, v133
	v_add_f32_e32 v133, v156, v148
	v_add_f32_e32 v3, 1.0, v3
	v_rcp_f32_e32 v142, v3
	v_add_f32_e32 v3, v152, v144
	v_mul_f32_e32 v3, 0xbfb8aa3b, v3
	v_exp_f32_e32 v3, v3
	v_exp_f32_e32 v143, v143
	v_mul_f32_e32 v133, 0xbfb8aa3b, v133
	v_add_f32_e32 v4, v162, v4
	v_exp_f32_e32 v144, v133
	v_add_f32_e32 v133, v165, v146
	v_mul_f32_e32 v4, 0xbfb8aa3b, v4
	v_mul_f32_e32 v5, 0xbfb8aa3b, v5
	v_mul_f32_e32 v132, 0xbfb8aa3b, v132
	v_add_f32_e32 v3, 1.0, v3
	v_mul_f32_e32 v133, 0xbfb8aa3b, v133
	v_exp_f32_e32 v4, v4
	v_exp_f32_e32 v5, v5
	v_exp_f32_e32 v132, v132
	v_exp_f32_e32 v133, v133
	v_rcp_f32_e32 v146, v3
	v_add_f32_e32 v3, 1.0, v143
	v_rcp_f32_e32 v143, v3
	v_pk_add_f32 v[132:133], v[132:133], 1.0 op_sel_hi:[1,0]
	v_pk_add_f32 v[4:5], v[4:5], 1.0 op_sel_hi:[1,0]
	v_and_b32_e32 v149, 0xffff0000, v129
	v_pk_mul_f32 v[4:5], v[4:5], v[126:127]
	v_pk_mul_f32 v[126:127], v[132:133], v[142:143]
	v_add_f32_e32 v129, v155, v147
	v_pk_mul_f32 v[44:45], v[44:45], v[126:127]
	v_add_f32_e32 v126, v153, v145
	v_mul_f32_e32 v126, 0xbfb8aa3b, v126
	v_exp_f32_e32 v126, v126
	v_mul_f32_e32 v129, 0xbfb8aa3b, v129
	v_add_f32_e32 v3, v157, v149
	v_exp_f32_e32 v129, v129
	v_mul_f32_e32 v3, 0xbfb8aa3b, v3
	v_exp_f32_e32 v145, v3
	v_add_f32_e32 v3, 1.0, v126
	v_rcp_f32_e32 v147, v3
	v_pk_add_f32 v[126:127], v[128:129], 1.0 op_sel_hi:[1,0]
	v_pk_mul_f32 v[42:43], v[42:43], v[4:5]
	v_pk_add_f32 v[4:5], v[144:145], 1.0 op_sel_hi:[1,0]
	v_pk_mul_f32 v[126:127], v[126:127], v[130:131]
	v_pk_mul_f32 v[4:5], v[4:5], v[146:147]
	v_pk_mul_f32 v[38:39], v[38:39], v[126:127]
	global_load_dwordx4 v[194:197], v[204:205], off offset:256
	global_load_dwordx4 v[198:201], v[206:207], off offset:256
	global_load_dwordx4 v[146:149], v[208:209], off offset:256
	global_load_dwordx4 v[142:145], v[210:211], off offset:256
	global_load_dwordx4 v[130:133], v[212:213], off offset:256
	global_load_dwordx4 v[126:129], v[214:215], off offset:256
	s_waitcnt vmcnt(7)
; __device__ __forceinline__ void unpack8(const u32x4 w, float (&v)[8]) { v[0] = bf_lo(w.x); v[1] = bf_hi(w.x); v[2] = bf_lo(w.y); v[3] = bf_hi(w.y); v[4] = bf_lo(w.z); v[5] = bf_hi(w.z); v[6] = bf_lo(w.w); v[7] = bf_hi(w.w); }
;     __device__ __forceinline__ void after(int te, f32x4 (&acc)[2][2][4][2], const Unit& u, int wr, int wc, int fr, int fq) const {
;     ...
;                     for (int m = 0; m < 4; ++m) { const size_t r = (size_t)(row0 + ai * HALF + m * 16); gs[m] = *(const u32x4*)(proj + r * LDP + PGS + c); ga[m] = *(const u32x4*)(proj + r * LDP + PGA + c); }
; #pragma unroll
;                     for (int m = 0; m < 4; ++m) { float vs[8], va[8]; unpack8(gs[m], vs); unpack8(ga[m], va);
; #pragma unroll
;                         for (int e = 0; e < 4; ++e) {
;                             acc[ai][bj][m][0][e] *= (1.f + __expf(-(va[e] + a0[e]))) * __builtin_amdgcn_rcpf(1.f + __expf(-(vs[e] + s0[e])));
;                             acc[ai][bj][m][1][e] *= (1.f + __expf(-(va[4 + e] + a1[e]))) * __builtin_amdgcn_rcpf(1.f + __expf(-(vs[4 + e] + s1[e]))); } }
	v_lshlrev_b32_e32 v3, 16, v186
	v_add_f32_e32 v3, v158, v3
	v_mul_f32_e32 v3, 0xbfb8aa3b, v3
	v_exp_f32_e32 v3, v3
	v_lshlrev_b32_e32 v202, 16, v187
	v_and_b32_e32 v203, 0xffff0000, v187
	v_lshlrev_b32_e32 v187, 16, v188
	v_add_f32_e32 v3, 1.0, v3
	v_pk_mul_f32 v[40:41], v[40:41], v[4:5]
	v_and_b32_e32 v5, 0xffff0000, v186
	v_rcp_f32_e32 v186, v3
	v_add_f32_e32 v3, v150, v187
	v_mul_f32_e32 v3, 0xbfb8aa3b, v3
	v_exp_f32_e32 v3, v3
	v_lshlrev_b32_e32 v205, 16, v189
	v_and_b32_e32 v207, 0xffff0000, v189
	s_waitcnt vmcnt(6)
	v_lshlrev_b32_e32 v4, 16, v190
	v_add_f32_e32 v3, 1.0, v3
	v_and_b32_e32 v189, 0xffff0000, v190
	v_rcp_f32_e32 v190, v3
	v_add_f32_e32 v3, v159, v5
	v_mul_f32_e32 v3, 0xbfb8aa3b, v3
	v_exp_f32_e32 v3, v3
	v_and_b32_e32 v204, 0xffff0000, v188
	v_lshlrev_b32_e32 v188, 16, v192
	v_add_f32_e32 v187, v154, v188
	v_mul_f32_e32 v187, 0xbfb8aa3b, v187
	v_add_f32_e32 v3, 1.0, v3
	v_exp_f32_e32 v188, v187
	v_rcp_f32_e32 v187, v3
	v_add_f32_e32 v3, v151, v204
	v_mul_f32_e32 v3, 0xbfb8aa3b, v3
	v_exp_f32_e32 v3, v3
	v_lshlrev_b32_e32 v206, 16, v191
	v_and_b32_e32 v208, 0xffff0000, v191
	v_and_b32_e32 v191, 0xffff0000, v192
	v_add_f32_e32 v3, 1.0, v3
	v_add_f32_e32 v5, v163, v189
	v_add_f32_e32 v189, v155, v191
	v_rcp_f32_e32 v191, v3
	v_add_f32_e32 v3, v160, v202
	v_mul_f32_e32 v3, 0xbfb8aa3b, v3
	v_exp_f32_e32 v3, v3
	v_add_f32_e32 v203, v161, v203
	v_lshlrev_b32_e32 v209, 16, v193
	v_mul_f32_e32 v203, 0xbfb8aa3b, v203
	v_add_f32_e32 v3, 1.0, v3
	v_rcp_f32_e32 v202, v3
	v_add_f32_e32 v3, v152, v205
	v_mul_f32_e32 v3, 0xbfb8aa3b, v3
	v_exp_f32_e32 v3, v3
	v_and_b32_e32 v210, 0xffff0000, v193
	v_add_f32_e32 v193, v156, v209
	v_exp_f32_e32 v203, v203
	v_mul_f32_e32 v193, 0xbfb8aa3b, v193
	v_add_f32_e32 v4, v162, v4
	v_add_f32_e32 v192, v164, v206
	v_exp_f32_e32 v204, v193
	v_add_f32_e32 v193, v165, v208
	v_mul_f32_e32 v4, 0xbfb8aa3b, v4
	v_mul_f32_e32 v5, 0xbfb8aa3b, v5
	v_mul_f32_e32 v192, 0xbfb8aa3b, v192
	v_add_f32_e32 v3, 1.0, v3
	v_mul_f32_e32 v193, 0xbfb8aa3b, v193
	v_exp_f32_e32 v4, v4
	v_exp_f32_e32 v5, v5
	v_exp_f32_e32 v192, v192
	v_exp_f32_e32 v193, v193
	v_rcp_f32_e32 v206, v3
	v_add_f32_e32 v3, 1.0, v203
	v_rcp_f32_e32 v203, v3
	v_pk_add_f32 v[192:193], v[192:193], 1.0 op_sel_hi:[1,0]
	v_pk_add_f32 v[4:5], v[4:5], 1.0 op_sel_hi:[1,0]
	v_add_f32_e32 v3, v157, v210
	v_pk_mul_f32 v[4:5], v[4:5], v[186:187]
	v_pk_mul_f32 v[186:187], v[192:193], v[202:203]
	v_mul_f32_e32 v3, 0xbfb8aa3b, v3
	v_pk_mul_f32 v[36:37], v[36:37], v[186:187]
	v_add_f32_e32 v186, v153, v207
	v_mul_f32_e32 v186, 0xbfb8aa3b, v186
	v_exp_f32_e32 v186, v186
	v_exp_f32_e32 v205, v3
	v_mul_f32_e32 v189, 0xbfb8aa3b, v189
	v_exp_f32_e32 v189, v189
	v_add_f32_e32 v3, 1.0, v186
	v_rcp_f32_e32 v207, v3
	s_waitcnt vmcnt(5)
	v_lshlrev_b32_e32 v3, 16, v194
	v_add_f32_e32 v3, v158, v3
	v_mul_f32_e32 v3, 0xbfb8aa3b, v3
	v_exp_f32_e32 v3, v3
	v_pk_add_f32 v[186:187], v[188:189], 1.0 op_sel_hi:[1,0]
	v_pk_mul_f32 v[34:35], v[34:35], v[4:5]
	v_pk_mul_f32 v[186:187], v[186:187], v[190:191]
	v_add_f32_e32 v3, 1.0, v3
	v_pk_mul_f32 v[30:31], v[30:31], v[186:187]
	v_lshlrev_b32_e32 v187, 16, v196
	v_rcp_f32_e32 v186, v3
	v_add_f32_e32 v3, v150, v187
	v_mul_f32_e32 v3, 0xbfb8aa3b, v3
	v_exp_f32_e32 v3, v3
	v_pk_add_f32 v[4:5], v[204:205], 1.0 op_sel_hi:[1,0]
	s_waitcnt vmcnt(4)
	v_lshlrev_b32_e32 v188, 16, v200
	v_pk_mul_f32 v[4:5], v[4:5], v[206:207]
	v_add_f32_e32 v3, 1.0, v3
	v_pk_mul_f32 v[32:33], v[32:33], v[4:5]
	v_and_b32_e32 v5, 0xffff0000, v194
	v_rcp_f32_e32 v190, v3
	v_add_f32_e32 v3, v159, v5
	v_mul_f32_e32 v3, 0xbfb8aa3b, v3
	v_exp_f32_e32 v3, v3
	v_add_f32_e32 v187, v154, v188
	v_and_b32_e32 v189, 0xffff0000, v196
	v_mul_f32_e32 v187, 0xbfb8aa3b, v187
	v_add_f32_e32 v3, 1.0, v3
	v_exp_f32_e32 v188, v187
	v_rcp_f32_e32 v187, v3
	v_add_f32_e32 v3, v151, v189
	v_mul_f32_e32 v3, 0xbfb8aa3b, v3
	v_exp_f32_e32 v3, v3
	v_lshlrev_b32_e32 v192, 16, v195
	v_and_b32_e32 v191, 0xffff0000, v198
	v_add_f32_e32 v5, v163, v191
	v_add_f32_e32 v3, 1.0, v3
	v_rcp_f32_e32 v191, v3
	v_add_f32_e32 v3, v160, v192
	v_mul_f32_e32 v3, 0xbfb8aa3b, v3
	v_exp_f32_e32 v3, v3
	v_and_b32_e32 v193, 0xffff0000, v195
	v_lshlrev_b32_e32 v195, 16, v197
	v_lshlrev_b32_e32 v194, 16, v199
	v_add_f32_e32 v3, 1.0, v3
	v_add_f32_e32 v192, v164, v194
	v_rcp_f32_e32 v194, v3
	v_add_f32_e32 v3, v152, v195
	v_mul_f32_e32 v3, 0xbfb8aa3b, v3
	v_add_f32_e32 v193, v161, v193
	v_lshlrev_b32_e32 v4, 16, v198
	v_and_b32_e32 v198, 0xffff0000, v199
	v_lshlrev_b32_e32 v199, 16, v201
	v_exp_f32_e32 v3, v3
	v_mul_f32_e32 v193, 0xbfb8aa3b, v193
	v_add_f32_e32 v195, v156, v199
	v_exp_f32_e32 v199, v193
	v_and_b32_e32 v196, 0xffff0000, v200
	v_mul_f32_e32 v195, 0xbfb8aa3b, v195
	v_add_f32_e32 v4, v162, v4
	v_add_f32_e32 v189, v155, v196
	v_exp_f32_e32 v196, v195
	v_add_f32_e32 v195, v165, v198
	v_mul_f32_e32 v4, 0xbfb8aa3b, v4
	v_mul_f32_e32 v5, 0xbfb8aa3b, v5
	v_mul_f32_e32 v192, 0xbfb8aa3b, v192
	v_add_f32_e32 v3, 1.0, v3
	v_mul_f32_e32 v193, 0xbfb8aa3b, v195
	v_exp_f32_e32 v4, v4
	v_exp_f32_e32 v5, v5
	v_exp_f32_e32 v192, v192
	v_exp_f32_e32 v193, v193
	v_rcp_f32_e32 v198, v3
	v_add_f32_e32 v3, 1.0, v199
	v_rcp_f32_e32 v195, v3
	v_pk_add_f32 v[192:193], v[192:193], 1.0 op_sel_hi:[1,0]
	v_pk_add_f32 v[4:5], v[4:5], 1.0 op_sel_hi:[1,0]
	v_and_b32_e32 v197, 0xffff0000, v197
	v_pk_mul_f32 v[4:5], v[4:5], v[186:187]
	v_pk_mul_f32 v[186:187], v[192:193], v[194:195]
	v_and_b32_e32 v200, 0xffff0000, v201
	v_pk_mul_f32 v[28:29], v[28:29], v[186:187]
	v_add_f32_e32 v186, v153, v197
	v_mul_f32_e32 v186, 0xbfb8aa3b, v186
	v_exp_f32_e32 v186, v186
	v_add_f32_e32 v3, v157, v200
	v_mul_f32_e32 v3, 0xbfb8aa3b, v3
	v_exp_f32_e32 v197, v3
	v_add_f32_e32 v3, 1.0, v186
	v_rcp_f32_e32 v199, v3
	s_waitcnt vmcnt(3)
; __device__ __forceinline__ void unpack8(const u32x4 w, float (&v)[8]) { v[0] = bf_lo(w.x); v[1] = bf_hi(w.x); v[2] = bf_lo(w.y); v[3] = bf_hi(w.y); v[4] = bf_lo(w.z); v[5] = bf_hi(w.z); v[6] = bf_lo(w.w); v[7] = bf_hi(w.w); }
;     __device__ __forceinline__ void after(int te, f32x4 (&acc)[2][2][4][2], const Unit& u, int wr, int wc, int fr, int fq) const {
;     ...
;         if (g == 7) {
;             const int row0 = u.pm * BM + wr * 64 + fr, col0 = u.pn * BM + wc * 32 + 8 * fq;
; #pragma unroll
;             for (int bj = 0; bj < 2; ++bj) { const int c = col0 + bj * HALF;
;                 const f32x4 s0 = *(const f32x4*)(gb + c), s1 = *(const f32x4*)(gb + c + 4), a0 = *(const f32x4*)(gb + D_MODEL + c), a1 = *(const f32x4*)(gb + D_MODEL + c + 4);
; #pragma unroll
;                 for (int ai = 0; ai < 2; ++ai) {
;                     u32x4 gs[4], ga[4];
; #pragma unroll
;                     for (int m = 0; m < 4; ++m) { const size_t r = (size_t)(row0 + ai * HALF + m * 16); gs[m] = *(const u32x4*)(proj + r * LDP + PGS + c); ga[m] = *(const u32x4*)(proj + r * LDP + PGA + c); }
; #pragma unroll
;                     for (int m = 0; m < 4; ++m) { float vs[8], va[8]; unpack8(gs[m], vs); unpack8(ga[m], va);
; #pragma unroll
;                         for (int e = 0; e < 4; ++e) {
;                             acc[ai][bj][m][0][e] *= (1.f + __expf(-(va[e] + a0[e]))) * __builtin_amdgcn_rcpf(1.f + __expf(-(vs[e] + s0[e])));
;                             acc[ai][bj][m][1][e] *= (1.f + __expf(-(va[4 + e] + a1[e]))) * __builtin_amdgcn_rcpf(1.f + __expf(-(vs[4 + e] + s1[e]))); } }
;                     asm volatile("" ::: "memory");
;                 } }
	v_lshlrev_b32_e32 v3, 16, v146
	v_mul_f32_e32 v189, 0xbfb8aa3b, v189
	v_add_f32_e32 v3, v158, v3
	v_exp_f32_e32 v189, v189
	v_mul_f32_e32 v3, 0xbfb8aa3b, v3
	v_exp_f32_e32 v3, v3
	v_pk_mul_f32 v[26:27], v[26:27], v[4:5]
	v_pk_add_f32 v[4:5], v[196:197], 1.0 op_sel_hi:[1,0]
	v_pk_add_f32 v[186:187], v[188:189], 1.0 op_sel_hi:[1,0]
	v_pk_mul_f32 v[4:5], v[4:5], v[198:199]
	v_pk_mul_f32 v[186:187], v[186:187], v[190:191]
	v_pk_mul_f32 v[24:25], v[24:25], v[4:5]
	v_and_b32_e32 v5, 0xffff0000, v146
	v_lshlrev_b32_e32 v146, 16, v148
	v_add_f32_e32 v3, 1.0, v3
	v_pk_mul_f32 v[22:23], v[22:23], v[186:187]
	v_lshlrev_b32_e32 v186, 16, v147
	v_and_b32_e32 v187, 0xffff0000, v147
	v_and_b32_e32 v147, 0xffff0000, v148
	s_waitcnt vmcnt(2)
	v_lshlrev_b32_e32 v4, 16, v142
	v_and_b32_e32 v148, 0xffff0000, v142
	v_rcp_f32_e32 v142, v3
	v_add_f32_e32 v3, v150, v146
	v_mul_f32_e32 v3, 0xbfb8aa3b, v3
	v_exp_f32_e32 v3, v3
	v_lshlrev_b32_e32 v188, 16, v149
	v_and_b32_e32 v189, 0xffff0000, v149
	v_lshlrev_b32_e32 v149, 16, v143
	v_add_f32_e32 v3, 1.0, v3
	v_rcp_f32_e32 v146, v3
	v_add_f32_e32 v3, v159, v5
	v_mul_f32_e32 v3, 0xbfb8aa3b, v3
	v_exp_f32_e32 v3, v3
	v_and_b32_e32 v190, 0xffff0000, v143
	v_lshlrev_b32_e32 v143, 16, v144
	v_add_f32_e32 v143, v154, v143
	v_mul_f32_e32 v143, 0xbfb8aa3b, v143
	v_add_f32_e32 v3, 1.0, v3
	v_and_b32_e32 v191, 0xffff0000, v144
	v_exp_f32_e32 v144, v143
	v_rcp_f32_e32 v143, v3
	v_add_f32_e32 v3, v151, v147
	v_mul_f32_e32 v3, 0xbfb8aa3b, v3
	v_exp_f32_e32 v3, v3
	v_add_f32_e32 v187, v161, v187
	v_lshlrev_b32_e32 v192, 16, v145
	v_mul_f32_e32 v187, 0xbfb8aa3b, v187
	v_add_f32_e32 v3, 1.0, v3
	v_rcp_f32_e32 v147, v3
	v_add_f32_e32 v3, v160, v186
	v_mul_f32_e32 v3, 0xbfb8aa3b, v3
	v_exp_f32_e32 v3, v3
	v_add_f32_e32 v5, v163, v148
	v_add_f32_e32 v148, v164, v149
	v_add_f32_e32 v149, v156, v192
	v_add_f32_e32 v3, 1.0, v3
	v_rcp_f32_e32 v186, v3
	v_add_f32_e32 v3, v152, v188
	v_mul_f32_e32 v3, 0xbfb8aa3b, v3
	v_exp_f32_e32 v3, v3
	v_exp_f32_e32 v187, v187
	v_mul_f32_e32 v149, 0xbfb8aa3b, v149
	v_add_f32_e32 v4, v162, v4
	v_exp_f32_e32 v188, v149
	v_add_f32_e32 v149, v165, v190
	v_mul_f32_e32 v4, 0xbfb8aa3b, v4
	v_mul_f32_e32 v5, 0xbfb8aa3b, v5
	v_mul_f32_e32 v148, 0xbfb8aa3b, v148
	v_add_f32_e32 v3, 1.0, v3
	v_mul_f32_e32 v149, 0xbfb8aa3b, v149
	v_exp_f32_e32 v4, v4
	v_exp_f32_e32 v5, v5
	v_exp_f32_e32 v148, v148
	v_exp_f32_e32 v149, v149
	v_rcp_f32_e32 v190, v3
	v_add_f32_e32 v3, 1.0, v187
	v_rcp_f32_e32 v187, v3
	v_pk_add_f32 v[148:149], v[148:149], 1.0 op_sel_hi:[1,0]
	v_pk_add_f32 v[4:5], v[4:5], 1.0 op_sel_hi:[1,0]
	v_and_b32_e32 v193, 0xffff0000, v145
	v_pk_mul_f32 v[4:5], v[4:5], v[142:143]
	v_pk_mul_f32 v[142:143], v[148:149], v[186:187]
	v_add_f32_e32 v3, v157, v193
	v_pk_mul_f32 v[20:21], v[20:21], v[142:143]
	v_add_f32_e32 v142, v153, v189
	v_mul_f32_e32 v142, 0xbfb8aa3b, v142
	v_exp_f32_e32 v142, v142
	v_mul_f32_e32 v3, 0xbfb8aa3b, v3
	v_exp_f32_e32 v189, v3
	v_add_f32_e32 v145, v155, v191
	v_add_f32_e32 v3, 1.0, v142
	v_rcp_f32_e32 v191, v3
	s_waitcnt vmcnt(1)
	v_lshlrev_b32_e32 v3, 16, v130
	v_mul_f32_e32 v145, 0xbfb8aa3b, v145
	v_add_f32_e32 v3, v158, v3
	v_exp_f32_e32 v145, v145
	v_mul_f32_e32 v3, 0xbfb8aa3b, v3
	v_exp_f32_e32 v3, v3
	v_pk_mul_f32 v[18:19], v[18:19], v[4:5]
	v_pk_add_f32 v[4:5], v[188:189], 1.0 op_sel_hi:[1,0]
	v_pk_add_f32 v[142:143], v[144:145], 1.0 op_sel_hi:[1,0]
	v_pk_mul_f32 v[4:5], v[4:5], v[190:191]
	v_pk_mul_f32 v[142:143], v[142:143], v[146:147]
	v_pk_mul_f32 v[16:17], v[16:17], v[4:5]
	v_and_b32_e32 v5, 0xffff0000, v130
	v_lshlrev_b32_e32 v130, 16, v132
	v_add_f32_e32 v3, 1.0, v3
	v_pk_mul_f32 v[14:15], v[14:15], v[142:143]
	v_lshlrev_b32_e32 v142, 16, v131
	v_and_b32_e32 v143, 0xffff0000, v131
	v_and_b32_e32 v131, 0xffff0000, v132
	s_waitcnt vmcnt(0)
	v_lshlrev_b32_e32 v4, 16, v126
	v_and_b32_e32 v132, 0xffff0000, v126
	v_rcp_f32_e32 v126, v3
	v_add_f32_e32 v3, v150, v130
	v_mul_f32_e32 v3, 0xbfb8aa3b, v3
	v_exp_f32_e32 v3, v3
	v_lshlrev_b32_e32 v144, 16, v133
	v_and_b32_e32 v145, 0xffff0000, v133
	v_lshlrev_b32_e32 v133, 16, v127
	v_add_f32_e32 v3, 1.0, v3
	v_rcp_f32_e32 v130, v3
	v_add_f32_e32 v3, v159, v5
	v_mul_f32_e32 v3, 0xbfb8aa3b, v3
	v_exp_f32_e32 v3, v3
	v_and_b32_e32 v146, 0xffff0000, v127
	v_lshlrev_b32_e32 v127, 16, v128
	v_add_f32_e32 v127, v154, v127
	v_mul_f32_e32 v127, 0xbfb8aa3b, v127
	v_add_f32_e32 v3, 1.0, v3
	v_and_b32_e32 v147, 0xffff0000, v128
	v_exp_f32_e32 v128, v127
	v_rcp_f32_e32 v127, v3
	v_add_f32_e32 v3, v151, v131
	v_mul_f32_e32 v3, 0xbfb8aa3b, v3
	v_exp_f32_e32 v3, v3
	v_add_f32_e32 v143, v161, v143
	v_lshlrev_b32_e32 v148, 16, v129
	v_mul_f32_e32 v143, 0xbfb8aa3b, v143
	v_add_f32_e32 v3, 1.0, v3
	v_rcp_f32_e32 v131, v3
	v_add_f32_e32 v3, v160, v142
	v_mul_f32_e32 v3, 0xbfb8aa3b, v3
	v_exp_f32_e32 v3, v3
	v_add_f32_e32 v5, v163, v132
	v_add_f32_e32 v132, v164, v133
	v_add_f32_e32 v133, v156, v148
	v_add_f32_e32 v3, 1.0, v3
	v_rcp_f32_e32 v142, v3
	v_add_f32_e32 v3, v152, v144
	v_mul_f32_e32 v3, 0xbfb8aa3b, v3
	v_exp_f32_e32 v3, v3
	v_exp_f32_e32 v143, v143
	v_mul_f32_e32 v133, 0xbfb8aa3b, v133
	v_add_f32_e32 v4, v162, v4
	v_exp_f32_e32 v144, v133
	v_add_f32_e32 v133, v165, v146
	v_mul_f32_e32 v4, 0xbfb8aa3b, v4
	v_mul_f32_e32 v5, 0xbfb8aa3b, v5
	v_mul_f32_e32 v132, 0xbfb8aa3b, v132
	v_add_f32_e32 v3, 1.0, v3
	v_mul_f32_e32 v133, 0xbfb8aa3b, v133
	v_exp_f32_e32 v4, v4
	v_exp_f32_e32 v5, v5
	v_exp_f32_e32 v132, v132
	v_exp_f32_e32 v133, v133
	v_rcp_f32_e32 v146, v3
	v_add_f32_e32 v3, 1.0, v143
	v_rcp_f32_e32 v143, v3
	v_pk_add_f32 v[132:133], v[132:133], 1.0 op_sel_hi:[1,0]
	v_pk_add_f32 v[4:5], v[4:5], 1.0 op_sel_hi:[1,0]
	v_and_b32_e32 v149, 0xffff0000, v129
	v_pk_mul_f32 v[4:5], v[4:5], v[126:127]
	v_pk_mul_f32 v[126:127], v[132:133], v[142:143]
	v_add_f32_e32 v129, v155, v147
	v_pk_mul_f32 v[12:13], v[12:13], v[126:127]
	v_add_f32_e32 v126, v153, v145
	v_mul_f32_e32 v126, 0xbfb8aa3b, v126
	v_exp_f32_e32 v126, v126
	v_add_f32_e32 v3, v157, v149
	v_mul_f32_e32 v129, 0xbfb8aa3b, v129
	v_mul_f32_e32 v3, 0xbfb8aa3b, v3
	v_exp_f32_e32 v129, v129
	v_exp_f32_e32 v145, v3
	v_add_f32_e32 v3, 1.0, v126
	v_rcp_f32_e32 v147, v3
	v_pk_mul_f32 v[10:11], v[10:11], v[4:5]
	v_pk_add_f32 v[4:5], v[144:145], 1.0 op_sel_hi:[1,0]
	v_pk_add_f32 v[126:127], v[128:129], 1.0 op_sel_hi:[1,0]
	v_pk_mul_f32 v[4:5], v[4:5], v[146:147]
	v_pk_mul_f32 v[126:127], v[126:127], v[130:131]
	v_pk_mul_f32 v[8:9], v[8:9], v[4:5]
	v_pk_mul_f32 v[6:7], v[6:7], v[126:127]

; #define PG8_STAGE(bufoff, gbase, voff) do { _Pragma("unroll") for (int _i = 0; _i < 2; ++_i) \
;         __builtin_amdgcn_global_load_lds((const unsigned*)((const char*)(gbase) + (voff)[_i]), (LAS unsigned*)(lds + (bufoff) + ldsw + _i * 8192), 16, 0, 0); } while (0)
; #define PG8_LDA(dst, b, h) do { _Pragma("unroll") for (int m = 0; m < 4; ++m) _Pragma("unroll") for (int k = 0; k < 2; ++k) dst[m][k] = *(const LAS bf16x8*)(lds + PG8_SA(b, h) + aoff + m * 2048 + k * 1024); } while (0)
; #define PG8_LDB(dst, b, h) do { _Pragma("unroll") for (int n = 0; n < 2; ++n) _Pragma("unroll") for (int k = 0; k < 2; ++k) dst[n][k] = *(const LAS bf16x8*)(lds + PG8_SB(b, h) + boff + n * 2048 + k * 1024); } while (0)
; #define PG8_MMA(ai, bj, At, Bt) do { __builtin_amdgcn_s_setprio(1); _Pragma("unroll") for (int m = 0; m < 4; ++m) _Pragma("unroll") for (int n = 0; n < 2; ++n) _Pragma("unroll") for (int k = 0; k < 2; ++k) \
;         acc[ai][bj][m][n] = __builtin_amdgcn_mfma_f32_16x16x32_bf16(Bt[n][k], At[m][k], acc[ai][bj][m][n], 0, 0, 0); __builtin_amdgcn_s_setprio(0); } while (0)
; #define PG8_WAIT_V(n) asm volatile("s_waitcnt vmcnt(" #n ")" ::: "memory")
; #define PG8_WAIT_L(n) asm volatile("s_waitcnt lgkmcnt(" #n ")" ::: "memory")
; template <class Epi, class Sched, bool ALIGN_EPI, class Hook = NoHook>
; __device__ __forceinline__ void gemm_phase(LAS unsigned char* lds, const Gemm g, const Sched& S, const Epi& E, const Hook& H = Hook()) {
;     ...
;         for (int t = tb; t < te; t += 2) {
;             const bool last = (t == nt - 2);
;             const char* a1 = cA + (size_t)(t + 1) * kstep;
;             const char* a2 = last ? nA : cA + (size_t)(t + 2) * kstep; const char* b2 = last ? nB : cB + (size_t)(t + 2) * kstep;
;             const char* a3 = a2 + kstep; const char* b3 = b2 + kstep;
;             if (last && has_next) S.a_ready(nxt);
;             PG8_LDB(B0, 0, 0); PG8_LDB(B1, 0, 1); PG8_SCHED; PG8_LDA(At, 0, 0); PG8_STAGE(PG8_SA(1, 1), a1 + hA, voffA);
;             PG8_WAIT_V(8); PG8_WAIT_L(0); PG8_BAR; PG8_MMA(0, 0, At, B0); PG8_MMA(0, 1, At, B1); PG8_BAR; PG8_SCHED;
;             PG8_LDA(At, 0, 1); PG8_STAGE(PG8_SB(0, 0), b2, voffB); PG8_STAGE(PG8_SB(0, 1), b2 + hB, voffB); PG8_STAGE(PG8_SA(0, 0), a2, voffA);
;             PG8_WAIT_V(8); PG8_WAIT_L(0); PG8_BAR; PG8_MMA(1, 0, At, B0); PG8_MMA(1, 1, At, B1); PG8_BAR; PG8_SCHED;
.LBB0_850:
	ds_read_b128 v[146:149], v1
	ds_read_b128 v[150:153], v1 offset:1024
	s_add_u32 s20, s6, 0x87c00080
	s_addc_u32 s21, s7, -1
	s_cmp_lg_u32 s42, 60
	s_cselect_b32 s20, s20, 0
	s_cselect_b32 s21, s21, 0
	s_add_u32 s22, s2, s20
	s_addc_u32 s23, s3, s21
	s_add_u32 s20, s14, s20
	s_addc_u32 s21, s15, s21
	s_mov_b32 m0, s43
	ds_read_b128 v[154:157], v1 offset:2048
	ds_read_b128 v[158:161], v1 offset:3072
	ds_read_b128 v[162:165], v142
	ds_read_b128 v[166:169], v142 offset:1024
	ds_read_b128 v[170:173], v142 offset:2048
	ds_read_b128 v[174:177], v142 offset:3072
	v_lshl_add_u64 v[178:179], v[138:139], 0, s[6:7]
	global_load_lds_dwordx4 v[178:179], off
	ds_read_b128 v[186:189], v143
	ds_read_b128 v[190:193], v143 offset:1024
	ds_read_b128 v[194:197], v143 offset:2048
	ds_read_b128 v[198:201], v143 offset:3072
	ds_read_b128 v[202:205], v143 offset:4096
	ds_read_b128 v[206:209], v143 offset:5120
	ds_read_b128 v[210:213], v143 offset:6144
	ds_read_b128 v[214:217], v143 offset:7168
	v_lshl_add_u64 v[178:179], v[140:141], 0, s[6:7]
	s_mov_b32 m0, s44
	s_nop 0
	global_load_lds_dwordx4 v[178:179], off
	s_waitcnt vmcnt(8) lgkmcnt(0)
	s_barrier
	s_setprio 1
	v_mfma_f32_16x16x32_bf16 v[54:57], v[146:149], v[186:189], v[54:57]
	v_mfma_f32_16x16x32_bf16 v[34:37], v[154:157], v[186:189], v[34:37]
	v_mfma_f32_16x16x32_bf16 v[42:45], v[146:149], v[194:197], v[42:45]
	v_mfma_f32_16x16x32_bf16 v[30:33], v[154:157], v[194:197], v[30:33]
	v_mfma_f32_16x16x32_bf16 v[62:65], v[146:149], v[202:205], v[62:65]
	v_mfma_f32_16x16x32_bf16 v[50:53], v[154:157], v[202:205], v[50:53]
	v_mfma_f32_16x16x32_bf16 v[78:81], v[146:149], v[210:213], v[78:81]
	v_mfma_f32_16x16x32_bf16 v[70:73], v[154:157], v[210:213], v[70:73]
	v_mfma_f32_16x16x32_bf16 v[54:57], v[150:153], v[190:193], v[54:57]
	v_mfma_f32_16x16x32_bf16 v[34:37], v[158:161], v[190:193], v[34:37]
	v_mfma_f32_16x16x32_bf16 v[42:45], v[150:153], v[198:201], v[42:45]
	v_mfma_f32_16x16x32_bf16 v[30:33], v[158:161], v[198:201], v[30:33]
	v_mfma_f32_16x16x32_bf16 v[62:65], v[150:153], v[206:209], v[62:65]
	v_mfma_f32_16x16x32_bf16 v[50:53], v[158:161], v[206:209], v[50:53]
	v_mfma_f32_16x16x32_bf16 v[78:81], v[150:153], v[214:217], v[78:81]
	v_mfma_f32_16x16x32_bf16 v[70:73], v[158:161], v[214:217], v[70:73]
	v_mfma_f32_16x16x32_bf16 v[10:13], v[162:165], v[186:189], v[10:13]
	v_mfma_f32_16x16x32_bf16 v[2:5], v[170:173], v[186:189], v[2:5]
	v_mfma_f32_16x16x32_bf16 v[14:17], v[162:165], v[194:197], v[14:17]
	v_mfma_f32_16x16x32_bf16 v[6:9], v[170:173], v[194:197], v[6:9]
	v_mfma_f32_16x16x32_bf16 v[22:25], v[162:165], v[202:205], v[22:25]
	v_mfma_f32_16x16x32_bf16 v[18:21], v[170:173], v[202:205], v[18:21]
	v_mfma_f32_16x16x32_bf16 v[38:41], v[162:165], v[210:213], v[38:41]
	v_mfma_f32_16x16x32_bf16 v[26:29], v[170:173], v[210:213], v[26:29]
	v_mfma_f32_16x16x32_bf16 v[10:13], v[166:169], v[190:193], v[10:13]
	v_mfma_f32_16x16x32_bf16 v[2:5], v[174:177], v[190:193], v[2:5]
	v_mfma_f32_16x16x32_bf16 v[14:17], v[166:169], v[198:201], v[14:17]
	v_mfma_f32_16x16x32_bf16 v[6:9], v[174:177], v[198:201], v[6:9]
	v_mfma_f32_16x16x32_bf16 v[22:25], v[166:169], v[206:209], v[22:25]
	v_mfma_f32_16x16x32_bf16 v[18:21], v[174:177], v[206:209], v[18:21]
	v_mfma_f32_16x16x32_bf16 v[38:41], v[166:169], v[214:217], v[38:41]
	v_mfma_f32_16x16x32_bf16 v[26:29], v[174:177], v[214:217], v[26:29]
	s_barrier
	s_setprio 0
	s_mov_b32 m0, s45
	s_add_u32 s54, s20, 0x100000
	ds_read_b128 v[186:189], v143 offset:16384
	ds_read_b128 v[190:193], v143 offset:17408
	global_load_lds_dwordx4 v132, s[20:21]
	ds_read_b128 v[194:197], v143 offset:18432
	s_mov_b32 m0, s46
	s_addc_u32 s55, s21, 0
	global_load_lds_dwordx4 v136, s[20:21]
	ds_read_b128 v[198:201], v143 offset:19456
	s_mov_b32 m0, s47
	s_nop 0
	global_load_lds_dwordx4 v132, s[54:55]
	ds_read_b128 v[202:205], v143 offset:20480
	s_mov_b32 m0, s48
	s_nop 0
	global_load_lds_dwordx4 v136, s[54:55]
	ds_read_b128 v[206:209], v143 offset:21504
	s_add_u32 s58, s22, s4
	s_addc_u32 s59, s23, s5
	s_mov_b32 m0, s28
	s_nop 0
	global_load_lds_dwordx4 v130, s[22:23]
	ds_read_b128 v[210:213], v143 offset:22528
	s_mov_b32 m0, s29
	s_nop 0
	global_load_lds_dwordx4 v134, s[22:23]
	ds_read_b128 v[214:217], v143 offset:23552
	s_waitcnt vmcnt(8) lgkmcnt(0)
	s_barrier
	s_setprio 1
	v_mfma_f32_16x16x32_bf16 v[94:97], v[146:149], v[186:189], v[94:97]
	v_mfma_f32_16x16x32_bf16 v[86:89], v[154:157], v[186:189], v[86:89]
	v_mfma_f32_16x16x32_bf16 v[102:105], v[146:149], v[194:197], v[102:105]
	v_mfma_f32_16x16x32_bf16 v[98:101], v[154:157], v[194:197], v[98:101]
	v_mfma_f32_16x16x32_bf16 v[110:113], v[146:149], v[202:205], v[110:113]
	v_mfma_f32_16x16x32_bf16 v[106:109], v[154:157], v[202:205], v[106:109]
	v_mfma_f32_16x16x32_bf16 v[126:129], v[146:149], v[210:213], v[126:129]
	v_mfma_f32_16x16x32_bf16 v[122:125], v[154:157], v[210:213], v[122:125]
	v_mfma_f32_16x16x32_bf16 v[94:97], v[150:153], v[190:193], v[94:97]
	v_mfma_f32_16x16x32_bf16 v[86:89], v[158:161], v[190:193], v[86:89]
	v_mfma_f32_16x16x32_bf16 v[102:105], v[150:153], v[198:201], v[102:105]
	v_mfma_f32_16x16x32_bf16 v[98:101], v[158:161], v[198:201], v[98:101]
	v_mfma_f32_16x16x32_bf16 v[110:113], v[150:153], v[206:209], v[110:113]
	v_mfma_f32_16x16x32_bf16 v[106:109], v[158:161], v[206:209], v[106:109]
	v_mfma_f32_16x16x32_bf16 v[126:129], v[150:153], v[214:217], v[126:129]
	v_mfma_f32_16x16x32_bf16 v[122:125], v[158:161], v[214:217], v[122:125]
	v_mfma_f32_16x16x32_bf16 v[58:61], v[162:165], v[186:189], v[58:61]
	v_mfma_f32_16x16x32_bf16 v[46:49], v[170:173], v[186:189], v[46:49]
	v_mfma_f32_16x16x32_bf16 v[74:77], v[162:165], v[194:197], v[74:77]
	v_mfma_f32_16x16x32_bf16 v[66:69], v[170:173], v[194:197], v[66:69]
	v_mfma_f32_16x16x32_bf16 v[90:93], v[162:165], v[202:205], v[90:93]
	v_mfma_f32_16x16x32_bf16 v[82:85], v[170:173], v[202:205], v[82:85]
	v_mfma_f32_16x16x32_bf16 v[118:121], v[162:165], v[210:213], v[118:121]
	v_mfma_f32_16x16x32_bf16 v[114:117], v[170:173], v[210:213], v[114:117]
	v_mfma_f32_16x16x32_bf16 v[58:61], v[166:169], v[190:193], v[58:61]
	v_mfma_f32_16x16x32_bf16 v[46:49], v[174:177], v[190:193], v[46:49]
	v_mfma_f32_16x16x32_bf16 v[74:77], v[166:169], v[198:201], v[74:77]
	v_mfma_f32_16x16x32_bf16 v[66:69], v[174:177], v[198:201], v[66:69]
	v_mfma_f32_16x16x32_bf16 v[90:93], v[166:169], v[206:209], v[90:93]
	v_mfma_f32_16x16x32_bf16 v[82:85], v[174:177], v[206:209], v[82:85]
	v_mfma_f32_16x16x32_bf16 v[118:121], v[166:169], v[214:217], v[118:121]
	v_mfma_f32_16x16x32_bf16 v[114:117], v[174:177], v[214:217], v[114:117]
	s_barrier
; #define PG8_STAGE(bufoff, gbase, voff) do { _Pragma("unroll") for (int _i = 0; _i < 2; ++_i) \
;         __builtin_amdgcn_global_load_lds((const unsigned*)((const char*)(gbase) + (voff)[_i]), (LAS unsigned*)(lds + (bufoff) + ldsw + _i * 8192), 16, 0, 0); } while (0)
; #define PG8_LDA(dst, b, h) do { _Pragma("unroll") for (int m = 0; m < 4; ++m) _Pragma("unroll") for (int k = 0; k < 2; ++k) dst[m][k] = *(const LAS bf16x8*)(lds + PG8_SA(b, h) + aoff + m * 2048 + k * 1024); } while (0)
; #define PG8_LDB(dst, b, h) do { _Pragma("unroll") for (int n = 0; n < 2; ++n) _Pragma("unroll") for (int k = 0; k < 2; ++k) dst[n][k] = *(const LAS bf16x8*)(lds + PG8_SB(b, h) + boff + n * 2048 + k * 1024); } while (0)
; #define PG8_MMA(ai, bj, At, Bt) do { __builtin_amdgcn_s_setprio(1); _Pragma("unroll") for (int m = 0; m < 4; ++m) _Pragma("unroll") for (int n = 0; n < 2; ++n) _Pragma("unroll") for (int k = 0; k < 2; ++k) \
;         acc[ai][bj][m][n] = __builtin_amdgcn_mfma_f32_16x16x32_bf16(Bt[n][k], At[m][k], acc[ai][bj][m][n], 0, 0, 0); __builtin_amdgcn_s_setprio(0); } while (0)
; #define PG8_WAIT_V(n) asm volatile("s_waitcnt vmcnt(" #n ")" ::: "memory")
; #define PG8_WAIT_L(n) asm volatile("s_waitcnt lgkmcnt(" #n ")" ::: "memory")
; #define PG8_BAR __builtin_amdgcn_s_barrier()
; #define PG8_SCHED __builtin_amdgcn_sched_barrier(0)
; template <class Epi, class Sched, bool ALIGN_EPI, class Hook = NoHook>
; __device__ __forceinline__ void gemm_phase(LAS unsigned char* lds, const Gemm g, const Sched& S, const Epi& E, const Hook& H = Hook()) {
;     ...
;             PG8_LDB(B0, 1, 0); PG8_LDB(B1, 1, 1); PG8_SCHED; PG8_LDA(At, 1, 0); PG8_STAGE(PG8_SA(0, 1), a2 + hA, voffA);
;             PG8_WAIT_V(8); PG8_WAIT_L(0); PG8_BAR; PG8_MMA(0, 0, At, B0); PG8_MMA(0, 1, At, B1); PG8_BAR; PG8_SCHED;
;             PG8_LDA(At, 1, 1); PG8_STAGE(PG8_SB(1, 0), b3, voffB); PG8_STAGE(PG8_SB(1, 1), b3 + hB, voffB); PG8_STAGE(PG8_SA(1, 0), a3, voffA);
;             PG8_WAIT_V(8); PG8_WAIT_L(0); PG8_BAR; PG8_MMA(1, 0, At, B0); PG8_MMA(1, 1, At, B1); PG8_BAR; PG8_SCHED;
;         }
;         if constexpr (Hook::ON) H.after(te, acc, cur, wr, wc, fr, fq);
;         }
;         if constexpr (ALIGN_EPI) { if (wr == 0) PG8_BAR; }
	s_setprio 0
	ds_read_b128 v[146:149], v144
	ds_read_b128 v[150:153], v144 offset:1024
	s_add_u32 s22, s22, 0x100000
	s_addc_u32 s23, s23, 0
	s_mov_b32 m0, s38
	s_nop 0
	global_load_lds_dwordx4 v130, s[22:23]
	ds_read_b128 v[154:157], v144 offset:2048
	ds_read_b128 v[158:161], v144 offset:3072
	ds_read_b128 v[162:165], v145
	ds_read_b128 v[166:169], v145 offset:1024
	ds_read_b128 v[170:173], v145 offset:2048
	ds_read_b128 v[174:177], v145 offset:3072
	ds_read_b128 v[186:189], v143 offset:32768
	s_mov_b32 m0, s39
	s_nop 0
	global_load_lds_dwordx4 v134, s[22:23]
	ds_read_b128 v[190:193], v143 offset:33792
	ds_read_b128 v[194:197], v143 offset:34816
	ds_read_b128 v[198:201], v143 offset:35840
	ds_read_b128 v[202:205], v143 offset:36864
	ds_read_b128 v[206:209], v143 offset:37888
	ds_read_b128 v[210:213], v143 offset:38912
	ds_read_b128 v[214:217], v143 offset:39936
	s_waitcnt vmcnt(8) lgkmcnt(0)
	s_barrier
	s_setprio 1
	v_mfma_f32_16x16x32_bf16 v[54:57], v[146:149], v[186:189], v[54:57]
	v_mfma_f32_16x16x32_bf16 v[34:37], v[154:157], v[186:189], v[34:37]
	v_mfma_f32_16x16x32_bf16 v[42:45], v[146:149], v[194:197], v[42:45]
	v_mfma_f32_16x16x32_bf16 v[30:33], v[154:157], v[194:197], v[30:33]
	v_mfma_f32_16x16x32_bf16 v[62:65], v[146:149], v[202:205], v[62:65]
	v_mfma_f32_16x16x32_bf16 v[50:53], v[154:157], v[202:205], v[50:53]
	v_mfma_f32_16x16x32_bf16 v[78:81], v[146:149], v[210:213], v[78:81]
	v_mfma_f32_16x16x32_bf16 v[70:73], v[154:157], v[210:213], v[70:73]
	v_mfma_f32_16x16x32_bf16 v[54:57], v[150:153], v[190:193], v[54:57]
	v_mfma_f32_16x16x32_bf16 v[34:37], v[158:161], v[190:193], v[34:37]
	v_mfma_f32_16x16x32_bf16 v[42:45], v[150:153], v[198:201], v[42:45]
	v_mfma_f32_16x16x32_bf16 v[30:33], v[158:161], v[198:201], v[30:33]
	v_mfma_f32_16x16x32_bf16 v[62:65], v[150:153], v[206:209], v[62:65]
	v_mfma_f32_16x16x32_bf16 v[50:53], v[158:161], v[206:209], v[50:53]
	v_mfma_f32_16x16x32_bf16 v[78:81], v[150:153], v[214:217], v[78:81]
	v_mfma_f32_16x16x32_bf16 v[70:73], v[158:161], v[214:217], v[70:73]
	v_mfma_f32_16x16x32_bf16 v[10:13], v[162:165], v[186:189], v[10:13]
	v_mfma_f32_16x16x32_bf16 v[2:5], v[170:173], v[186:189], v[2:5]
	v_mfma_f32_16x16x32_bf16 v[14:17], v[162:165], v[194:197], v[14:17]
	v_mfma_f32_16x16x32_bf16 v[6:9], v[170:173], v[194:197], v[6:9]
	v_mfma_f32_16x16x32_bf16 v[22:25], v[162:165], v[202:205], v[22:25]
	v_mfma_f32_16x16x32_bf16 v[18:21], v[170:173], v[202:205], v[18:21]
	v_mfma_f32_16x16x32_bf16 v[38:41], v[162:165], v[210:213], v[38:41]
	v_mfma_f32_16x16x32_bf16 v[26:29], v[170:173], v[210:213], v[26:29]
	v_mfma_f32_16x16x32_bf16 v[10:13], v[166:169], v[190:193], v[10:13]
	v_mfma_f32_16x16x32_bf16 v[2:5], v[174:177], v[190:193], v[2:5]
	v_mfma_f32_16x16x32_bf16 v[14:17], v[166:169], v[198:201], v[14:17]
	v_mfma_f32_16x16x32_bf16 v[6:9], v[174:177], v[198:201], v[6:9]
	v_mfma_f32_16x16x32_bf16 v[22:25], v[166:169], v[206:209], v[22:25]
	v_mfma_f32_16x16x32_bf16 v[18:21], v[174:177], v[206:209], v[18:21]
	v_mfma_f32_16x16x32_bf16 v[38:41], v[166:169], v[214:217], v[38:41]
	v_mfma_f32_16x16x32_bf16 v[26:29], v[174:177], v[214:217], v[26:29]
	s_barrier
	s_setprio 0
	s_mov_b32 m0, s49
	s_add_u32 s56, s20, s4
	s_addc_u32 s57, s21, s5
	s_add_u32 s20, s20, 0x100080
	ds_read_b128 v[186:189], v143 offset:49152
	ds_read_b128 v[190:193], v143 offset:50176
	global_load_lds_dwordx4 v132, s[56:57]
	ds_read_b128 v[194:197], v143 offset:51200
	s_mov_b32 m0, s50
	s_addc_u32 s21, s21, 0
	global_load_lds_dwordx4 v136, s[56:57]
	ds_read_b128 v[198:201], v143 offset:52224
	s_mov_b32 m0, s51
	s_nop 0
	global_load_lds_dwordx4 v132, s[20:21]
	ds_read_b128 v[202:205], v143 offset:53248
	s_mov_b32 m0, s52
	s_nop 0
	global_load_lds_dwordx4 v136, s[20:21]
	ds_read_b128 v[206:209], v143 offset:54272
	s_mov_b32 m0, s40
	s_nop 0
	global_load_lds_dwordx4 v130, s[58:59]
	ds_read_b128 v[210:213], v143 offset:55296
	s_mov_b32 m0, s41
	s_nop 0
	global_load_lds_dwordx4 v134, s[58:59]
	s_add_i32 s42, s42, 2
	s_add_u32 s6, s6, 0x100
	s_addc_u32 s7, s7, 0
	s_cmp_gt_u32 s42, 61
	ds_read_b128 v[214:217], v143 offset:56320
	s_waitcnt vmcnt(8) lgkmcnt(0)
	s_barrier
	s_setprio 1
	v_mfma_f32_16x16x32_bf16 v[94:97], v[146:149], v[186:189], v[94:97]
	v_mfma_f32_16x16x32_bf16 v[86:89], v[154:157], v[186:189], v[86:89]
	v_mfma_f32_16x16x32_bf16 v[102:105], v[146:149], v[194:197], v[102:105]
	v_mfma_f32_16x16x32_bf16 v[98:101], v[154:157], v[194:197], v[98:101]
	v_mfma_f32_16x16x32_bf16 v[110:113], v[146:149], v[202:205], v[110:113]
	v_mfma_f32_16x16x32_bf16 v[106:109], v[154:157], v[202:205], v[106:109]
	v_mfma_f32_16x16x32_bf16 v[126:129], v[146:149], v[210:213], v[126:129]
	v_mfma_f32_16x16x32_bf16 v[122:125], v[154:157], v[210:213], v[122:125]
	v_mfma_f32_16x16x32_bf16 v[94:97], v[150:153], v[190:193], v[94:97]
	v_mfma_f32_16x16x32_bf16 v[86:89], v[158:161], v[190:193], v[86:89]
	v_mfma_f32_16x16x32_bf16 v[102:105], v[150:153], v[198:201], v[102:105]
	v_mfma_f32_16x16x32_bf16 v[98:101], v[158:161], v[198:201], v[98:101]
	v_mfma_f32_16x16x32_bf16 v[110:113], v[150:153], v[206:209], v[110:113]
	v_mfma_f32_16x16x32_bf16 v[106:109], v[158:161], v[206:209], v[106:109]
	v_mfma_f32_16x16x32_bf16 v[126:129], v[150:153], v[214:217], v[126:129]
	v_mfma_f32_16x16x32_bf16 v[122:125], v[158:161], v[214:217], v[122:125]
	v_mfma_f32_16x16x32_bf16 v[58:61], v[162:165], v[186:189], v[58:61]
	v_mfma_f32_16x16x32_bf16 v[46:49], v[170:173], v[186:189], v[46:49]
	v_mfma_f32_16x16x32_bf16 v[74:77], v[162:165], v[194:197], v[74:77]
	v_mfma_f32_16x16x32_bf16 v[66:69], v[170:173], v[194:197], v[66:69]
	v_mfma_f32_16x16x32_bf16 v[90:93], v[162:165], v[202:205], v[90:93]
	v_mfma_f32_16x16x32_bf16 v[82:85], v[170:173], v[202:205], v[82:85]
	v_mfma_f32_16x16x32_bf16 v[118:121], v[162:165], v[210:213], v[118:121]
	v_mfma_f32_16x16x32_bf16 v[114:117], v[170:173], v[210:213], v[114:117]
	v_mfma_f32_16x16x32_bf16 v[58:61], v[166:169], v[190:193], v[58:61]
	v_mfma_f32_16x16x32_bf16 v[46:49], v[174:177], v[190:193], v[46:49]
	v_mfma_f32_16x16x32_bf16 v[74:77], v[166:169], v[198:201], v[74:77]
	v_mfma_f32_16x16x32_bf16 v[66:69], v[174:177], v[198:201], v[66:69]
	v_mfma_f32_16x16x32_bf16 v[90:93], v[166:169], v[206:209], v[90:93]
	v_mfma_f32_16x16x32_bf16 v[82:85], v[174:177], v[206:209], v[82:85]
	v_mfma_f32_16x16x32_bf16 v[118:121], v[166:169], v[214:217], v[118:121]
	v_mfma_f32_16x16x32_bf16 v[114:117], v[174:177], v[214:217], v[114:117]
	s_barrier
	s_setprio 0
	s_cbranch_scc0 .LBB0_850
	s_cmpk_lt_u32 s26, 0x100
	s_cbranch_scc0 .LBB0_853
	s_barrier

; #define PG8_STAGE(bufoff, gbase, voff) do { _Pragma("unroll") for (int _i = 0; _i < 2; ++_i) \
;         __builtin_amdgcn_global_load_lds((const unsigned*)((const char*)(gbase) + (voff)[_i]), (LAS unsigned*)(lds + (bufoff) + ldsw + _i * 8192), 16, 0, 0); } while (0)
; #define PG8_LDA(dst, b, h) do { _Pragma("unroll") for (int m = 0; m < 4; ++m) _Pragma("unroll") for (int k = 0; k < 2; ++k) dst[m][k] = *(const LAS bf16x8*)(lds + PG8_SA(b, h) + aoff + m * 2048 + k * 1024); } while (0)
; #define PG8_LDB(dst, b, h) do { _Pragma("unroll") for (int n = 0; n < 2; ++n) _Pragma("unroll") for (int k = 0; k < 2; ++k) dst[n][k] = *(const LAS bf16x8*)(lds + PG8_SB(b, h) + boff + n * 2048 + k * 1024); } while (0)
; #define PG8_MMA(ai, bj, At, Bt) do { __builtin_amdgcn_s_setprio(1); _Pragma("unroll") for (int m = 0; m < 4; ++m) _Pragma("unroll") for (int n = 0; n < 2; ++n) _Pragma("unroll") for (int k = 0; k < 2; ++k) \
;         acc[ai][bj][m][n] = __builtin_amdgcn_mfma_f32_16x16x32_bf16(Bt[n][k], At[m][k], acc[ai][bj][m][n], 0, 0, 0); __builtin_amdgcn_s_setprio(0); } while (0)
; #define PG8_WAIT_V(n) asm volatile("s_waitcnt vmcnt(" #n ")" ::: "memory")
; #define PG8_WAIT_L(n) asm volatile("s_waitcnt lgkmcnt(" #n ")" ::: "memory")
; template <class Epi, class Sched, bool ALIGN_EPI, class Hook = NoHook>
; __device__ __forceinline__ void gemm_phase(LAS unsigned char* lds, const Gemm g, const Sched& S, const Epi& E, const Hook& H = Hook()) {
;     ...
;         for (int t = tb; t < te; t += 2) {
;             const bool last = (t == nt - 2);
;             const char* a1 = cA + (size_t)(t + 1) * kstep;
;             const char* a2 = last ? nA : cA + (size_t)(t + 2) * kstep; const char* b2 = last ? nB : cB + (size_t)(t + 2) * kstep;
;             const char* a3 = a2 + kstep; const char* b3 = b2 + kstep;
;             if (last && has_next) S.a_ready(nxt);
;             PG8_LDB(B0, 0, 0); PG8_LDB(B1, 0, 1); PG8_SCHED; PG8_LDA(At, 0, 0); PG8_STAGE(PG8_SA(1, 1), a1 + hA, voffA);
;             PG8_WAIT_V(8); PG8_WAIT_L(0); PG8_BAR; PG8_MMA(0, 0, At, B0); PG8_MMA(0, 1, At, B1); PG8_BAR; PG8_SCHED;
;             PG8_LDA(At, 0, 1); PG8_STAGE(PG8_SB(0, 0), b2, voffB); PG8_STAGE(PG8_SB(0, 1), b2 + hB, voffB); PG8_STAGE(PG8_SA(0, 0), a2, voffA);
;             PG8_WAIT_V(8); PG8_WAIT_L(0); PG8_BAR; PG8_MMA(1, 0, At, B0); PG8_MMA(1, 1, At, B1); PG8_BAR; PG8_SCHED;
.LBB0_896:
	ds_read_b128 v[146:149], v140
	ds_read_b128 v[150:153], v140 offset:1024
	s_add_u32 s10, s6, 0x87c00080
	s_addc_u32 s11, s7, -1
	s_cmp_lg_u32 s18, 60
	s_cselect_b32 s10, s10, 0
	s_cselect_b32 s11, s11, 0
	s_add_u32 s16, s2, s10
	s_addc_u32 s17, s3, s11
	s_add_u32 s10, s14, s10
	s_addc_u32 s11, s15, s11
	s_mov_b32 m0, s19
	ds_read_b128 v[154:157], v140 offset:2048
	ds_read_b128 v[158:161], v140 offset:3072
	ds_read_b128 v[162:165], v141
	ds_read_b128 v[166:169], v141 offset:1024
	ds_read_b128 v[170:173], v141 offset:2048
	ds_read_b128 v[174:177], v141 offset:3072
	v_lshl_add_u64 v[178:179], v[136:137], 0, s[6:7]
	global_load_lds_dwordx4 v[178:179], off
	ds_read_b128 v[186:189], v142
	ds_read_b128 v[190:193], v142 offset:1024
	ds_read_b128 v[194:197], v142 offset:2048
	ds_read_b128 v[198:201], v142 offset:3072
	ds_read_b128 v[202:205], v142 offset:4096
	ds_read_b128 v[206:209], v142 offset:5120
	ds_read_b128 v[210:213], v142 offset:6144
	ds_read_b128 v[214:217], v142 offset:7168
	v_lshl_add_u64 v[178:179], v[138:139], 0, s[6:7]
	s_mov_b32 m0, s31
	s_nop 0
	global_load_lds_dwordx4 v[178:179], off
	s_waitcnt vmcnt(8) lgkmcnt(0)
	s_barrier
	s_setprio 1
	v_mfma_f32_16x16x32_bf16 v[54:57], v[146:149], v[186:189], v[54:57]
	v_mfma_f32_16x16x32_bf16 v[34:37], v[154:157], v[186:189], v[34:37]
	v_mfma_f32_16x16x32_bf16 v[42:45], v[146:149], v[194:197], v[42:45]
	v_mfma_f32_16x16x32_bf16 v[30:33], v[154:157], v[194:197], v[30:33]
	v_mfma_f32_16x16x32_bf16 v[62:65], v[146:149], v[202:205], v[62:65]
	v_mfma_f32_16x16x32_bf16 v[50:53], v[154:157], v[202:205], v[50:53]
	v_mfma_f32_16x16x32_bf16 v[78:81], v[146:149], v[210:213], v[78:81]
	v_mfma_f32_16x16x32_bf16 v[70:73], v[154:157], v[210:213], v[70:73]
	v_mfma_f32_16x16x32_bf16 v[54:57], v[150:153], v[190:193], v[54:57]
	v_mfma_f32_16x16x32_bf16 v[34:37], v[158:161], v[190:193], v[34:37]
	v_mfma_f32_16x16x32_bf16 v[42:45], v[150:153], v[198:201], v[42:45]
	v_mfma_f32_16x16x32_bf16 v[30:33], v[158:161], v[198:201], v[30:33]
	v_mfma_f32_16x16x32_bf16 v[62:65], v[150:153], v[206:209], v[62:65]
	v_mfma_f32_16x16x32_bf16 v[50:53], v[158:161], v[206:209], v[50:53]
	v_mfma_f32_16x16x32_bf16 v[78:81], v[150:153], v[214:217], v[78:81]
	v_mfma_f32_16x16x32_bf16 v[70:73], v[158:161], v[214:217], v[70:73]
	v_mfma_f32_16x16x32_bf16 v[10:13], v[162:165], v[186:189], v[10:13]
	v_mfma_f32_16x16x32_bf16 v[2:5], v[170:173], v[186:189], v[2:5]
	v_mfma_f32_16x16x32_bf16 v[14:17], v[162:165], v[194:197], v[14:17]
	v_mfma_f32_16x16x32_bf16 v[6:9], v[170:173], v[194:197], v[6:9]
	v_mfma_f32_16x16x32_bf16 v[22:25], v[162:165], v[202:205], v[22:25]
	v_mfma_f32_16x16x32_bf16 v[18:21], v[170:173], v[202:205], v[18:21]
	v_mfma_f32_16x16x32_bf16 v[38:41], v[162:165], v[210:213], v[38:41]
	v_mfma_f32_16x16x32_bf16 v[26:29], v[170:173], v[210:213], v[26:29]
	v_mfma_f32_16x16x32_bf16 v[10:13], v[166:169], v[190:193], v[10:13]
	v_mfma_f32_16x16x32_bf16 v[2:5], v[174:177], v[190:193], v[2:5]
	v_mfma_f32_16x16x32_bf16 v[14:17], v[166:169], v[198:201], v[14:17]
	v_mfma_f32_16x16x32_bf16 v[6:9], v[174:177], v[198:201], v[6:9]
	v_mfma_f32_16x16x32_bf16 v[22:25], v[166:169], v[206:209], v[22:25]
	v_mfma_f32_16x16x32_bf16 v[18:21], v[174:177], v[206:209], v[18:21]
	v_mfma_f32_16x16x32_bf16 v[38:41], v[166:169], v[214:217], v[38:41]
	v_mfma_f32_16x16x32_bf16 v[26:29], v[174:177], v[214:217], v[26:29]
	s_barrier
	s_setprio 0
	s_mov_b32 m0, s33
	s_add_u32 s46, s10, 0x100000
	ds_read_b128 v[186:189], v142 offset:16384
	ds_read_b128 v[190:193], v142 offset:17408
	global_load_lds_dwordx4 v180, s[10:11]
	ds_read_b128 v[194:197], v142 offset:18432
	s_mov_b32 m0, s34
	s_addc_u32 s47, s11, 0
	global_load_lds_dwordx4 v134, s[10:11]
	ds_read_b128 v[198:201], v142 offset:19456
	s_mov_b32 m0, s35
	s_nop 0
	global_load_lds_dwordx4 v180, s[46:47]
	ds_read_b128 v[202:205], v142 offset:20480
	s_mov_b32 m0, s42
	s_nop 0
	global_load_lds_dwordx4 v134, s[46:47]
	ds_read_b128 v[206:209], v142 offset:21504
	s_add_u32 s50, s16, s4
	s_addc_u32 s51, s17, s5
	s_mov_b32 m0, s27
	s_nop 0
	global_load_lds_dwordx4 v130, s[16:17]
	ds_read_b128 v[210:213], v142 offset:22528
	s_mov_b32 m0, s28
	s_nop 0
	global_load_lds_dwordx4 v132, s[16:17]
	ds_read_b128 v[214:217], v142 offset:23552
	s_waitcnt vmcnt(8) lgkmcnt(0)
	s_barrier
	s_setprio 1
	v_mfma_f32_16x16x32_bf16 v[94:97], v[146:149], v[186:189], v[94:97]
	v_mfma_f32_16x16x32_bf16 v[86:89], v[154:157], v[186:189], v[86:89]
	v_mfma_f32_16x16x32_bf16 v[102:105], v[146:149], v[194:197], v[102:105]
	v_mfma_f32_16x16x32_bf16 v[98:101], v[154:157], v[194:197], v[98:101]
	v_mfma_f32_16x16x32_bf16 v[110:113], v[146:149], v[202:205], v[110:113]
	v_mfma_f32_16x16x32_bf16 v[106:109], v[154:157], v[202:205], v[106:109]
	v_mfma_f32_16x16x32_bf16 v[126:129], v[146:149], v[210:213], v[126:129]
	v_mfma_f32_16x16x32_bf16 v[122:125], v[154:157], v[210:213], v[122:125]
	v_mfma_f32_16x16x32_bf16 v[94:97], v[150:153], v[190:193], v[94:97]
	v_mfma_f32_16x16x32_bf16 v[86:89], v[158:161], v[190:193], v[86:89]
	v_mfma_f32_16x16x32_bf16 v[102:105], v[150:153], v[198:201], v[102:105]
	v_mfma_f32_16x16x32_bf16 v[98:101], v[158:161], v[198:201], v[98:101]
	v_mfma_f32_16x16x32_bf16 v[110:113], v[150:153], v[206:209], v[110:113]
	v_mfma_f32_16x16x32_bf16 v[106:109], v[158:161], v[206:209], v[106:109]
	v_mfma_f32_16x16x32_bf16 v[126:129], v[150:153], v[214:217], v[126:129]
	v_mfma_f32_16x16x32_bf16 v[122:125], v[158:161], v[214:217], v[122:125]
	v_mfma_f32_16x16x32_bf16 v[58:61], v[162:165], v[186:189], v[58:61]
	v_mfma_f32_16x16x32_bf16 v[46:49], v[170:173], v[186:189], v[46:49]
	v_mfma_f32_16x16x32_bf16 v[74:77], v[162:165], v[194:197], v[74:77]
	v_mfma_f32_16x16x32_bf16 v[66:69], v[170:173], v[194:197], v[66:69]
	v_mfma_f32_16x16x32_bf16 v[90:93], v[162:165], v[202:205], v[90:93]
	v_mfma_f32_16x16x32_bf16 v[82:85], v[170:173], v[202:205], v[82:85]
	v_mfma_f32_16x16x32_bf16 v[118:121], v[162:165], v[210:213], v[118:121]
	v_mfma_f32_16x16x32_bf16 v[114:117], v[170:173], v[210:213], v[114:117]
	v_mfma_f32_16x16x32_bf16 v[58:61], v[166:169], v[190:193], v[58:61]
	v_mfma_f32_16x16x32_bf16 v[46:49], v[174:177], v[190:193], v[46:49]
	v_mfma_f32_16x16x32_bf16 v[74:77], v[166:169], v[198:201], v[74:77]
	v_mfma_f32_16x16x32_bf16 v[66:69], v[174:177], v[198:201], v[66:69]
	v_mfma_f32_16x16x32_bf16 v[90:93], v[166:169], v[206:209], v[90:93]
	v_mfma_f32_16x16x32_bf16 v[82:85], v[174:177], v[206:209], v[82:85]
	v_mfma_f32_16x16x32_bf16 v[118:121], v[166:169], v[214:217], v[118:121]
	v_mfma_f32_16x16x32_bf16 v[114:117], v[174:177], v[214:217], v[114:117]
	s_barrier
; #define PG8_STAGE(bufoff, gbase, voff) do { _Pragma("unroll") for (int _i = 0; _i < 2; ++_i) \
;         __builtin_amdgcn_global_load_lds((const unsigned*)((const char*)(gbase) + (voff)[_i]), (LAS unsigned*)(lds + (bufoff) + ldsw + _i * 8192), 16, 0, 0); } while (0)
; #define PG8_LDA(dst, b, h) do { _Pragma("unroll") for (int m = 0; m < 4; ++m) _Pragma("unroll") for (int k = 0; k < 2; ++k) dst[m][k] = *(const LAS bf16x8*)(lds + PG8_SA(b, h) + aoff + m * 2048 + k * 1024); } while (0)
; #define PG8_LDB(dst, b, h) do { _Pragma("unroll") for (int n = 0; n < 2; ++n) _Pragma("unroll") for (int k = 0; k < 2; ++k) dst[n][k] = *(const LAS bf16x8*)(lds + PG8_SB(b, h) + boff + n * 2048 + k * 1024); } while (0)
; #define PG8_MMA(ai, bj, At, Bt) do { __builtin_amdgcn_s_setprio(1); _Pragma("unroll") for (int m = 0; m < 4; ++m) _Pragma("unroll") for (int n = 0; n < 2; ++n) _Pragma("unroll") for (int k = 0; k < 2; ++k) \
;         acc[ai][bj][m][n] = __builtin_amdgcn_mfma_f32_16x16x32_bf16(Bt[n][k], At[m][k], acc[ai][bj][m][n], 0, 0, 0); __builtin_amdgcn_s_setprio(0); } while (0)
; #define PG8_WAIT_V(n) asm volatile("s_waitcnt vmcnt(" #n ")" ::: "memory")
; #define PG8_WAIT_L(n) asm volatile("s_waitcnt lgkmcnt(" #n ")" ::: "memory")
; #define PG8_BAR __builtin_amdgcn_s_barrier()
; #define PG8_SCHED __builtin_amdgcn_sched_barrier(0)
; template <class Epi, class Sched, bool ALIGN_EPI, class Hook = NoHook>
; __device__ __forceinline__ void gemm_phase(LAS unsigned char* lds, const Gemm g, const Sched& S, const Epi& E, const Hook& H = Hook()) {
;     ...
;             PG8_LDB(B0, 1, 0); PG8_LDB(B1, 1, 1); PG8_SCHED; PG8_LDA(At, 1, 0); PG8_STAGE(PG8_SA(0, 1), a2 + hA, voffA);
;             PG8_WAIT_V(8); PG8_WAIT_L(0); PG8_BAR; PG8_MMA(0, 0, At, B0); PG8_MMA(0, 1, At, B1); PG8_BAR; PG8_SCHED;
;             PG8_LDA(At, 1, 1); PG8_STAGE(PG8_SB(1, 0), b3, voffB); PG8_STAGE(PG8_SB(1, 1), b3 + hB, voffB); PG8_STAGE(PG8_SA(1, 0), a3, voffA);
;             PG8_WAIT_V(8); PG8_WAIT_L(0); PG8_BAR; PG8_MMA(1, 0, At, B0); PG8_MMA(1, 1, At, B1); PG8_BAR; PG8_SCHED;
;         }
;         if constexpr (Hook::ON) H.after(te, acc, cur, wr, wc, fr, fq);
;         }
;         if constexpr (ALIGN_EPI) { if (wr == 0) PG8_BAR; }
	s_setprio 0
	ds_read_b128 v[146:149], v143
	ds_read_b128 v[150:153], v143 offset:1024
	s_add_u32 s16, s16, 0x100000
	s_addc_u32 s17, s17, 0
	s_mov_b32 m0, s29
	s_nop 0
	global_load_lds_dwordx4 v130, s[16:17]
	ds_read_b128 v[154:157], v143 offset:2048
	ds_read_b128 v[158:161], v143 offset:3072
	ds_read_b128 v[162:165], v144
	ds_read_b128 v[166:169], v144 offset:1024
	ds_read_b128 v[170:173], v144 offset:2048
	ds_read_b128 v[174:177], v144 offset:3072
	ds_read_b128 v[186:189], v142 offset:32768
	s_mov_b32 m0, s39
	s_nop 0
	global_load_lds_dwordx4 v132, s[16:17]
	ds_read_b128 v[190:193], v142 offset:33792
	ds_read_b128 v[194:197], v142 offset:34816
	ds_read_b128 v[198:201], v142 offset:35840
	ds_read_b128 v[202:205], v142 offset:36864
	ds_read_b128 v[206:209], v142 offset:37888
	ds_read_b128 v[210:213], v142 offset:38912
	ds_read_b128 v[214:217], v142 offset:39936
	s_waitcnt vmcnt(8) lgkmcnt(0)
	s_barrier
	s_setprio 1
	v_mfma_f32_16x16x32_bf16 v[54:57], v[146:149], v[186:189], v[54:57]
	v_mfma_f32_16x16x32_bf16 v[34:37], v[154:157], v[186:189], v[34:37]
	v_mfma_f32_16x16x32_bf16 v[42:45], v[146:149], v[194:197], v[42:45]
	v_mfma_f32_16x16x32_bf16 v[30:33], v[154:157], v[194:197], v[30:33]
	v_mfma_f32_16x16x32_bf16 v[62:65], v[146:149], v[202:205], v[62:65]
	v_mfma_f32_16x16x32_bf16 v[50:53], v[154:157], v[202:205], v[50:53]
	v_mfma_f32_16x16x32_bf16 v[78:81], v[146:149], v[210:213], v[78:81]
	v_mfma_f32_16x16x32_bf16 v[70:73], v[154:157], v[210:213], v[70:73]
	v_mfma_f32_16x16x32_bf16 v[54:57], v[150:153], v[190:193], v[54:57]
	v_mfma_f32_16x16x32_bf16 v[34:37], v[158:161], v[190:193], v[34:37]
	v_mfma_f32_16x16x32_bf16 v[42:45], v[150:153], v[198:201], v[42:45]
	v_mfma_f32_16x16x32_bf16 v[30:33], v[158:161], v[198:201], v[30:33]
	v_mfma_f32_16x16x32_bf16 v[62:65], v[150:153], v[206:209], v[62:65]
	v_mfma_f32_16x16x32_bf16 v[50:53], v[158:161], v[206:209], v[50:53]
	v_mfma_f32_16x16x32_bf16 v[78:81], v[150:153], v[214:217], v[78:81]
	v_mfma_f32_16x16x32_bf16 v[70:73], v[158:161], v[214:217], v[70:73]
	v_mfma_f32_16x16x32_bf16 v[10:13], v[162:165], v[186:189], v[10:13]
	v_mfma_f32_16x16x32_bf16 v[2:5], v[170:173], v[186:189], v[2:5]
	v_mfma_f32_16x16x32_bf16 v[14:17], v[162:165], v[194:197], v[14:17]
	v_mfma_f32_16x16x32_bf16 v[6:9], v[170:173], v[194:197], v[6:9]
	v_mfma_f32_16x16x32_bf16 v[22:25], v[162:165], v[202:205], v[22:25]
	v_mfma_f32_16x16x32_bf16 v[18:21], v[170:173], v[202:205], v[18:21]
	v_mfma_f32_16x16x32_bf16 v[38:41], v[162:165], v[210:213], v[38:41]
	v_mfma_f32_16x16x32_bf16 v[26:29], v[170:173], v[210:213], v[26:29]
	v_mfma_f32_16x16x32_bf16 v[10:13], v[166:169], v[190:193], v[10:13]
	v_mfma_f32_16x16x32_bf16 v[2:5], v[174:177], v[190:193], v[2:5]
	v_mfma_f32_16x16x32_bf16 v[14:17], v[166:169], v[198:201], v[14:17]
	v_mfma_f32_16x16x32_bf16 v[6:9], v[174:177], v[198:201], v[6:9]
	v_mfma_f32_16x16x32_bf16 v[22:25], v[166:169], v[206:209], v[22:25]
	v_mfma_f32_16x16x32_bf16 v[18:21], v[174:177], v[206:209], v[18:21]
	v_mfma_f32_16x16x32_bf16 v[38:41], v[166:169], v[214:217], v[38:41]
	v_mfma_f32_16x16x32_bf16 v[26:29], v[174:177], v[214:217], v[26:29]
	s_barrier
	s_setprio 0
	s_mov_b32 m0, s36
	s_add_u32 s48, s10, s4
	s_addc_u32 s49, s11, s5
	s_add_u32 s10, s10, 0x100080
	ds_read_b128 v[186:189], v142 offset:49152
	ds_read_b128 v[190:193], v142 offset:50176
	global_load_lds_dwordx4 v180, s[48:49]
	ds_read_b128 v[194:197], v142 offset:51200
	s_mov_b32 m0, s43
	s_addc_u32 s11, s11, 0
	global_load_lds_dwordx4 v134, s[48:49]
	ds_read_b128 v[198:201], v142 offset:52224
	s_mov_b32 m0, s37
	s_nop 0
	global_load_lds_dwordx4 v180, s[10:11]
	ds_read_b128 v[202:205], v142 offset:53248
	s_mov_b32 m0, s44
	s_nop 0
	global_load_lds_dwordx4 v134, s[10:11]
	ds_read_b128 v[206:209], v142 offset:54272
	s_mov_b32 m0, s40
	s_nop 0
	global_load_lds_dwordx4 v130, s[50:51]
	ds_read_b128 v[210:213], v142 offset:55296
	s_mov_b32 m0, s41
	s_nop 0
	global_load_lds_dwordx4 v132, s[50:51]
	s_add_i32 s18, s18, 2
	s_add_u32 s6, s6, 0x100
	s_addc_u32 s7, s7, 0
	s_cmp_gt_u32 s18, 61
	ds_read_b128 v[214:217], v142 offset:56320
	s_waitcnt vmcnt(8) lgkmcnt(0)
	s_barrier
	s_setprio 1
	v_mfma_f32_16x16x32_bf16 v[94:97], v[146:149], v[186:189], v[94:97]
	v_mfma_f32_16x16x32_bf16 v[86:89], v[154:157], v[186:189], v[86:89]
	v_mfma_f32_16x16x32_bf16 v[102:105], v[146:149], v[194:197], v[102:105]
	v_mfma_f32_16x16x32_bf16 v[98:101], v[154:157], v[194:197], v[98:101]
	v_mfma_f32_16x16x32_bf16 v[110:113], v[146:149], v[202:205], v[110:113]
	v_mfma_f32_16x16x32_bf16 v[106:109], v[154:157], v[202:205], v[106:109]
	v_mfma_f32_16x16x32_bf16 v[126:129], v[146:149], v[210:213], v[126:129]
	v_mfma_f32_16x16x32_bf16 v[122:125], v[154:157], v[210:213], v[122:125]
	v_mfma_f32_16x16x32_bf16 v[94:97], v[150:153], v[190:193], v[94:97]
	v_mfma_f32_16x16x32_bf16 v[86:89], v[158:161], v[190:193], v[86:89]
	v_mfma_f32_16x16x32_bf16 v[102:105], v[150:153], v[198:201], v[102:105]
	v_mfma_f32_16x16x32_bf16 v[98:101], v[158:161], v[198:201], v[98:101]
	v_mfma_f32_16x16x32_bf16 v[110:113], v[150:153], v[206:209], v[110:113]
	v_mfma_f32_16x16x32_bf16 v[106:109], v[158:161], v[206:209], v[106:109]
	v_mfma_f32_16x16x32_bf16 v[126:129], v[150:153], v[214:217], v[126:129]
	v_mfma_f32_16x16x32_bf16 v[122:125], v[158:161], v[214:217], v[122:125]
	v_mfma_f32_16x16x32_bf16 v[58:61], v[162:165], v[186:189], v[58:61]
	v_mfma_f32_16x16x32_bf16 v[46:49], v[170:173], v[186:189], v[46:49]
	v_mfma_f32_16x16x32_bf16 v[74:77], v[162:165], v[194:197], v[74:77]
	v_mfma_f32_16x16x32_bf16 v[66:69], v[170:173], v[194:197], v[66:69]
	v_mfma_f32_16x16x32_bf16 v[90:93], v[162:165], v[202:205], v[90:93]
	v_mfma_f32_16x16x32_bf16 v[82:85], v[170:173], v[202:205], v[82:85]
	v_mfma_f32_16x16x32_bf16 v[118:121], v[162:165], v[210:213], v[118:121]
	v_mfma_f32_16x16x32_bf16 v[114:117], v[170:173], v[210:213], v[114:117]
	v_mfma_f32_16x16x32_bf16 v[58:61], v[166:169], v[190:193], v[58:61]
	v_mfma_f32_16x16x32_bf16 v[46:49], v[174:177], v[190:193], v[46:49]
	v_mfma_f32_16x16x32_bf16 v[74:77], v[166:169], v[198:201], v[74:77]
	v_mfma_f32_16x16x32_bf16 v[66:69], v[174:177], v[198:201], v[66:69]
	v_mfma_f32_16x16x32_bf16 v[90:93], v[166:169], v[206:209], v[90:93]
	v_mfma_f32_16x16x32_bf16 v[82:85], v[174:177], v[206:209], v[82:85]
	v_mfma_f32_16x16x32_bf16 v[118:121], v[166:169], v[214:217], v[118:121]
	v_mfma_f32_16x16x32_bf16 v[114:117], v[174:177], v[214:217], v[114:117]
	s_barrier
	s_setprio 0
	s_cbranch_scc0 .LBB0_896
	s_cmpk_lt_u32 s22, 0x100
	s_cbranch_scc0 .LBB0_899
	s_barrier

; #define PG8_STAGE(bufoff, gbase, voff) do { _Pragma("unroll") for (int _i = 0; _i < 2; ++_i) \
;         __builtin_amdgcn_global_load_lds((const unsigned*)((const char*)(gbase) + (voff)[_i]), (LAS unsigned*)(lds + (bufoff) + ldsw + _i * 8192), 16, 0, 0); } while (0)
; #define PG8_LDA(dst, b, h) do { _Pragma("unroll") for (int m = 0; m < 4; ++m) _Pragma("unroll") for (int k = 0; k < 2; ++k) dst[m][k] = *(const LAS bf16x8*)(lds + PG8_SA(b, h) + aoff + m * 2048 + k * 1024); } while (0)
; #define PG8_LDB(dst, b, h) do { _Pragma("unroll") for (int n = 0; n < 2; ++n) _Pragma("unroll") for (int k = 0; k < 2; ++k) dst[n][k] = *(const LAS bf16x8*)(lds + PG8_SB(b, h) + boff + n * 2048 + k * 1024); } while (0)
; #define PG8_MMA(ai, bj, At, Bt) do { __builtin_amdgcn_s_setprio(1); _Pragma("unroll") for (int m = 0; m < 4; ++m) _Pragma("unroll") for (int n = 0; n < 2; ++n) _Pragma("unroll") for (int k = 0; k < 2; ++k) \
;         acc[ai][bj][m][n] = __builtin_amdgcn_mfma_f32_16x16x32_bf16(Bt[n][k], At[m][k], acc[ai][bj][m][n], 0, 0, 0); __builtin_amdgcn_s_setprio(0); } while (0)
; #define PG8_WAIT_V(n) asm volatile("s_waitcnt vmcnt(" #n ")" ::: "memory")
; #define PG8_WAIT_L(n) asm volatile("s_waitcnt lgkmcnt(" #n ")" ::: "memory")
; template <class Epi, class Sched, bool ALIGN_EPI, class Hook = NoHook>
; __device__ __forceinline__ void gemm_phase(LAS unsigned char* lds, const Gemm g, const Sched& S, const Epi& E, const Hook& H = Hook()) {
;     ...
;         for (int t = tb; t < te; t += 2) {
;             const bool last = (t == nt - 2);
;             const char* a1 = cA + (size_t)(t + 1) * kstep;
;             const char* a2 = last ? nA : cA + (size_t)(t + 2) * kstep; const char* b2 = last ? nB : cB + (size_t)(t + 2) * kstep;
;             const char* a3 = a2 + kstep; const char* b3 = b2 + kstep;
;             if (last && has_next) S.a_ready(nxt);
;             PG8_LDB(B0, 0, 0); PG8_LDB(B1, 0, 1); PG8_SCHED; PG8_LDA(At, 0, 0); PG8_STAGE(PG8_SA(1, 1), a1 + hA, voffA);
;             PG8_WAIT_V(8); PG8_WAIT_L(0); PG8_BAR; PG8_MMA(0, 0, At, B0); PG8_MMA(0, 1, At, B1); PG8_BAR; PG8_SCHED;
;             PG8_LDA(At, 0, 1); PG8_STAGE(PG8_SB(0, 0), b2, voffB); PG8_STAGE(PG8_SB(0, 1), b2 + hB, voffB); PG8_STAGE(PG8_SA(0, 0), a2, voffA);
;             PG8_WAIT_V(8); PG8_WAIT_L(0); PG8_BAR; PG8_MMA(1, 0, At, B0); PG8_MMA(1, 1, At, B1); PG8_BAR; PG8_SCHED;
.LBB0_1001:
	ds_read_b128 v[106:109], v246
	ds_read_b128 v[110:113], v246 offset:1024
	s_add_u32 s42, s6, 0x100
	s_addc_u32 s43, s7, 0
	s_cmp_eq_u32 s70, 60
	s_cselect_b32 s47, s35, s43
	s_cselect_b32 s46, s66, s42
	s_cselect_b32 s45, s31, s69
	s_cselect_b32 s44, s67, s68
	s_add_i32 m0, s51, 0xc000
	s_nop 0
	global_load_lds_dwordx4 v236, s[6:7]
	ds_read_b128 v[114:117], v246 offset:2048
	ds_read_b128 v[118:121], v246 offset:3072
	ds_read_b128 v[122:125], v247
	ds_read_b128 v[126:129], v247 offset:1024
	ds_read_b128 v[130:133], v247 offset:2048
	ds_read_b128 v[134:137], v247 offset:3072
	ds_read_b128 v[138:141], v248
	s_add_i32 m0, s51, 0xe000
	s_nop 0
	global_load_lds_dwordx4 v238, s[6:7]
	ds_read_b128 v[142:145], v248 offset:1024
	ds_read_b128 v[146:149], v248 offset:2048
	ds_read_b128 v[150:153], v248 offset:3072
	ds_read_b128 v[154:157], v248 offset:4096
	ds_read_b128 v[158:161], v248 offset:5120
	ds_read_b128 v[162:165], v248 offset:6144
	ds_read_b128 v[170:173], v248 offset:7168
	s_waitcnt vmcnt(8) lgkmcnt(0)
	s_barrier
	s_setprio 1
	v_mfma_f32_16x16x32_bf16 v[190:193], v[106:109], v[138:141], v[190:193]
	v_mfma_f32_16x16x32_bf16 v[178:181], v[114:117], v[138:141], v[178:181]
	v_mfma_f32_16x16x32_bf16 v[182:185], v[106:109], v[146:149], v[182:185]
	v_mfma_f32_16x16x32_bf16 v[98:101], v[114:117], v[146:149], v[98:101]
	v_mfma_f32_16x16x32_bf16 v[102:105], v[106:109], v[154:157], v[102:105]
	v_mfma_f32_16x16x32_bf16 v[86:89], v[114:117], v[154:157], v[86:89]
	v_mfma_f32_16x16x32_bf16 v[78:81], v[106:109], v[162:165], v[78:81]
	v_mfma_f32_16x16x32_bf16 v[70:73], v[114:117], v[162:165], v[70:73]
	v_mfma_f32_16x16x32_bf16 v[190:193], v[110:113], v[142:145], v[190:193]
	v_mfma_f32_16x16x32_bf16 v[178:181], v[118:121], v[142:145], v[178:181]
	v_mfma_f32_16x16x32_bf16 v[182:185], v[110:113], v[150:153], v[182:185]
	v_mfma_f32_16x16x32_bf16 v[98:101], v[118:121], v[150:153], v[98:101]
	v_mfma_f32_16x16x32_bf16 v[102:105], v[110:113], v[158:161], v[102:105]
	v_mfma_f32_16x16x32_bf16 v[86:89], v[118:121], v[158:161], v[86:89]
	v_mfma_f32_16x16x32_bf16 v[78:81], v[110:113], v[170:173], v[78:81]
	v_mfma_f32_16x16x32_bf16 v[70:73], v[118:121], v[170:173], v[70:73]
	v_mfma_f32_16x16x32_bf16 v[186:189], v[122:125], v[138:141], v[186:189]
	v_mfma_f32_16x16x32_bf16 v[138:141], v[130:133], v[138:141], v[174:177]
	v_mfma_f32_16x16x32_bf16 v[94:97], v[130:133], v[146:149], v[94:97]
	v_mfma_f32_16x16x32_bf16 v[90:93], v[122:125], v[154:157], v[90:93]
	v_mfma_f32_16x16x32_bf16 v[82:85], v[130:133], v[154:157], v[82:85]
	v_mfma_f32_16x16x32_bf16 v[74:77], v[122:125], v[162:165], v[74:77]
	v_mfma_f32_16x16x32_bf16 v[66:69], v[130:133], v[162:165], v[66:69]
	v_mfma_f32_16x16x32_bf16 v[186:189], v[126:129], v[142:145], v[186:189]
	v_mfma_f32_16x16x32_bf16 v[138:141], v[134:137], v[142:145], v[138:141]
	v_mfma_f32_16x16x32_bf16 v[142:145], v[122:125], v[146:149], v[166:169]
	v_mfma_f32_16x16x32_bf16 v[94:97], v[134:137], v[150:153], v[94:97]
	v_mfma_f32_16x16x32_bf16 v[90:93], v[126:129], v[158:161], v[90:93]
	v_mfma_f32_16x16x32_bf16 v[82:85], v[134:137], v[158:161], v[82:85]
	v_mfma_f32_16x16x32_bf16 v[74:77], v[126:129], v[170:173], v[74:77]
	v_mfma_f32_16x16x32_bf16 v[66:69], v[134:137], v[170:173], v[66:69]
	v_mfma_f32_16x16x32_bf16 v[142:145], v[126:129], v[150:153], v[142:145]
	s_barrier
	s_setprio 0
	s_add_i32 s6, s63, s29
	s_mov_b32 m0, s6
	ds_read_b128 v[146:149], v248 offset:16384
	ds_read_b128 v[150:153], v248 offset:17408
	global_load_lds_dwordx4 v232, s[44:45]
	ds_read_b128 v[154:157], v248 offset:18432
	s_add_i32 m0, s6, 0x2000
	s_add_u32 s6, s44, 0x100000
	s_addc_u32 s7, s45, 0
	s_add_i32 s71, s64, s29
	global_load_lds_dwordx4 v228, s[44:45]
	ds_read_b128 v[158:161], v248 offset:19456
	s_mov_b32 m0, s71
	s_nop 0
	global_load_lds_dwordx4 v232, s[6:7]
	ds_read_b128 v[162:165], v248 offset:20480
	s_add_i32 m0, s71, 0x2000
	s_nop 0
	global_load_lds_dwordx4 v228, s[6:7]
	ds_read_b128 v[166:169], v248 offset:21504
	s_mov_b32 m0, s51
	s_nop 0
	global_load_lds_dwordx4 v234, s[46:47]
	ds_read_b128 v[170:173], v248 offset:22528
	s_mov_b32 m0, s52
	s_nop 0
	global_load_lds_dwordx4 v230, s[46:47]
	ds_read_b128 v[174:177], v248 offset:23552
	s_waitcnt vmcnt(8) lgkmcnt(0)
	s_barrier
	s_setprio 1
	v_mfma_f32_16x16x32_bf16 v[62:65], v[106:109], v[146:149], v[62:65]
	v_mfma_f32_16x16x32_bf16 v[54:57], v[114:117], v[146:149], v[54:57]
	v_mfma_f32_16x16x32_bf16 v[46:49], v[106:109], v[154:157], v[46:49]
	v_mfma_f32_16x16x32_bf16 v[22:25], v[114:117], v[154:157], v[22:25]
	v_mfma_f32_16x16x32_bf16 v[42:45], v[106:109], v[162:165], v[42:45]
	v_mfma_f32_16x16x32_bf16 v[10:13], v[114:117], v[162:165], v[10:13]
	v_mfma_f32_16x16x32_bf16 v[38:41], v[106:109], v[170:173], v[38:41]
	v_mfma_f32_16x16x32_bf16 v[14:17], v[114:117], v[170:173], v[14:17]
	v_mfma_f32_16x16x32_bf16 v[62:65], v[110:113], v[150:153], v[62:65]
	v_mfma_f32_16x16x32_bf16 v[54:57], v[118:121], v[150:153], v[54:57]
	v_mfma_f32_16x16x32_bf16 v[46:49], v[110:113], v[158:161], v[46:49]
	v_mfma_f32_16x16x32_bf16 v[22:25], v[118:121], v[158:161], v[22:25]
	v_mfma_f32_16x16x32_bf16 v[42:45], v[110:113], v[166:169], v[42:45]
	v_mfma_f32_16x16x32_bf16 v[10:13], v[118:121], v[166:169], v[10:13]
	v_mfma_f32_16x16x32_bf16 v[38:41], v[110:113], v[174:177], v[38:41]
	v_mfma_f32_16x16x32_bf16 v[14:17], v[118:121], v[174:177], v[14:17]
	v_mfma_f32_16x16x32_bf16 v[58:61], v[122:125], v[146:149], v[58:61]
	v_mfma_f32_16x16x32_bf16 v[50:53], v[130:133], v[146:149], v[50:53]
	v_mfma_f32_16x16x32_bf16 v[34:37], v[122:125], v[154:157], v[34:37]
	v_mfma_f32_16x16x32_bf16 v[18:21], v[130:133], v[154:157], v[18:21]
	v_mfma_f32_16x16x32_bf16 v[30:33], v[122:125], v[162:165], v[30:33]
	v_mfma_f32_16x16x32_bf16 v[2:5], v[130:133], v[162:165], v[2:5]
	v_mfma_f32_16x16x32_bf16 v[26:29], v[122:125], v[170:173], v[26:29]
	v_mfma_f32_16x16x32_bf16 v[6:9], v[130:133], v[170:173], v[6:9]
	v_mfma_f32_16x16x32_bf16 v[58:61], v[126:129], v[150:153], v[58:61]
	v_mfma_f32_16x16x32_bf16 v[50:53], v[134:137], v[150:153], v[50:53]
	v_mfma_f32_16x16x32_bf16 v[34:37], v[126:129], v[158:161], v[34:37]
	v_mfma_f32_16x16x32_bf16 v[18:21], v[134:137], v[158:161], v[18:21]
	v_mfma_f32_16x16x32_bf16 v[30:33], v[126:129], v[166:169], v[30:33]
	v_mfma_f32_16x16x32_bf16 v[2:5], v[134:137], v[166:169], v[2:5]
	v_mfma_f32_16x16x32_bf16 v[26:29], v[126:129], v[174:177], v[26:29]
	v_mfma_f32_16x16x32_bf16 v[6:9], v[134:137], v[174:177], v[6:9]
	s_barrier
; #define PG8_STAGE(bufoff, gbase, voff) do { _Pragma("unroll") for (int _i = 0; _i < 2; ++_i) \
;         __builtin_amdgcn_global_load_lds((const unsigned*)((const char*)(gbase) + (voff)[_i]), (LAS unsigned*)(lds + (bufoff) + ldsw + _i * 8192), 16, 0, 0); } while (0)
; #define PG8_LDA(dst, b, h) do { _Pragma("unroll") for (int m = 0; m < 4; ++m) _Pragma("unroll") for (int k = 0; k < 2; ++k) dst[m][k] = *(const LAS bf16x8*)(lds + PG8_SA(b, h) + aoff + m * 2048 + k * 1024); } while (0)
; #define PG8_LDB(dst, b, h) do { _Pragma("unroll") for (int n = 0; n < 2; ++n) _Pragma("unroll") for (int k = 0; k < 2; ++k) dst[n][k] = *(const LAS bf16x8*)(lds + PG8_SB(b, h) + boff + n * 2048 + k * 1024); } while (0)
; #define PG8_MMA(ai, bj, At, Bt) do { __builtin_amdgcn_s_setprio(1); _Pragma("unroll") for (int m = 0; m < 4; ++m) _Pragma("unroll") for (int n = 0; n < 2; ++n) _Pragma("unroll") for (int k = 0; k < 2; ++k) \
;         acc[ai][bj][m][n] = __builtin_amdgcn_mfma_f32_16x16x32_bf16(Bt[n][k], At[m][k], acc[ai][bj][m][n], 0, 0, 0); __builtin_amdgcn_s_setprio(0); } while (0)
; #define PG8_WAIT_V(n) asm volatile("s_waitcnt vmcnt(" #n ")" ::: "memory")
; #define PG8_WAIT_L(n) asm volatile("s_waitcnt lgkmcnt(" #n ")" ::: "memory")
; #define PG8_BAR __builtin_amdgcn_s_barrier()
; #define PG8_SCHED __builtin_amdgcn_sched_barrier(0)
; template <class Epi, class Sched, bool ALIGN_EPI, class Hook = NoHook>
; __device__ __forceinline__ void gemm_phase(LAS unsigned char* lds, const Gemm g, const Sched& S, const Epi& E, const Hook& H = Hook()) {
;     ...
;             PG8_LDB(B0, 1, 0); PG8_LDB(B1, 1, 1); PG8_SCHED; PG8_LDA(At, 1, 0); PG8_STAGE(PG8_SA(0, 1), a2 + hA, voffA);
;             PG8_WAIT_V(8); PG8_WAIT_L(0); PG8_BAR; PG8_MMA(0, 0, At, B0); PG8_MMA(0, 1, At, B1); PG8_BAR; PG8_SCHED;
;             PG8_LDA(At, 1, 1); PG8_STAGE(PG8_SB(1, 0), b3, voffB); PG8_STAGE(PG8_SB(1, 1), b3 + hB, voffB); PG8_STAGE(PG8_SA(1, 0), a3, voffA);
;             PG8_WAIT_V(8); PG8_WAIT_L(0); PG8_BAR; PG8_MMA(1, 0, At, B0); PG8_MMA(1, 1, At, B1); PG8_BAR; PG8_SCHED;
;         }
;         if constexpr (Hook::ON) H.after(te, acc, cur, wr, wc, fr, fq);
;         }
;         if constexpr (ALIGN_EPI) { if (wr == 0) PG8_BAR; }
	s_setprio 0
	s_add_i32 s71, 0, 0x18000
	s_add_i32 s72, 0, 0x1c000
	v_add_u32_e32 v118, s71, v245
	v_add_u32_e32 v134, s72, v245
	ds_read_b128 v[106:109], v118
	ds_read_b128 v[110:113], v118 offset:1024
	s_add_u32 s6, s46, 0x8000
	s_addc_u32 s7, s47, 0
	s_mov_b32 m0, s53
	s_nop 0
	global_load_lds_dwordx4 v234, s[6:7]
	ds_read_b128 v[114:117], v118 offset:2048
	ds_read_b128 v[118:121], v118 offset:3072
	ds_read_b128 v[122:125], v134
	ds_read_b128 v[126:129], v134 offset:1024
	ds_read_b128 v[130:133], v134 offset:2048
	ds_read_b128 v[134:137], v134 offset:3072
	ds_read_b128 v[146:149], v248 offset:32768
	s_mov_b32 m0, s54
	s_nop 0
	global_load_lds_dwordx4 v230, s[6:7]
	ds_read_b128 v[150:153], v248 offset:33792
	ds_read_b128 v[154:157], v248 offset:34816
	ds_read_b128 v[158:161], v248 offset:35840
	ds_read_b128 v[162:165], v248 offset:36864
	ds_read_b128 v[170:173], v248 offset:37888
	ds_read_b128 v[194:197], v248 offset:38912
	ds_read_b128 v[198:201], v248 offset:39936
	s_waitcnt vmcnt(8) lgkmcnt(0)
	s_barrier
	s_setprio 1
	v_mfma_f32_16x16x32_bf16 v[166:169], v[106:109], v[146:149], v[190:193]
	v_mfma_f32_16x16x32_bf16 v[190:193], v[110:113], v[150:153], v[166:169]
	v_mfma_f32_16x16x32_bf16 v[166:169], v[114:117], v[146:149], v[178:181]
	v_mfma_f32_16x16x32_bf16 v[178:181], v[118:121], v[150:153], v[166:169]
	v_mfma_f32_16x16x32_bf16 v[166:169], v[106:109], v[154:157], v[182:185]
	v_mfma_f32_16x16x32_bf16 v[98:101], v[114:117], v[154:157], v[98:101]
	v_mfma_f32_16x16x32_bf16 v[102:105], v[106:109], v[162:165], v[102:105]
	v_mfma_f32_16x16x32_bf16 v[86:89], v[114:117], v[162:165], v[86:89]
	v_mfma_f32_16x16x32_bf16 v[78:81], v[106:109], v[194:197], v[78:81]
	v_mfma_f32_16x16x32_bf16 v[70:73], v[114:117], v[194:197], v[70:73]
	v_mfma_f32_16x16x32_bf16 v[182:185], v[110:113], v[158:161], v[166:169]
	v_mfma_f32_16x16x32_bf16 v[98:101], v[118:121], v[158:161], v[98:101]
	v_mfma_f32_16x16x32_bf16 v[102:105], v[110:113], v[170:173], v[102:105]
	v_mfma_f32_16x16x32_bf16 v[86:89], v[118:121], v[170:173], v[86:89]
	v_mfma_f32_16x16x32_bf16 v[78:81], v[110:113], v[198:201], v[78:81]
	v_mfma_f32_16x16x32_bf16 v[70:73], v[118:121], v[198:201], v[70:73]
	v_mfma_f32_16x16x32_bf16 v[138:141], v[130:133], v[146:149], v[138:141]
	v_mfma_f32_16x16x32_bf16 v[166:169], v[122:125], v[146:149], v[186:189]
	v_mfma_f32_16x16x32_bf16 v[174:177], v[134:137], v[150:153], v[138:141]
	v_mfma_f32_16x16x32_bf16 v[138:141], v[122:125], v[154:157], v[142:145]
	v_mfma_f32_16x16x32_bf16 v[94:97], v[130:133], v[154:157], v[94:97]
	v_mfma_f32_16x16x32_bf16 v[90:93], v[122:125], v[162:165], v[90:93]
	v_mfma_f32_16x16x32_bf16 v[82:85], v[130:133], v[162:165], v[82:85]
	v_mfma_f32_16x16x32_bf16 v[74:77], v[122:125], v[194:197], v[74:77]
	v_mfma_f32_16x16x32_bf16 v[66:69], v[130:133], v[194:197], v[66:69]
	v_mfma_f32_16x16x32_bf16 v[186:189], v[126:129], v[150:153], v[166:169]
	v_mfma_f32_16x16x32_bf16 v[166:169], v[126:129], v[158:161], v[138:141]
	v_mfma_f32_16x16x32_bf16 v[94:97], v[134:137], v[158:161], v[94:97]
	v_mfma_f32_16x16x32_bf16 v[90:93], v[126:129], v[170:173], v[90:93]
	v_mfma_f32_16x16x32_bf16 v[82:85], v[134:137], v[170:173], v[82:85]
	v_mfma_f32_16x16x32_bf16 v[74:77], v[126:129], v[198:201], v[74:77]
	v_mfma_f32_16x16x32_bf16 v[66:69], v[134:137], v[198:201], v[66:69]
	s_barrier
	s_setprio 0
	s_add_i32 s6, s71, s29
	s_add_u32 s74, s44, s14
	s_addc_u32 s75, s45, s15
	s_mov_b32 m0, s6
	ds_read_b128 v[138:141], v248 offset:49152
	ds_read_b128 v[142:145], v248 offset:50176
	global_load_lds_dwordx4 v232, s[74:75]
	ds_read_b128 v[146:149], v248 offset:51200
	s_add_i32 m0, s6, 0x2000
	s_add_u32 s6, s44, 0x100080
	s_addc_u32 s7, s45, 0
	s_add_i32 s44, s72, s29
	global_load_lds_dwordx4 v228, s[74:75]
	ds_read_b128 v[150:153], v248 offset:52224
	s_mov_b32 m0, s44
	s_nop 0
	global_load_lds_dwordx4 v232, s[6:7]
	ds_read_b128 v[154:157], v248 offset:53248
	s_add_i32 m0, s44, 0x2000
	s_nop 0
	global_load_lds_dwordx4 v228, s[6:7]
	ds_read_b128 v[158:161], v248 offset:54272
	s_add_u32 s78, s46, s14
	s_addc_u32 s79, s47, s15
	s_mov_b32 m0, s57
	s_nop 0
	global_load_lds_dwordx4 v234, s[78:79]
	ds_read_b128 v[162:165], v248 offset:55296
	s_mov_b32 m0, s58
	s_nop 0
	global_load_lds_dwordx4 v230, s[78:79]
	s_add_i32 s70, s70, 2
	s_add_u32 s68, s68, 0x100
	s_addc_u32 s69, s69, 0
	s_cmp_gt_u32 s70, 61
	s_mov_b64 s[6:7], s[42:43]
	ds_read_b128 v[170:173], v248 offset:56320
	s_waitcnt vmcnt(8) lgkmcnt(0)
	s_barrier
	s_setprio 1
	v_mfma_f32_16x16x32_bf16 v[62:65], v[106:109], v[138:141], v[62:65]
	v_mfma_f32_16x16x32_bf16 v[54:57], v[114:117], v[138:141], v[54:57]
	v_mfma_f32_16x16x32_bf16 v[46:49], v[106:109], v[146:149], v[46:49]
	v_mfma_f32_16x16x32_bf16 v[22:25], v[114:117], v[146:149], v[22:25]
	v_mfma_f32_16x16x32_bf16 v[42:45], v[106:109], v[154:157], v[42:45]
	v_mfma_f32_16x16x32_bf16 v[10:13], v[114:117], v[154:157], v[10:13]
	v_mfma_f32_16x16x32_bf16 v[38:41], v[106:109], v[162:165], v[38:41]
	v_mfma_f32_16x16x32_bf16 v[14:17], v[114:117], v[162:165], v[14:17]
	v_mfma_f32_16x16x32_bf16 v[62:65], v[110:113], v[142:145], v[62:65]
	v_mfma_f32_16x16x32_bf16 v[54:57], v[118:121], v[142:145], v[54:57]
	v_mfma_f32_16x16x32_bf16 v[46:49], v[110:113], v[150:153], v[46:49]
	v_mfma_f32_16x16x32_bf16 v[22:25], v[118:121], v[150:153], v[22:25]
	v_mfma_f32_16x16x32_bf16 v[42:45], v[110:113], v[158:161], v[42:45]
	v_mfma_f32_16x16x32_bf16 v[10:13], v[118:121], v[158:161], v[10:13]
	v_mfma_f32_16x16x32_bf16 v[38:41], v[110:113], v[170:173], v[38:41]
	v_mfma_f32_16x16x32_bf16 v[14:17], v[118:121], v[170:173], v[14:17]
	v_mfma_f32_16x16x32_bf16 v[58:61], v[122:125], v[138:141], v[58:61]
	v_mfma_f32_16x16x32_bf16 v[50:53], v[130:133], v[138:141], v[50:53]
	v_mfma_f32_16x16x32_bf16 v[34:37], v[122:125], v[146:149], v[34:37]
	v_mfma_f32_16x16x32_bf16 v[18:21], v[130:133], v[146:149], v[18:21]
	v_mfma_f32_16x16x32_bf16 v[30:33], v[122:125], v[154:157], v[30:33]
	v_mfma_f32_16x16x32_bf16 v[2:5], v[130:133], v[154:157], v[2:5]
	v_mfma_f32_16x16x32_bf16 v[26:29], v[122:125], v[162:165], v[26:29]
	v_mfma_f32_16x16x32_bf16 v[6:9], v[130:133], v[162:165], v[6:9]
	v_mfma_f32_16x16x32_bf16 v[58:61], v[126:129], v[142:145], v[58:61]
	v_mfma_f32_16x16x32_bf16 v[50:53], v[134:137], v[142:145], v[50:53]
	v_mfma_f32_16x16x32_bf16 v[34:37], v[126:129], v[150:153], v[34:37]
	v_mfma_f32_16x16x32_bf16 v[18:21], v[134:137], v[150:153], v[18:21]
	v_mfma_f32_16x16x32_bf16 v[30:33], v[126:129], v[158:161], v[30:33]
	v_mfma_f32_16x16x32_bf16 v[2:5], v[134:137], v[158:161], v[2:5]
	v_mfma_f32_16x16x32_bf16 v[26:29], v[126:129], v[170:173], v[26:29]
	v_mfma_f32_16x16x32_bf16 v[6:9], v[134:137], v[170:173], v[6:9]
	s_barrier
	s_setprio 0
	s_cbranch_scc0 .LBB0_1001
	s_and_b64 vcc, exec, s[2:3]
	s_cbranch_vccz .LBB0_1004
	s_barrier

; #define PG8_STAGE(bufoff, gbase, voff) do { _Pragma("unroll") for (int _i = 0; _i < 2; ++_i) \
;         __builtin_amdgcn_global_load_lds((const unsigned*)((const char*)(gbase) + (voff)[_i]), (LAS unsigned*)(lds + (bufoff) + ldsw + _i * 8192), 16, 0, 0); } while (0)
; #define PG8_LDA(dst, b, h) do { _Pragma("unroll") for (int m = 0; m < 4; ++m) _Pragma("unroll") for (int k = 0; k < 2; ++k) dst[m][k] = *(const LAS bf16x8*)(lds + PG8_SA(b, h) + aoff + m * 2048 + k * 1024); } while (0)
; #define PG8_LDB(dst, b, h) do { _Pragma("unroll") for (int n = 0; n < 2; ++n) _Pragma("unroll") for (int k = 0; k < 2; ++k) dst[n][k] = *(const LAS bf16x8*)(lds + PG8_SB(b, h) + boff + n * 2048 + k * 1024); } while (0)
; #define PG8_MMA(ai, bj, At, Bt) do { __builtin_amdgcn_s_setprio(1); _Pragma("unroll") for (int m = 0; m < 4; ++m) _Pragma("unroll") for (int n = 0; n < 2; ++n) _Pragma("unroll") for (int k = 0; k < 2; ++k) \
;         acc[ai][bj][m][n] = __builtin_amdgcn_mfma_f32_16x16x32_bf16(Bt[n][k], At[m][k], acc[ai][bj][m][n], 0, 0, 0); __builtin_amdgcn_s_setprio(0); } while (0)
; #define PG8_WAIT_V(n) asm volatile("s_waitcnt vmcnt(" #n ")" ::: "memory")
; #define PG8_WAIT_L(n) asm volatile("s_waitcnt lgkmcnt(" #n ")" ::: "memory")
; template <class Epi, class Sched, bool ALIGN_EPI, class Hook = NoHook>
; __device__ __forceinline__ void gemm_phase(LAS unsigned char* lds, const Gemm g, const Sched& S, const Epi& E, const Hook& H = Hook()) {
;     ...
;         for (int t = tb; t < te; t += 2) {
;             const bool last = (t == nt - 2);
;             const char* a1 = cA + (size_t)(t + 1) * kstep;
;             const char* a2 = last ? nA : cA + (size_t)(t + 2) * kstep; const char* b2 = last ? nB : cB + (size_t)(t + 2) * kstep;
;             const char* a3 = a2 + kstep; const char* b3 = b2 + kstep;
;             if (last && has_next) S.a_ready(nxt);
;             PG8_LDB(B0, 0, 0); PG8_LDB(B1, 0, 1); PG8_SCHED; PG8_LDA(At, 0, 0); PG8_STAGE(PG8_SA(1, 1), a1 + hA, voffA);
;             PG8_WAIT_V(8); PG8_WAIT_L(0); PG8_BAR; PG8_MMA(0, 0, At, B0); PG8_MMA(0, 1, At, B1); PG8_BAR; PG8_SCHED;
;             PG8_LDA(At, 0, 1); PG8_STAGE(PG8_SB(0, 0), b2, voffB); PG8_STAGE(PG8_SB(0, 1), b2 + hB, voffB); PG8_STAGE(PG8_SA(0, 0), a2, voffA);
;             PG8_WAIT_V(8); PG8_WAIT_L(0); PG8_BAR; PG8_MMA(1, 0, At, B0); PG8_MMA(1, 1, At, B1); PG8_BAR; PG8_SCHED;
.LBB0_1360:
	ds_read_b128 v[146:149], v1
	ds_read_b128 v[150:153], v1 offset:1024
	s_add_u32 s14, s4, 0xbb050080
	s_addc_u32 s15, s5, -1
	s_cmpk_lg_i32 s41, 0xa8
	s_cselect_b32 s14, s14, 0
	s_cselect_b32 s15, s15, 0
	s_add_u32 s20, s0, s14
	s_addc_u32 s21, s1, s15
	s_add_u32 s14, s12, s14
	s_addc_u32 s15, s13, s15
	s_mov_b32 m0, s42
	ds_read_b128 v[154:157], v1 offset:2048
	ds_read_b128 v[158:161], v1 offset:3072
	ds_read_b128 v[164:167], v142
	ds_read_b128 v[170:173], v142 offset:1024
	ds_read_b128 v[174:177], v142 offset:2048
	ds_read_b128 v[178:181], v142 offset:3072
	v_lshl_add_u64 v[214:215], v[138:139], 0, s[4:5]
	global_load_lds_dwordx4 v[214:215], off
	ds_read_b128 v[182:185], v143
	ds_read_b128 v[186:189], v143 offset:1024
	ds_read_b128 v[190:193], v143 offset:2048
	ds_read_b128 v[194:197], v143 offset:3072
	ds_read_b128 v[198:201], v143 offset:4096
	ds_read_b128 v[202:205], v143 offset:5120
	ds_read_b128 v[206:209], v143 offset:6144
	ds_read_b128 v[210:213], v143 offset:7168
	v_lshl_add_u64 v[214:215], v[140:141], 0, s[4:5]
	s_mov_b32 m0, s43
	s_nop 0
	global_load_lds_dwordx4 v[214:215], off
	s_waitcnt vmcnt(8) lgkmcnt(0)
	s_barrier
	s_setprio 1
	v_mfma_f32_16x16x32_bf16 v[82:85], v[146:149], v[182:185], v[82:85]
	v_mfma_f32_16x16x32_bf16 v[54:57], v[154:157], v[182:185], v[54:57]
	v_mfma_f32_16x16x32_bf16 v[58:61], v[146:149], v[190:193], v[58:61]
	v_mfma_f32_16x16x32_bf16 v[42:45], v[154:157], v[190:193], v[42:45]
	v_mfma_f32_16x16x32_bf16 v[70:73], v[146:149], v[198:201], v[70:73]
	v_mfma_f32_16x16x32_bf16 v[50:53], v[154:157], v[198:201], v[50:53]
	v_mfma_f32_16x16x32_bf16 v[86:89], v[146:149], v[206:209], v[86:89]
	v_mfma_f32_16x16x32_bf16 v[74:77], v[154:157], v[206:209], v[74:77]
	v_mfma_f32_16x16x32_bf16 v[82:85], v[150:153], v[186:189], v[82:85]
	v_mfma_f32_16x16x32_bf16 v[54:57], v[158:161], v[186:189], v[54:57]
	v_mfma_f32_16x16x32_bf16 v[58:61], v[150:153], v[194:197], v[58:61]
	v_mfma_f32_16x16x32_bf16 v[42:45], v[158:161], v[194:197], v[42:45]
	v_mfma_f32_16x16x32_bf16 v[70:73], v[150:153], v[202:205], v[70:73]
	v_mfma_f32_16x16x32_bf16 v[50:53], v[158:161], v[202:205], v[50:53]
	v_mfma_f32_16x16x32_bf16 v[86:89], v[150:153], v[210:213], v[86:89]
	v_mfma_f32_16x16x32_bf16 v[74:77], v[158:161], v[210:213], v[74:77]
	v_mfma_f32_16x16x32_bf16 v[14:17], v[164:167], v[182:185], v[14:17]
	v_mfma_f32_16x16x32_bf16 v[2:5], v[174:177], v[182:185], v[2:5]
	v_mfma_f32_16x16x32_bf16 v[18:21], v[164:167], v[190:193], v[18:21]
	v_mfma_f32_16x16x32_bf16 v[6:9], v[174:177], v[190:193], v[6:9]
	v_mfma_f32_16x16x32_bf16 v[22:25], v[164:167], v[198:201], v[22:25]
	v_mfma_f32_16x16x32_bf16 v[10:13], v[174:177], v[198:201], v[10:13]
	v_mfma_f32_16x16x32_bf16 v[30:33], v[164:167], v[206:209], v[30:33]
	v_mfma_f32_16x16x32_bf16 v[26:29], v[174:177], v[206:209], v[26:29]
	v_mfma_f32_16x16x32_bf16 v[14:17], v[170:173], v[186:189], v[14:17]
	v_mfma_f32_16x16x32_bf16 v[2:5], v[178:181], v[186:189], v[2:5]
	v_mfma_f32_16x16x32_bf16 v[18:21], v[170:173], v[194:197], v[18:21]
	v_mfma_f32_16x16x32_bf16 v[6:9], v[178:181], v[194:197], v[6:9]
	v_mfma_f32_16x16x32_bf16 v[22:25], v[170:173], v[202:205], v[22:25]
	v_mfma_f32_16x16x32_bf16 v[10:13], v[178:181], v[202:205], v[10:13]
	v_mfma_f32_16x16x32_bf16 v[30:33], v[170:173], v[210:213], v[30:33]
	v_mfma_f32_16x16x32_bf16 v[26:29], v[178:181], v[210:213], v[26:29]
	s_barrier
	s_setprio 0
	s_mov_b32 m0, s44
	s_add_u32 s52, s14, 0x2b0000
	ds_read_b128 v[182:185], v143 offset:16384
	ds_read_b128 v[186:189], v143 offset:17408
	global_load_lds_dwordx4 v132, s[14:15]
	ds_read_b128 v[190:193], v143 offset:18432
	s_mov_b32 m0, s45
	s_addc_u32 s53, s15, 0
	global_load_lds_dwordx4 v136, s[14:15]
	ds_read_b128 v[194:197], v143 offset:19456
	s_mov_b32 m0, s46
	s_nop 0
	global_load_lds_dwordx4 v132, s[52:53]
	ds_read_b128 v[198:201], v143 offset:20480
	s_mov_b32 m0, s47
	s_nop 0
	global_load_lds_dwordx4 v136, s[52:53]
	ds_read_b128 v[202:205], v143 offset:21504
	s_add_u32 s56, s20, s2
	s_addc_u32 s57, s21, s3
	s_mov_b32 m0, s25
	s_nop 0
	global_load_lds_dwordx4 v130, s[20:21]
	ds_read_b128 v[206:209], v143 offset:22528
	s_mov_b32 m0, s27
	s_nop 0
	global_load_lds_dwordx4 v134, s[20:21]
	ds_read_b128 v[210:213], v143 offset:23552
	s_waitcnt vmcnt(8) lgkmcnt(0)
	s_barrier
	s_setprio 1
	v_mfma_f32_16x16x32_bf16 v[94:97], v[146:149], v[182:185], v[94:97]
	v_mfma_f32_16x16x32_bf16 v[90:93], v[154:157], v[182:185], v[90:93]
	v_mfma_f32_16x16x32_bf16 v[106:109], v[146:149], v[190:193], v[106:109]
	v_mfma_f32_16x16x32_bf16 v[98:101], v[154:157], v[190:193], v[98:101]
	v_mfma_f32_16x16x32_bf16 v[110:113], v[146:149], v[198:201], v[110:113]
	v_mfma_f32_16x16x32_bf16 v[102:105], v[154:157], v[198:201], v[102:105]
	v_mfma_f32_16x16x32_bf16 v[126:129], v[146:149], v[206:209], v[126:129]
	v_mfma_f32_16x16x32_bf16 v[122:125], v[154:157], v[206:209], v[122:125]
	v_mfma_f32_16x16x32_bf16 v[94:97], v[150:153], v[186:189], v[94:97]
	v_mfma_f32_16x16x32_bf16 v[90:93], v[158:161], v[186:189], v[90:93]
	v_mfma_f32_16x16x32_bf16 v[106:109], v[150:153], v[194:197], v[106:109]
	v_mfma_f32_16x16x32_bf16 v[98:101], v[158:161], v[194:197], v[98:101]
	v_mfma_f32_16x16x32_bf16 v[110:113], v[150:153], v[202:205], v[110:113]
	v_mfma_f32_16x16x32_bf16 v[102:105], v[158:161], v[202:205], v[102:105]
	v_mfma_f32_16x16x32_bf16 v[126:129], v[150:153], v[210:213], v[126:129]
	v_mfma_f32_16x16x32_bf16 v[122:125], v[158:161], v[210:213], v[122:125]
	v_mfma_f32_16x16x32_bf16 v[38:41], v[164:167], v[182:185], v[38:41]
	v_mfma_f32_16x16x32_bf16 v[34:37], v[174:177], v[182:185], v[34:37]
	v_mfma_f32_16x16x32_bf16 v[66:69], v[164:167], v[190:193], v[66:69]
	v_mfma_f32_16x16x32_bf16 v[46:49], v[174:177], v[190:193], v[46:49]
	v_mfma_f32_16x16x32_bf16 v[78:81], v[164:167], v[198:201], v[78:81]
	v_mfma_f32_16x16x32_bf16 v[62:65], v[174:177], v[198:201], v[62:65]
	v_mfma_f32_16x16x32_bf16 v[118:121], v[164:167], v[206:209], v[118:121]
	v_mfma_f32_16x16x32_bf16 v[114:117], v[174:177], v[206:209], v[114:117]
	v_mfma_f32_16x16x32_bf16 v[38:41], v[170:173], v[186:189], v[38:41]
	v_mfma_f32_16x16x32_bf16 v[34:37], v[178:181], v[186:189], v[34:37]
	v_mfma_f32_16x16x32_bf16 v[66:69], v[170:173], v[194:197], v[66:69]
	v_mfma_f32_16x16x32_bf16 v[46:49], v[178:181], v[194:197], v[46:49]
	v_mfma_f32_16x16x32_bf16 v[78:81], v[170:173], v[202:205], v[78:81]
	v_mfma_f32_16x16x32_bf16 v[62:65], v[178:181], v[202:205], v[62:65]
	v_mfma_f32_16x16x32_bf16 v[118:121], v[170:173], v[210:213], v[118:121]
	v_mfma_f32_16x16x32_bf16 v[114:117], v[178:181], v[210:213], v[114:117]
	s_barrier
; #define PG8_STAGE(bufoff, gbase, voff) do { _Pragma("unroll") for (int _i = 0; _i < 2; ++_i) \
;         __builtin_amdgcn_global_load_lds((const unsigned*)((const char*)(gbase) + (voff)[_i]), (LAS unsigned*)(lds + (bufoff) + ldsw + _i * 8192), 16, 0, 0); } while (0)
; #define PG8_LDA(dst, b, h) do { _Pragma("unroll") for (int m = 0; m < 4; ++m) _Pragma("unroll") for (int k = 0; k < 2; ++k) dst[m][k] = *(const LAS bf16x8*)(lds + PG8_SA(b, h) + aoff + m * 2048 + k * 1024); } while (0)
; #define PG8_LDB(dst, b, h) do { _Pragma("unroll") for (int n = 0; n < 2; ++n) _Pragma("unroll") for (int k = 0; k < 2; ++k) dst[n][k] = *(const LAS bf16x8*)(lds + PG8_SB(b, h) + boff + n * 2048 + k * 1024); } while (0)
; #define PG8_MMA(ai, bj, At, Bt) do { __builtin_amdgcn_s_setprio(1); _Pragma("unroll") for (int m = 0; m < 4; ++m) _Pragma("unroll") for (int n = 0; n < 2; ++n) _Pragma("unroll") for (int k = 0; k < 2; ++k) \
;         acc[ai][bj][m][n] = __builtin_amdgcn_mfma_f32_16x16x32_bf16(Bt[n][k], At[m][k], acc[ai][bj][m][n], 0, 0, 0); __builtin_amdgcn_s_setprio(0); } while (0)
; #define PG8_WAIT_V(n) asm volatile("s_waitcnt vmcnt(" #n ")" ::: "memory")
; #define PG8_WAIT_L(n) asm volatile("s_waitcnt lgkmcnt(" #n ")" ::: "memory")
; #define PG8_BAR __builtin_amdgcn_s_barrier()
; #define PG8_SCHED __builtin_amdgcn_sched_barrier(0)
; template <class Epi, class Sched, bool ALIGN_EPI, class Hook = NoHook>
; __device__ __forceinline__ void gemm_phase(LAS unsigned char* lds, const Gemm g, const Sched& S, const Epi& E, const Hook& H = Hook()) {
;     ...
;             PG8_LDB(B0, 1, 0); PG8_LDB(B1, 1, 1); PG8_SCHED; PG8_LDA(At, 1, 0); PG8_STAGE(PG8_SA(0, 1), a2 + hA, voffA);
;             PG8_WAIT_V(8); PG8_WAIT_L(0); PG8_BAR; PG8_MMA(0, 0, At, B0); PG8_MMA(0, 1, At, B1); PG8_BAR; PG8_SCHED;
;             PG8_LDA(At, 1, 1); PG8_STAGE(PG8_SB(1, 0), b3, voffB); PG8_STAGE(PG8_SB(1, 1), b3 + hB, voffB); PG8_STAGE(PG8_SA(1, 0), a3, voffA);
;             PG8_WAIT_V(8); PG8_WAIT_L(0); PG8_BAR; PG8_MMA(1, 0, At, B0); PG8_MMA(1, 1, At, B1); PG8_BAR; PG8_SCHED;
;         }
;         if constexpr (Hook::ON) H.after(te, acc, cur, wr, wc, fr, fq);
;         }
;         if constexpr (ALIGN_EPI) { if (wr == 0) PG8_BAR; }
	s_setprio 0
	ds_read_b128 v[146:149], v144
	ds_read_b128 v[150:153], v144 offset:1024
	s_add_u32 s20, s20, 0x2b0000
	s_addc_u32 s21, s21, 0
	s_mov_b32 m0, s28
	s_nop 0
	global_load_lds_dwordx4 v130, s[20:21]
	ds_read_b128 v[154:157], v144 offset:2048
	ds_read_b128 v[158:161], v144 offset:3072
	ds_read_b128 v[164:167], v145
	ds_read_b128 v[170:173], v145 offset:1024
	ds_read_b128 v[174:177], v145 offset:2048
	ds_read_b128 v[178:181], v145 offset:3072
	ds_read_b128 v[182:185], v143 offset:32768
	s_mov_b32 m0, s38
	s_nop 0
	global_load_lds_dwordx4 v134, s[20:21]
	ds_read_b128 v[186:189], v143 offset:33792
	ds_read_b128 v[190:193], v143 offset:34816
	ds_read_b128 v[194:197], v143 offset:35840
	ds_read_b128 v[198:201], v143 offset:36864
	ds_read_b128 v[202:205], v143 offset:37888
	ds_read_b128 v[206:209], v143 offset:38912
	ds_read_b128 v[210:213], v143 offset:39936
	s_waitcnt vmcnt(8) lgkmcnt(0)
	s_barrier
	s_setprio 1
	v_mfma_f32_16x16x32_bf16 v[82:85], v[146:149], v[182:185], v[82:85]
	v_mfma_f32_16x16x32_bf16 v[54:57], v[154:157], v[182:185], v[54:57]
	v_mfma_f32_16x16x32_bf16 v[58:61], v[146:149], v[190:193], v[58:61]
	v_mfma_f32_16x16x32_bf16 v[42:45], v[154:157], v[190:193], v[42:45]
	v_mfma_f32_16x16x32_bf16 v[70:73], v[146:149], v[198:201], v[70:73]
	v_mfma_f32_16x16x32_bf16 v[50:53], v[154:157], v[198:201], v[50:53]
	v_mfma_f32_16x16x32_bf16 v[86:89], v[146:149], v[206:209], v[86:89]
	v_mfma_f32_16x16x32_bf16 v[74:77], v[154:157], v[206:209], v[74:77]
	v_mfma_f32_16x16x32_bf16 v[82:85], v[150:153], v[186:189], v[82:85]
	v_mfma_f32_16x16x32_bf16 v[54:57], v[158:161], v[186:189], v[54:57]
	v_mfma_f32_16x16x32_bf16 v[58:61], v[150:153], v[194:197], v[58:61]
	v_mfma_f32_16x16x32_bf16 v[42:45], v[158:161], v[194:197], v[42:45]
	v_mfma_f32_16x16x32_bf16 v[70:73], v[150:153], v[202:205], v[70:73]
	v_mfma_f32_16x16x32_bf16 v[50:53], v[158:161], v[202:205], v[50:53]
	v_mfma_f32_16x16x32_bf16 v[86:89], v[150:153], v[210:213], v[86:89]
	v_mfma_f32_16x16x32_bf16 v[74:77], v[158:161], v[210:213], v[74:77]
	v_mfma_f32_16x16x32_bf16 v[14:17], v[164:167], v[182:185], v[14:17]
	v_mfma_f32_16x16x32_bf16 v[2:5], v[174:177], v[182:185], v[2:5]
	v_mfma_f32_16x16x32_bf16 v[18:21], v[164:167], v[190:193], v[18:21]
	v_mfma_f32_16x16x32_bf16 v[6:9], v[174:177], v[190:193], v[6:9]
	v_mfma_f32_16x16x32_bf16 v[22:25], v[164:167], v[198:201], v[22:25]
	v_mfma_f32_16x16x32_bf16 v[10:13], v[174:177], v[198:201], v[10:13]
	v_mfma_f32_16x16x32_bf16 v[30:33], v[164:167], v[206:209], v[30:33]
	v_mfma_f32_16x16x32_bf16 v[26:29], v[174:177], v[206:209], v[26:29]
	v_mfma_f32_16x16x32_bf16 v[14:17], v[170:173], v[186:189], v[14:17]
	v_mfma_f32_16x16x32_bf16 v[2:5], v[178:181], v[186:189], v[2:5]
	v_mfma_f32_16x16x32_bf16 v[18:21], v[170:173], v[194:197], v[18:21]
	v_mfma_f32_16x16x32_bf16 v[6:9], v[178:181], v[194:197], v[6:9]
	v_mfma_f32_16x16x32_bf16 v[22:25], v[170:173], v[202:205], v[22:25]
	v_mfma_f32_16x16x32_bf16 v[10:13], v[178:181], v[202:205], v[10:13]
	v_mfma_f32_16x16x32_bf16 v[30:33], v[170:173], v[210:213], v[30:33]
	v_mfma_f32_16x16x32_bf16 v[26:29], v[178:181], v[210:213], v[26:29]
	s_barrier
	s_setprio 0
	s_mov_b32 m0, s48
	s_add_u32 s54, s14, s2
	s_addc_u32 s55, s15, s3
	s_add_u32 s14, s14, 0x2b0080
	ds_read_b128 v[182:185], v143 offset:49152
	ds_read_b128 v[186:189], v143 offset:50176
	global_load_lds_dwordx4 v132, s[54:55]
	ds_read_b128 v[190:193], v143 offset:51200
	s_mov_b32 m0, s49
	s_addc_u32 s15, s15, 0
	global_load_lds_dwordx4 v136, s[54:55]
	ds_read_b128 v[194:197], v143 offset:52224
	s_mov_b32 m0, s50
	s_nop 0
	global_load_lds_dwordx4 v132, s[14:15]
	ds_read_b128 v[198:201], v143 offset:53248
	s_mov_b32 m0, s51
	s_nop 0
	global_load_lds_dwordx4 v136, s[14:15]
	ds_read_b128 v[202:205], v143 offset:54272
	s_mov_b32 m0, s39
	s_nop 0
	global_load_lds_dwordx4 v130, s[56:57]
	ds_read_b128 v[206:209], v143 offset:55296
	s_mov_b32 m0, s40
	s_nop 0
	global_load_lds_dwordx4 v134, s[56:57]
	s_add_i32 s41, s41, 2
	s_add_u32 s4, s4, 0x100
	s_addc_u32 s5, s5, 0
	s_cmpk_gt_u32 s41, 0xa9
	ds_read_b128 v[210:213], v143 offset:56320
	s_waitcnt vmcnt(8) lgkmcnt(0)
	s_barrier
	s_setprio 1
	v_mfma_f32_16x16x32_bf16 v[94:97], v[146:149], v[182:185], v[94:97]
	v_mfma_f32_16x16x32_bf16 v[90:93], v[154:157], v[182:185], v[90:93]
	v_mfma_f32_16x16x32_bf16 v[106:109], v[146:149], v[190:193], v[106:109]
	v_mfma_f32_16x16x32_bf16 v[98:101], v[154:157], v[190:193], v[98:101]
	v_mfma_f32_16x16x32_bf16 v[110:113], v[146:149], v[198:201], v[110:113]
	v_mfma_f32_16x16x32_bf16 v[102:105], v[154:157], v[198:201], v[102:105]
	v_mfma_f32_16x16x32_bf16 v[126:129], v[146:149], v[206:209], v[126:129]
	v_mfma_f32_16x16x32_bf16 v[122:125], v[154:157], v[206:209], v[122:125]
	v_mfma_f32_16x16x32_bf16 v[94:97], v[150:153], v[186:189], v[94:97]
	v_mfma_f32_16x16x32_bf16 v[90:93], v[158:161], v[186:189], v[90:93]
	v_mfma_f32_16x16x32_bf16 v[106:109], v[150:153], v[194:197], v[106:109]
	v_mfma_f32_16x16x32_bf16 v[98:101], v[158:161], v[194:197], v[98:101]
	v_mfma_f32_16x16x32_bf16 v[110:113], v[150:153], v[202:205], v[110:113]
	v_mfma_f32_16x16x32_bf16 v[102:105], v[158:161], v[202:205], v[102:105]
	v_mfma_f32_16x16x32_bf16 v[126:129], v[150:153], v[210:213], v[126:129]
	v_mfma_f32_16x16x32_bf16 v[122:125], v[158:161], v[210:213], v[122:125]
	v_mfma_f32_16x16x32_bf16 v[38:41], v[164:167], v[182:185], v[38:41]
	v_mfma_f32_16x16x32_bf16 v[34:37], v[174:177], v[182:185], v[34:37]
	v_mfma_f32_16x16x32_bf16 v[66:69], v[164:167], v[190:193], v[66:69]
	v_mfma_f32_16x16x32_bf16 v[46:49], v[174:177], v[190:193], v[46:49]
	v_mfma_f32_16x16x32_bf16 v[78:81], v[164:167], v[198:201], v[78:81]
	v_mfma_f32_16x16x32_bf16 v[62:65], v[174:177], v[198:201], v[62:65]
	v_mfma_f32_16x16x32_bf16 v[118:121], v[164:167], v[206:209], v[118:121]
	v_mfma_f32_16x16x32_bf16 v[114:117], v[174:177], v[206:209], v[114:117]
	v_mfma_f32_16x16x32_bf16 v[38:41], v[170:173], v[186:189], v[38:41]
	v_mfma_f32_16x16x32_bf16 v[34:37], v[178:181], v[186:189], v[34:37]
	v_mfma_f32_16x16x32_bf16 v[66:69], v[170:173], v[194:197], v[66:69]
	v_mfma_f32_16x16x32_bf16 v[46:49], v[178:181], v[194:197], v[46:49]
	v_mfma_f32_16x16x32_bf16 v[78:81], v[170:173], v[202:205], v[78:81]
	v_mfma_f32_16x16x32_bf16 v[62:65], v[178:181], v[202:205], v[62:65]
	v_mfma_f32_16x16x32_bf16 v[118:121], v[170:173], v[210:213], v[118:121]
	v_mfma_f32_16x16x32_bf16 v[114:117], v[178:181], v[210:213], v[114:117]
	s_barrier
	s_setprio 0
	s_cbranch_scc0 .LBB0_1360
	s_cmpk_lt_u32 s26, 0x100
	s_cbranch_scc0 .LBB0_1363
	s_barrier

; #define PG8_STAGE(bufoff, gbase, voff) do { _Pragma("unroll") for (int _i = 0; _i < 2; ++_i) \
;         __builtin_amdgcn_global_load_lds((const unsigned*)((const char*)(gbase) + (voff)[_i]), (LAS unsigned*)(lds + (bufoff) + ldsw + _i * 8192), 16, 0, 0); } while (0)
; #define PG8_LDA(dst, b, h) do { _Pragma("unroll") for (int m = 0; m < 4; ++m) _Pragma("unroll") for (int k = 0; k < 2; ++k) dst[m][k] = *(const LAS bf16x8*)(lds + PG8_SA(b, h) + aoff + m * 2048 + k * 1024); } while (0)
; #define PG8_LDB(dst, b, h) do { _Pragma("unroll") for (int n = 0; n < 2; ++n) _Pragma("unroll") for (int k = 0; k < 2; ++k) dst[n][k] = *(const LAS bf16x8*)(lds + PG8_SB(b, h) + boff + n * 2048 + k * 1024); } while (0)
; #define PG8_MMA(ai, bj, At, Bt) do { __builtin_amdgcn_s_setprio(1); _Pragma("unroll") for (int m = 0; m < 4; ++m) _Pragma("unroll") for (int n = 0; n < 2; ++n) _Pragma("unroll") for (int k = 0; k < 2; ++k) \
;         acc[ai][bj][m][n] = __builtin_amdgcn_mfma_f32_16x16x32_bf16(Bt[n][k], At[m][k], acc[ai][bj][m][n], 0, 0, 0); __builtin_amdgcn_s_setprio(0); } while (0)
; #define PG8_WAIT_V(n) asm volatile("s_waitcnt vmcnt(" #n ")" ::: "memory")
; #define PG8_WAIT_L(n) asm volatile("s_waitcnt lgkmcnt(" #n ")" ::: "memory")
; template <class Epi, class Sched, bool ALIGN_EPI, class Hook = NoHook>
; __device__ __forceinline__ void gemm_phase(LAS unsigned char* lds, const Gemm g, const Sched& S, const Epi& E, const Hook& H = Hook()) {
;     ...
;         for (int t = tb; t < te; t += 2) {
;             const bool last = (t == nt - 2);
;             const char* a1 = cA + (size_t)(t + 1) * kstep;
;             const char* a2 = last ? nA : cA + (size_t)(t + 2) * kstep; const char* b2 = last ? nB : cB + (size_t)(t + 2) * kstep;
;             const char* a3 = a2 + kstep; const char* b3 = b2 + kstep;
;             if (last && has_next) S.a_ready(nxt);
;             PG8_LDB(B0, 0, 0); PG8_LDB(B1, 0, 1); PG8_SCHED; PG8_LDA(At, 0, 0); PG8_STAGE(PG8_SA(1, 1), a1 + hA, voffA);
;             PG8_WAIT_V(8); PG8_WAIT_L(0); PG8_BAR; PG8_MMA(0, 0, At, B0); PG8_MMA(0, 1, At, B1); PG8_BAR; PG8_SCHED;
;             PG8_LDA(At, 0, 1); PG8_STAGE(PG8_SB(0, 0), b2, voffB); PG8_STAGE(PG8_SB(0, 1), b2 + hB, voffB); PG8_STAGE(PG8_SA(0, 0), a2, voffA);
;             PG8_WAIT_V(8); PG8_WAIT_L(0); PG8_BAR; PG8_MMA(1, 0, At, B0); PG8_MMA(1, 1, At, B1); PG8_BAR; PG8_SCHED;
.LBB0_1406:
	ds_read_b128 v[146:149], v140
	ds_read_b128 v[150:153], v140 offset:1024
	s_add_u32 s10, s4, 0xbb050080
	s_addc_u32 s11, s5, -1
	s_cmpk_lg_i32 s18, 0xa8
	s_cselect_b32 s10, s10, 0
	s_cselect_b32 s11, s11, 0
	s_add_u32 s16, s0, s10
	s_addc_u32 s17, s1, s11
	s_add_u32 s10, s12, s10
	s_addc_u32 s11, s13, s11
	s_mov_b32 m0, s19
	ds_read_b128 v[154:157], v140 offset:2048
	ds_read_b128 v[158:161], v140 offset:3072
	ds_read_b128 v[170:173], v141
	ds_read_b128 v[174:177], v141 offset:1024
	ds_read_b128 v[178:181], v141 offset:2048
	ds_read_b128 v[182:185], v141 offset:3072
	v_lshl_add_u64 v[218:219], v[136:137], 0, s[4:5]
	global_load_lds_dwordx4 v[218:219], off
	ds_read_b128 v[186:189], v142
	ds_read_b128 v[190:193], v142 offset:1024
	ds_read_b128 v[194:197], v142 offset:2048
	ds_read_b128 v[198:201], v142 offset:3072
	ds_read_b128 v[202:205], v142 offset:4096
	ds_read_b128 v[206:209], v142 offset:5120
	ds_read_b128 v[210:213], v142 offset:6144
	ds_read_b128 v[214:217], v142 offset:7168
	v_lshl_add_u64 v[218:219], v[138:139], 0, s[4:5]
	s_mov_b32 m0, s31
	s_nop 0
	global_load_lds_dwordx4 v[218:219], off
	s_waitcnt vmcnt(8) lgkmcnt(0)
	s_barrier
	s_setprio 1
	v_mfma_f32_16x16x32_bf16 v[82:85], v[146:149], v[186:189], v[82:85]
	v_mfma_f32_16x16x32_bf16 v[54:57], v[154:157], v[186:189], v[54:57]
	v_mfma_f32_16x16x32_bf16 v[58:61], v[146:149], v[194:197], v[58:61]
	v_mfma_f32_16x16x32_bf16 v[42:45], v[154:157], v[194:197], v[42:45]
	v_mfma_f32_16x16x32_bf16 v[70:73], v[146:149], v[202:205], v[70:73]
	v_mfma_f32_16x16x32_bf16 v[50:53], v[154:157], v[202:205], v[50:53]
	v_mfma_f32_16x16x32_bf16 v[86:89], v[146:149], v[210:213], v[86:89]
	v_mfma_f32_16x16x32_bf16 v[74:77], v[154:157], v[210:213], v[74:77]
	v_mfma_f32_16x16x32_bf16 v[82:85], v[150:153], v[190:193], v[82:85]
	v_mfma_f32_16x16x32_bf16 v[54:57], v[158:161], v[190:193], v[54:57]
	v_mfma_f32_16x16x32_bf16 v[58:61], v[150:153], v[198:201], v[58:61]
	v_mfma_f32_16x16x32_bf16 v[42:45], v[158:161], v[198:201], v[42:45]
	v_mfma_f32_16x16x32_bf16 v[70:73], v[150:153], v[206:209], v[70:73]
	v_mfma_f32_16x16x32_bf16 v[50:53], v[158:161], v[206:209], v[50:53]
	v_mfma_f32_16x16x32_bf16 v[86:89], v[150:153], v[214:217], v[86:89]
	v_mfma_f32_16x16x32_bf16 v[74:77], v[158:161], v[214:217], v[74:77]
	v_mfma_f32_16x16x32_bf16 v[14:17], v[170:173], v[186:189], v[14:17]
	v_mfma_f32_16x16x32_bf16 v[2:5], v[178:181], v[186:189], v[2:5]
	v_mfma_f32_16x16x32_bf16 v[18:21], v[170:173], v[194:197], v[18:21]
	v_mfma_f32_16x16x32_bf16 v[6:9], v[178:181], v[194:197], v[6:9]
	v_mfma_f32_16x16x32_bf16 v[22:25], v[170:173], v[202:205], v[22:25]
	v_mfma_f32_16x16x32_bf16 v[10:13], v[178:181], v[202:205], v[10:13]
	v_mfma_f32_16x16x32_bf16 v[30:33], v[170:173], v[210:213], v[30:33]
	v_mfma_f32_16x16x32_bf16 v[26:29], v[178:181], v[210:213], v[26:29]
	v_mfma_f32_16x16x32_bf16 v[14:17], v[174:177], v[190:193], v[14:17]
	v_mfma_f32_16x16x32_bf16 v[2:5], v[182:185], v[190:193], v[2:5]
	v_mfma_f32_16x16x32_bf16 v[18:21], v[174:177], v[198:201], v[18:21]
	v_mfma_f32_16x16x32_bf16 v[6:9], v[182:185], v[198:201], v[6:9]
	v_mfma_f32_16x16x32_bf16 v[22:25], v[174:177], v[206:209], v[22:25]
	v_mfma_f32_16x16x32_bf16 v[10:13], v[182:185], v[206:209], v[10:13]
	v_mfma_f32_16x16x32_bf16 v[30:33], v[174:177], v[214:217], v[30:33]
	v_mfma_f32_16x16x32_bf16 v[26:29], v[182:185], v[214:217], v[26:29]
	s_barrier
	s_setprio 0
	s_mov_b32 m0, s33
	s_add_u32 s46, s10, 0x2b0000
	ds_read_b128 v[186:189], v142 offset:16384
	ds_read_b128 v[190:193], v142 offset:17408
	global_load_lds_dwordx4 v162, s[10:11]
	ds_read_b128 v[194:197], v142 offset:18432
	s_mov_b32 m0, s34
	s_addc_u32 s47, s11, 0
	global_load_lds_dwordx4 v134, s[10:11]
	ds_read_b128 v[198:201], v142 offset:19456
	s_mov_b32 m0, s35
	s_nop 0
	global_load_lds_dwordx4 v162, s[46:47]
	ds_read_b128 v[202:205], v142 offset:20480
	s_mov_b32 m0, s43
	s_nop 0
	global_load_lds_dwordx4 v134, s[46:47]
	ds_read_b128 v[206:209], v142 offset:21504
	s_add_u32 s54, s16, s2
	s_addc_u32 s55, s17, s3
	s_mov_b32 m0, s27
	s_nop 0
	global_load_lds_dwordx4 v130, s[16:17]
	ds_read_b128 v[210:213], v142 offset:22528
	s_mov_b32 m0, s28
	s_nop 0
	global_load_lds_dwordx4 v132, s[16:17]
	ds_read_b128 v[214:217], v142 offset:23552
	s_waitcnt vmcnt(8) lgkmcnt(0)
	s_barrier
	s_setprio 1
	v_mfma_f32_16x16x32_bf16 v[94:97], v[146:149], v[186:189], v[94:97]
	v_mfma_f32_16x16x32_bf16 v[90:93], v[154:157], v[186:189], v[90:93]
	v_mfma_f32_16x16x32_bf16 v[118:121], v[146:149], v[194:197], v[118:121]
	v_mfma_f32_16x16x32_bf16 v[98:101], v[154:157], v[194:197], v[98:101]
	v_mfma_f32_16x16x32_bf16 v[126:129], v[146:149], v[202:205], v[126:129]
	v_mfma_f32_16x16x32_bf16 v[110:113], v[154:157], v[202:205], v[110:113]
	v_mfma_f32_16x16x32_bf16 v[122:125], v[146:149], v[210:213], v[122:125]
	v_mfma_f32_16x16x32_bf16 v[114:117], v[154:157], v[210:213], v[114:117]
	v_mfma_f32_16x16x32_bf16 v[94:97], v[150:153], v[190:193], v[94:97]
	v_mfma_f32_16x16x32_bf16 v[90:93], v[158:161], v[190:193], v[90:93]
	v_mfma_f32_16x16x32_bf16 v[118:121], v[150:153], v[198:201], v[118:121]
	v_mfma_f32_16x16x32_bf16 v[98:101], v[158:161], v[198:201], v[98:101]
	v_mfma_f32_16x16x32_bf16 v[126:129], v[150:153], v[206:209], v[126:129]
	v_mfma_f32_16x16x32_bf16 v[110:113], v[158:161], v[206:209], v[110:113]
	v_mfma_f32_16x16x32_bf16 v[122:125], v[150:153], v[214:217], v[122:125]
	v_mfma_f32_16x16x32_bf16 v[114:117], v[158:161], v[214:217], v[114:117]
	v_mfma_f32_16x16x32_bf16 v[38:41], v[170:173], v[186:189], v[38:41]
	v_mfma_f32_16x16x32_bf16 v[34:37], v[178:181], v[186:189], v[34:37]
	v_mfma_f32_16x16x32_bf16 v[66:69], v[170:173], v[194:197], v[66:69]
	v_mfma_f32_16x16x32_bf16 v[46:49], v[178:181], v[194:197], v[46:49]
	v_mfma_f32_16x16x32_bf16 v[78:81], v[170:173], v[202:205], v[78:81]
	v_mfma_f32_16x16x32_bf16 v[62:65], v[178:181], v[202:205], v[62:65]
	v_mfma_f32_16x16x32_bf16 v[106:109], v[170:173], v[210:213], v[106:109]
	v_mfma_f32_16x16x32_bf16 v[102:105], v[178:181], v[210:213], v[102:105]
	v_mfma_f32_16x16x32_bf16 v[38:41], v[174:177], v[190:193], v[38:41]
	v_mfma_f32_16x16x32_bf16 v[34:37], v[182:185], v[190:193], v[34:37]
	v_mfma_f32_16x16x32_bf16 v[66:69], v[174:177], v[198:201], v[66:69]
	v_mfma_f32_16x16x32_bf16 v[46:49], v[182:185], v[198:201], v[46:49]
	v_mfma_f32_16x16x32_bf16 v[78:81], v[174:177], v[206:209], v[78:81]
	v_mfma_f32_16x16x32_bf16 v[62:65], v[182:185], v[206:209], v[62:65]
	v_mfma_f32_16x16x32_bf16 v[106:109], v[174:177], v[214:217], v[106:109]
	v_mfma_f32_16x16x32_bf16 v[102:105], v[182:185], v[214:217], v[102:105]
	s_barrier
; #define PG8_STAGE(bufoff, gbase, voff) do { _Pragma("unroll") for (int _i = 0; _i < 2; ++_i) \
;         __builtin_amdgcn_global_load_lds((const unsigned*)((const char*)(gbase) + (voff)[_i]), (LAS unsigned*)(lds + (bufoff) + ldsw + _i * 8192), 16, 0, 0); } while (0)
; #define PG8_LDA(dst, b, h) do { _Pragma("unroll") for (int m = 0; m < 4; ++m) _Pragma("unroll") for (int k = 0; k < 2; ++k) dst[m][k] = *(const LAS bf16x8*)(lds + PG8_SA(b, h) + aoff + m * 2048 + k * 1024); } while (0)
; #define PG8_LDB(dst, b, h) do { _Pragma("unroll") for (int n = 0; n < 2; ++n) _Pragma("unroll") for (int k = 0; k < 2; ++k) dst[n][k] = *(const LAS bf16x8*)(lds + PG8_SB(b, h) + boff + n * 2048 + k * 1024); } while (0)
; #define PG8_MMA(ai, bj, At, Bt) do { __builtin_amdgcn_s_setprio(1); _Pragma("unroll") for (int m = 0; m < 4; ++m) _Pragma("unroll") for (int n = 0; n < 2; ++n) _Pragma("unroll") for (int k = 0; k < 2; ++k) \
;         acc[ai][bj][m][n] = __builtin_amdgcn_mfma_f32_16x16x32_bf16(Bt[n][k], At[m][k], acc[ai][bj][m][n], 0, 0, 0); __builtin_amdgcn_s_setprio(0); } while (0)
; #define PG8_WAIT_V(n) asm volatile("s_waitcnt vmcnt(" #n ")" ::: "memory")
; #define PG8_WAIT_L(n) asm volatile("s_waitcnt lgkmcnt(" #n ")" ::: "memory")
; #define PG8_BAR __builtin_amdgcn_s_barrier()
; #define PG8_SCHED __builtin_amdgcn_sched_barrier(0)
; template <class Epi, class Sched, bool ALIGN_EPI, class Hook = NoHook>
; __device__ __forceinline__ void gemm_phase(LAS unsigned char* lds, const Gemm g, const Sched& S, const Epi& E, const Hook& H = Hook()) {
;     ...
;             PG8_LDB(B0, 1, 0); PG8_LDB(B1, 1, 1); PG8_SCHED; PG8_LDA(At, 1, 0); PG8_STAGE(PG8_SA(0, 1), a2 + hA, voffA);
;             PG8_WAIT_V(8); PG8_WAIT_L(0); PG8_BAR; PG8_MMA(0, 0, At, B0); PG8_MMA(0, 1, At, B1); PG8_BAR; PG8_SCHED;
;             PG8_LDA(At, 1, 1); PG8_STAGE(PG8_SB(1, 0), b3, voffB); PG8_STAGE(PG8_SB(1, 1), b3 + hB, voffB); PG8_STAGE(PG8_SA(1, 0), a3, voffA);
;             PG8_WAIT_V(8); PG8_WAIT_L(0); PG8_BAR; PG8_MMA(1, 0, At, B0); PG8_MMA(1, 1, At, B1); PG8_BAR; PG8_SCHED;
;         }
;         if constexpr (Hook::ON) H.after(te, acc, cur, wr, wc, fr, fq);
;         }
;         if constexpr (ALIGN_EPI) { if (wr == 0) PG8_BAR; }
	s_setprio 0
	ds_read_b128 v[146:149], v143
	ds_read_b128 v[150:153], v143 offset:1024
	s_add_u32 s16, s16, 0x2b0000
	s_addc_u32 s17, s17, 0
	s_mov_b32 m0, s29
	s_nop 0
	global_load_lds_dwordx4 v130, s[16:17]
	ds_read_b128 v[154:157], v143 offset:2048
	ds_read_b128 v[158:161], v143 offset:3072
	ds_read_b128 v[170:173], v144
	ds_read_b128 v[174:177], v144 offset:1024
	ds_read_b128 v[178:181], v144 offset:2048
	ds_read_b128 v[182:185], v144 offset:3072
	ds_read_b128 v[186:189], v142 offset:32768
	s_mov_b32 m0, s39
	s_nop 0
	global_load_lds_dwordx4 v132, s[16:17]
	ds_read_b128 v[190:193], v142 offset:33792
	ds_read_b128 v[194:197], v142 offset:34816
	ds_read_b128 v[198:201], v142 offset:35840
	ds_read_b128 v[202:205], v142 offset:36864
	ds_read_b128 v[206:209], v142 offset:37888
	ds_read_b128 v[210:213], v142 offset:38912
	ds_read_b128 v[214:217], v142 offset:39936
	s_waitcnt vmcnt(8) lgkmcnt(0)
	s_barrier
	s_setprio 1
	v_mfma_f32_16x16x32_bf16 v[82:85], v[146:149], v[186:189], v[82:85]
	v_mfma_f32_16x16x32_bf16 v[54:57], v[154:157], v[186:189], v[54:57]
	v_mfma_f32_16x16x32_bf16 v[58:61], v[146:149], v[194:197], v[58:61]
	v_mfma_f32_16x16x32_bf16 v[42:45], v[154:157], v[194:197], v[42:45]
	v_mfma_f32_16x16x32_bf16 v[70:73], v[146:149], v[202:205], v[70:73]
	v_mfma_f32_16x16x32_bf16 v[50:53], v[154:157], v[202:205], v[50:53]
	v_mfma_f32_16x16x32_bf16 v[86:89], v[146:149], v[210:213], v[86:89]
	v_mfma_f32_16x16x32_bf16 v[74:77], v[154:157], v[210:213], v[74:77]
	v_mfma_f32_16x16x32_bf16 v[82:85], v[150:153], v[190:193], v[82:85]
	v_mfma_f32_16x16x32_bf16 v[54:57], v[158:161], v[190:193], v[54:57]
	v_mfma_f32_16x16x32_bf16 v[58:61], v[150:153], v[198:201], v[58:61]
	v_mfma_f32_16x16x32_bf16 v[42:45], v[158:161], v[198:201], v[42:45]
	v_mfma_f32_16x16x32_bf16 v[70:73], v[150:153], v[206:209], v[70:73]
	v_mfma_f32_16x16x32_bf16 v[50:53], v[158:161], v[206:209], v[50:53]
	v_mfma_f32_16x16x32_bf16 v[86:89], v[150:153], v[214:217], v[86:89]
	v_mfma_f32_16x16x32_bf16 v[74:77], v[158:161], v[214:217], v[74:77]
	v_mfma_f32_16x16x32_bf16 v[14:17], v[170:173], v[186:189], v[14:17]
	v_mfma_f32_16x16x32_bf16 v[2:5], v[178:181], v[186:189], v[2:5]
	v_mfma_f32_16x16x32_bf16 v[18:21], v[170:173], v[194:197], v[18:21]
	v_mfma_f32_16x16x32_bf16 v[6:9], v[178:181], v[194:197], v[6:9]
	v_mfma_f32_16x16x32_bf16 v[22:25], v[170:173], v[202:205], v[22:25]
	v_mfma_f32_16x16x32_bf16 v[10:13], v[178:181], v[202:205], v[10:13]
	v_mfma_f32_16x16x32_bf16 v[30:33], v[170:173], v[210:213], v[30:33]
	v_mfma_f32_16x16x32_bf16 v[26:29], v[178:181], v[210:213], v[26:29]
	v_mfma_f32_16x16x32_bf16 v[14:17], v[174:177], v[190:193], v[14:17]
	v_mfma_f32_16x16x32_bf16 v[2:5], v[182:185], v[190:193], v[2:5]
	v_mfma_f32_16x16x32_bf16 v[18:21], v[174:177], v[198:201], v[18:21]
	v_mfma_f32_16x16x32_bf16 v[6:9], v[182:185], v[198:201], v[6:9]
	v_mfma_f32_16x16x32_bf16 v[22:25], v[174:177], v[206:209], v[22:25]
	v_mfma_f32_16x16x32_bf16 v[10:13], v[182:185], v[206:209], v[10:13]
	v_mfma_f32_16x16x32_bf16 v[30:33], v[174:177], v[214:217], v[30:33]
	v_mfma_f32_16x16x32_bf16 v[26:29], v[182:185], v[214:217], v[26:29]
	s_barrier
	s_setprio 0
	s_mov_b32 m0, s36
	s_add_u32 s52, s10, s2
	s_addc_u32 s53, s11, s3
	s_add_u32 s10, s10, 0x2b0080
	ds_read_b128 v[186:189], v142 offset:49152
	ds_read_b128 v[190:193], v142 offset:50176
	global_load_lds_dwordx4 v162, s[52:53]
	ds_read_b128 v[194:197], v142 offset:51200
	s_mov_b32 m0, s44
	s_addc_u32 s11, s11, 0
	global_load_lds_dwordx4 v134, s[52:53]
	ds_read_b128 v[198:201], v142 offset:52224
	s_mov_b32 m0, s37
	s_nop 0
	global_load_lds_dwordx4 v162, s[10:11]
	ds_read_b128 v[202:205], v142 offset:53248
	s_mov_b32 m0, s45
	s_nop 0
	global_load_lds_dwordx4 v134, s[10:11]
	ds_read_b128 v[206:209], v142 offset:54272
	s_mov_b32 m0, s41
	s_nop 0
	global_load_lds_dwordx4 v130, s[54:55]
	ds_read_b128 v[210:213], v142 offset:55296
	s_mov_b32 m0, s42
	s_nop 0
	global_load_lds_dwordx4 v132, s[54:55]
	s_add_i32 s18, s18, 2
	s_add_u32 s4, s4, 0x100
	s_addc_u32 s5, s5, 0
	s_cmpk_gt_u32 s18, 0xa9
	ds_read_b128 v[214:217], v142 offset:56320
	s_waitcnt vmcnt(8) lgkmcnt(0)
	s_barrier
	s_setprio 1
	v_mfma_f32_16x16x32_bf16 v[94:97], v[146:149], v[186:189], v[94:97]
	v_mfma_f32_16x16x32_bf16 v[90:93], v[154:157], v[186:189], v[90:93]
	v_mfma_f32_16x16x32_bf16 v[118:121], v[146:149], v[194:197], v[118:121]
	v_mfma_f32_16x16x32_bf16 v[98:101], v[154:157], v[194:197], v[98:101]
	v_mfma_f32_16x16x32_bf16 v[126:129], v[146:149], v[202:205], v[126:129]
	v_mfma_f32_16x16x32_bf16 v[110:113], v[154:157], v[202:205], v[110:113]
	v_mfma_f32_16x16x32_bf16 v[122:125], v[146:149], v[210:213], v[122:125]
	v_mfma_f32_16x16x32_bf16 v[114:117], v[154:157], v[210:213], v[114:117]
	v_mfma_f32_16x16x32_bf16 v[94:97], v[150:153], v[190:193], v[94:97]
	v_mfma_f32_16x16x32_bf16 v[90:93], v[158:161], v[190:193], v[90:93]
	v_mfma_f32_16x16x32_bf16 v[118:121], v[150:153], v[198:201], v[118:121]
	v_mfma_f32_16x16x32_bf16 v[98:101], v[158:161], v[198:201], v[98:101]
	v_mfma_f32_16x16x32_bf16 v[126:129], v[150:153], v[206:209], v[126:129]
	v_mfma_f32_16x16x32_bf16 v[110:113], v[158:161], v[206:209], v[110:113]
	v_mfma_f32_16x16x32_bf16 v[122:125], v[150:153], v[214:217], v[122:125]
	v_mfma_f32_16x16x32_bf16 v[114:117], v[158:161], v[214:217], v[114:117]
	v_mfma_f32_16x16x32_bf16 v[38:41], v[170:173], v[186:189], v[38:41]
	v_mfma_f32_16x16x32_bf16 v[34:37], v[178:181], v[186:189], v[34:37]
	v_mfma_f32_16x16x32_bf16 v[66:69], v[170:173], v[194:197], v[66:69]
	v_mfma_f32_16x16x32_bf16 v[46:49], v[178:181], v[194:197], v[46:49]
	v_mfma_f32_16x16x32_bf16 v[78:81], v[170:173], v[202:205], v[78:81]
	v_mfma_f32_16x16x32_bf16 v[62:65], v[178:181], v[202:205], v[62:65]
	v_mfma_f32_16x16x32_bf16 v[106:109], v[170:173], v[210:213], v[106:109]
	v_mfma_f32_16x16x32_bf16 v[102:105], v[178:181], v[210:213], v[102:105]
	v_mfma_f32_16x16x32_bf16 v[38:41], v[174:177], v[190:193], v[38:41]
	v_mfma_f32_16x16x32_bf16 v[34:37], v[182:185], v[190:193], v[34:37]
	v_mfma_f32_16x16x32_bf16 v[66:69], v[174:177], v[198:201], v[66:69]
	v_mfma_f32_16x16x32_bf16 v[46:49], v[182:185], v[198:201], v[46:49]
	v_mfma_f32_16x16x32_bf16 v[78:81], v[174:177], v[206:209], v[78:81]
	v_mfma_f32_16x16x32_bf16 v[62:65], v[182:185], v[206:209], v[62:65]
	v_mfma_f32_16x16x32_bf16 v[106:109], v[174:177], v[214:217], v[106:109]
	v_mfma_f32_16x16x32_bf16 v[102:105], v[182:185], v[214:217], v[102:105]
	s_barrier
	s_setprio 0
	s_cbranch_scc0 .LBB0_1406
	s_cmpk_lt_u32 s22, 0x100
	s_cbranch_scc0 .LBB0_1409
	s_barrier
